# hand-written output-projection tile: GEMM core shared with in-projection, batched gated-residual epilogue, residual tile prefetched into spare registers one piece per K tile
# baseline (speedup 1.0000x reference)
.LBB0_625:
	s_lshr_b32 s0, s41, 6
	s_and_b32 s1, s41, 63
	s_lshr_b32 s82, s1, 3
	s_and_b32 s1, s1, 7
	s_lshl_b32 s0, s0, 3
	s_or_b32 s83, s0, s1
	s_lshl_b32 s0, s83, 18
	s_add_u32 s0, s0, 0x1100000
	s_add_u32 s76, s94, s0
	s_addc_u32 s77, s95, 0
	s_lshl_b32 s0, s82, 18
	s_add_u32 s78, s38, s0
	s_addc_u32 s79, s39, 0
	v_lshrrev_b32_e32 v98, 3, v138
	v_bfe_u32 v99, v138, 4, 3
	v_and_b32_e32 v100, 7, v138
	v_xor_b32_e32 v99, v99, v100
	v_lshlrev_b32_e32 v99, 4, v99
	v_lshl_add_u32 v240, v98, 11, v99
	v_add_u32_e32 v241, 0x10000, v240
	v_add_u32_e32 v242, 0x20000, v240
	v_add_u32_e32 v243, 0x30000, v240
	v_lshrrev_b32_e32 v101, 6, v138
	v_and_b32_e32 v104, 15, v138
	v_readfirstlane_b32 s80, v101
	v_bfe_u32 v105, v138, 4, 2
	v_lshrrev_b32_e32 v106, 1, v104
	v_xor_b32_e32 v106, v106, v105
	v_lshlrev_b32_e32 v106, 4, v106
	s_lshl_b32 s81, s80, 10
	v_lshrrev_b32_e32 v107, 1, v101
	v_and_b32_e32 v101, 1, v101
	v_lshl_add_u32 v98, v107, 6, v104
	v_lshl_add_u32 v244, v98, 7, v106
	v_xor_b32_e32 v245, 64, v244
	v_lshl_add_u32 v98, v101, 6, v104
	v_lshl_add_u32 v246, v98, 7, v106
	v_add_u32_e32 v246, 0x4000, v246
	v_xor_b32_e32 v247, 64, v246
	v_lshlrev_b32_e32 v98, 6, v107
	v_lshl_add_u32 v98, v105, 2, v98
	s_movk_i32 s0, 0x210
	v_mul_lo_u32 v98, v98, s0
	v_lshl_add_u32 v99, v101, 6, v104
	v_lshl_add_u32 v248, v99, 2, v98
	v_lshrrev_b32_e32 v110, 4, v138
	v_and_b32_e32 v111, 15, v138
	v_lshlrev_b32_e32 v114, 5, v111
	v_lshl_add_u32 v102, v110, 12, v114
	v_lshlrev_b32_e32 v108, 4, v111
	v_lshl_add_u32 v108, v110, 11, v108
	v_mul_lo_u32 v124, v110, s0
	v_add_u32_e32 v124, v124, v114
	s_lshl_b32 s0, s83, 7
	s_lshl_b32 s1, s82, 7
	s_lshl_b32 s2, s0, 10
	s_add_u32 s2, s2, s1
	s_cmp_eq_u64 s[52:53], 0
	s_cbranch_scc0 .Lot_l1addr
	v_readlane_b32 s86, v207, 4
	v_readlane_b32 s87, v207, 5
	s_lshl_b32 s3, s2, 2
	s_add_u32 s86, s86, s3
	s_addc_u32 s87, s87, 0
	s_lshl_b32 s3, s2, 1
	s_add_u32 s3, s3, 0xa700000
	s_add_u32 s88, s94, s3
	s_addc_u32 s89, s95, 0
	s_branch .Lot_addr_done
.Lot_l1addr:
	s_lshl_b32 s3, s2, 1
	s_add_u32 s3, s3, 0xa700000
	s_add_u32 s86, s94, s3
	s_addc_u32 s87, s95, 0
	s_lshl_b32 s3, s2, 2
	s_add_u32 s88, s92, s3
	s_addc_u32 s89, s93, 0
.Lot_addr_done:
	s_lshr_b32 s2, s83, 6
	s_mul_i32 s2, s2, 0x3000
	s_lshl_b32 s3, s1, 2
	s_add_u32 s2, s2, s3
	s_add_u32 s2, s2, 0x2000
	s_add_u32 s90, s12, s2
	s_addc_u32 s91, s13, 0
	v_mov_b32_e32 v0, 0
	v_mov_b32_e32 v1, 0
	v_mov_b32_e32 v2, 0
	v_mov_b32_e32 v3, 0
	v_mov_b32_e32 v4, 0
	v_mov_b32_e32 v5, 0
	v_mov_b32_e32 v6, 0
	v_mov_b32_e32 v7, 0
	v_mov_b32_e32 v8, 0
	v_mov_b32_e32 v9, 0
	v_mov_b32_e32 v10, 0
	v_mov_b32_e32 v11, 0
	v_mov_b32_e32 v12, 0
	v_mov_b32_e32 v13, 0
	v_mov_b32_e32 v14, 0
	v_mov_b32_e32 v15, 0
	v_mov_b32_e32 v16, 0
	v_mov_b32_e32 v17, 0
	v_mov_b32_e32 v18, 0
	v_mov_b32_e32 v19, 0
	v_mov_b32_e32 v20, 0
	v_mov_b32_e32 v21, 0
	v_mov_b32_e32 v22, 0
	v_mov_b32_e32 v23, 0
	v_mov_b32_e32 v24, 0
	v_mov_b32_e32 v25, 0
	v_mov_b32_e32 v26, 0
	v_mov_b32_e32 v27, 0
	v_mov_b32_e32 v28, 0
	v_mov_b32_e32 v29, 0
	v_mov_b32_e32 v30, 0
	v_mov_b32_e32 v31, 0
	v_mov_b32_e32 v32, 0
	v_mov_b32_e32 v33, 0
	v_mov_b32_e32 v34, 0
	v_mov_b32_e32 v35, 0
	v_mov_b32_e32 v36, 0
	v_mov_b32_e32 v37, 0
	v_mov_b32_e32 v38, 0
	v_mov_b32_e32 v39, 0
	v_mov_b32_e32 v40, 0
	v_mov_b32_e32 v41, 0
	v_mov_b32_e32 v42, 0
	v_mov_b32_e32 v43, 0
	v_mov_b32_e32 v44, 0
	v_mov_b32_e32 v45, 0
	v_mov_b32_e32 v46, 0
	v_mov_b32_e32 v47, 0
	v_mov_b32_e32 v48, 0
	v_mov_b32_e32 v49, 0
	v_mov_b32_e32 v50, 0
	v_mov_b32_e32 v51, 0
	v_mov_b32_e32 v52, 0
	v_mov_b32_e32 v53, 0
	v_mov_b32_e32 v54, 0
	v_mov_b32_e32 v55, 0
	v_mov_b32_e32 v56, 0
	v_mov_b32_e32 v57, 0
	v_mov_b32_e32 v58, 0
	v_mov_b32_e32 v59, 0
	v_mov_b32_e32 v60, 0
	v_mov_b32_e32 v61, 0
	v_mov_b32_e32 v62, 0
	v_mov_b32_e32 v63, 0
	s_barrier
	s_add_i32 m0, s81, 0
	s_nop 0
	global_load_lds_dwordx4 v240, s[76:77]
	s_add_i32 m0, s81, 4096
	s_nop 0
	global_load_lds_dwordx4 v241, s[76:77]
	s_add_i32 m0, s81, 8192
	s_nop 0
	global_load_lds_dwordx4 v242, s[76:77]
	s_add_i32 m0, s81, 12288
	s_nop 0
	global_load_lds_dwordx4 v243, s[76:77]
	s_add_i32 m0, s81, 16384
	s_nop 0
	global_load_lds_dwordx4 v240, s[78:79]
	s_add_i32 m0, s81, 20480
	s_nop 0
	global_load_lds_dwordx4 v241, s[78:79]
	s_add_i32 m0, s81, 24576
	s_nop 0
	global_load_lds_dwordx4 v242, s[78:79]
	s_add_i32 m0, s81, 28672
	s_nop 0
	global_load_lds_dwordx4 v243, s[78:79]
	s_add_u32 s76, s76, 0x80
	s_addc_u32 s77, s77, 0
	s_add_u32 s78, s78, 0x80
	s_addc_u32 s79, s79, 0
	s_cmp_eq_u64 s[52:53], 0
	s_cbranch_scc0 .Lot_main_l1
	s_waitcnt vmcnt(0)
	s_barrier
	ds_read_b128 v[176:179], v244 offset:0
	ds_read_b128 v[80:83], v246 offset:0
	ds_read_b128 v[84:87], v246 offset:2048
	ds_read_b128 v[88:91], v246 offset:4096
	ds_read_b128 v[92:95], v246 offset:6144
	ds_read_b128 v[180:183], v244 offset:2048
	ds_read_b128 v[184:187], v244 offset:4096
	ds_read_b128 v[188:191], v244 offset:6144
	s_waitcnt lgkmcnt(6)
	v_mfma_f32_16x16x32_bf16 v[0:3], v[176:179], v[80:83], v[0:3]
	ds_read_b128 v[208:211], v245 offset:0
	s_add_i32 m0, s81, 32768
	s_waitcnt lgkmcnt(6)
	v_mfma_f32_16x16x32_bf16 v[4:7], v[176:179], v[84:87], v[4:7]
	ds_read_b128 v[224:227], v247 offset:0
	global_load_lds_dwordx4 v240, s[76:77]
	s_waitcnt lgkmcnt(6)
	v_mfma_f32_16x16x32_bf16 v[8:11], v[176:179], v[88:91], v[8:11]
	ds_read_b128 v[228:231], v247 offset:2048
	s_add_i32 m0, s81, 36864
	s_waitcnt lgkmcnt(6)
	v_mfma_f32_16x16x32_bf16 v[12:15], v[176:179], v[92:95], v[12:15]
	ds_read_b128 v[232:235], v247 offset:4096
	global_load_lds_dwordx4 v241, s[76:77]
	s_waitcnt lgkmcnt(6)
	v_mfma_f32_16x16x32_bf16 v[16:19], v[180:183], v[80:83], v[16:19]
	ds_read_b128 v[236:239], v247 offset:6144
	s_add_i32 m0, s81, 40960
	v_mfma_f32_16x16x32_bf16 v[20:23], v[180:183], v[84:87], v[20:23]
	ds_read_b128 v[212:215], v245 offset:2048
	global_load_lds_dwordx4 v242, s[76:77]
	v_mfma_f32_16x16x32_bf16 v[24:27], v[180:183], v[88:91], v[24:27]
	ds_read_b128 v[216:219], v245 offset:4096
	s_add_i32 m0, s81, 45056
	v_mfma_f32_16x16x32_bf16 v[28:31], v[180:183], v[92:95], v[28:31]
	ds_read_b128 v[220:223], v245 offset:6144
	global_load_lds_dwordx4 v243, s[76:77]
	s_waitcnt lgkmcnt(9)
	v_mfma_f32_16x16x32_bf16 v[32:35], v[184:187], v[80:83], v[32:35]
	s_add_i32 m0, s81, 49152
	v_mfma_f32_16x16x32_bf16 v[36:39], v[184:187], v[84:87], v[36:39]
	global_load_lds_dwordx4 v240, s[78:79]
	v_mfma_f32_16x16x32_bf16 v[40:43], v[184:187], v[88:91], v[40:43]
	s_add_i32 m0, s81, 53248
	v_mfma_f32_16x16x32_bf16 v[44:47], v[184:187], v[92:95], v[44:47]
	global_load_lds_dwordx4 v241, s[78:79]
	s_waitcnt lgkmcnt(8)
	v_mfma_f32_16x16x32_bf16 v[48:51], v[188:191], v[80:83], v[48:51]
	s_add_i32 m0, s81, 57344
	v_mfma_f32_16x16x32_bf16 v[52:55], v[188:191], v[84:87], v[52:55]
	global_load_lds_dwordx4 v242, s[78:79]
	v_mfma_f32_16x16x32_bf16 v[56:59], v[188:191], v[88:91], v[56:59]
	s_add_i32 m0, s81, 61440
	v_mfma_f32_16x16x32_bf16 v[60:63], v[188:191], v[92:95], v[60:63]
	global_load_lds_dwordx4 v243, s[78:79]
	s_waitcnt lgkmcnt(6)
	v_mfma_f32_16x16x32_bf16 v[0:3], v[208:211], v[224:227], v[0:3]
	s_add_u32 s76, s76, 0x80
	s_addc_u32 s77, s77, 0
	s_waitcnt lgkmcnt(5)
	v_mfma_f32_16x16x32_bf16 v[4:7], v[208:211], v[228:231], v[4:7]
	s_waitcnt lgkmcnt(4)
	v_mfma_f32_16x16x32_bf16 v[8:11], v[208:211], v[232:235], v[8:11]
	s_add_u32 s78, s78, 0x80
	s_addc_u32 s79, s79, 0
	s_waitcnt lgkmcnt(3)
	v_mfma_f32_16x16x32_bf16 v[12:15], v[208:211], v[236:239], v[12:15]
	s_waitcnt lgkmcnt(2)
	v_mfma_f32_16x16x32_bf16 v[16:19], v[212:215], v[224:227], v[16:19]
	v_mfma_f32_16x16x32_bf16 v[20:23], v[212:215], v[228:231], v[20:23]
	v_mfma_f32_16x16x32_bf16 v[24:27], v[212:215], v[232:235], v[24:27]
	v_mfma_f32_16x16x32_bf16 v[28:31], v[212:215], v[236:239], v[28:31]
	s_waitcnt lgkmcnt(1)
	v_mfma_f32_16x16x32_bf16 v[32:35], v[216:219], v[224:227], v[32:35]
	v_mfma_f32_16x16x32_bf16 v[36:39], v[216:219], v[228:231], v[36:39]
	v_mfma_f32_16x16x32_bf16 v[40:43], v[216:219], v[232:235], v[40:43]
	v_mfma_f32_16x16x32_bf16 v[44:47], v[216:219], v[236:239], v[44:47]
	s_waitcnt lgkmcnt(0)
	v_mfma_f32_16x16x32_bf16 v[48:51], v[220:223], v[224:227], v[48:51]
	v_mfma_f32_16x16x32_bf16 v[52:55], v[220:223], v[228:231], v[52:55]
	v_mfma_f32_16x16x32_bf16 v[56:59], v[220:223], v[232:235], v[56:59]
	v_mfma_f32_16x16x32_bf16 v[60:63], v[220:223], v[236:239], v[60:63]
	s_waitcnt vmcnt(0)
	s_barrier
	ds_read_b128 v[176:179], v244 offset:32768
	ds_read_b128 v[80:83], v246 offset:32768
	ds_read_b128 v[84:87], v246 offset:34816
	ds_read_b128 v[88:91], v246 offset:36864
	ds_read_b128 v[92:95], v246 offset:38912
	ds_read_b128 v[180:183], v244 offset:34816
	ds_read_b128 v[184:187], v244 offset:36864
	ds_read_b128 v[188:191], v244 offset:38912
	s_waitcnt lgkmcnt(6)
	v_mfma_f32_16x16x32_bf16 v[0:3], v[176:179], v[80:83], v[0:3]
	ds_read_b128 v[208:211], v245 offset:32768
	s_add_i32 m0, s81, 0
	s_waitcnt lgkmcnt(6)
	v_mfma_f32_16x16x32_bf16 v[4:7], v[176:179], v[84:87], v[4:7]
	ds_read_b128 v[224:227], v247 offset:32768
	global_load_lds_dwordx4 v240, s[76:77]
	s_waitcnt lgkmcnt(6)
	v_mfma_f32_16x16x32_bf16 v[8:11], v[176:179], v[88:91], v[8:11]
	ds_read_b128 v[228:231], v247 offset:34816
	s_add_i32 m0, s81, 4096
	s_waitcnt lgkmcnt(6)
	v_mfma_f32_16x16x32_bf16 v[12:15], v[176:179], v[92:95], v[12:15]
	ds_read_b128 v[232:235], v247 offset:36864
	global_load_lds_dwordx4 v241, s[76:77]
	s_waitcnt lgkmcnt(6)
	v_mfma_f32_16x16x32_bf16 v[16:19], v[180:183], v[80:83], v[16:19]
	ds_read_b128 v[236:239], v247 offset:38912
	s_add_i32 m0, s81, 8192
	v_mfma_f32_16x16x32_bf16 v[20:23], v[180:183], v[84:87], v[20:23]
	ds_read_b128 v[212:215], v245 offset:34816
	global_load_lds_dwordx4 v242, s[76:77]
	v_mfma_f32_16x16x32_bf16 v[24:27], v[180:183], v[88:91], v[24:27]
	ds_read_b128 v[216:219], v245 offset:36864
	s_add_i32 m0, s81, 12288
	v_mfma_f32_16x16x32_bf16 v[28:31], v[180:183], v[92:95], v[28:31]
	ds_read_b128 v[220:223], v245 offset:38912
	global_load_lds_dwordx4 v243, s[76:77]
	s_waitcnt lgkmcnt(9)
	v_mfma_f32_16x16x32_bf16 v[32:35], v[184:187], v[80:83], v[32:35]
	s_add_i32 m0, s81, 16384
	v_mfma_f32_16x16x32_bf16 v[36:39], v[184:187], v[84:87], v[36:39]
	global_load_lds_dwordx4 v240, s[78:79]
	v_mfma_f32_16x16x32_bf16 v[40:43], v[184:187], v[88:91], v[40:43]
	s_add_i32 m0, s81, 20480
	v_mfma_f32_16x16x32_bf16 v[44:47], v[184:187], v[92:95], v[44:47]
	global_load_lds_dwordx4 v241, s[78:79]
	s_waitcnt lgkmcnt(8)
	v_mfma_f32_16x16x32_bf16 v[48:51], v[188:191], v[80:83], v[48:51]
	s_add_i32 m0, s81, 24576
	v_mfma_f32_16x16x32_bf16 v[52:55], v[188:191], v[84:87], v[52:55]
	global_load_lds_dwordx4 v242, s[78:79]
	v_mfma_f32_16x16x32_bf16 v[56:59], v[188:191], v[88:91], v[56:59]
	s_add_i32 m0, s81, 28672
	v_mfma_f32_16x16x32_bf16 v[60:63], v[188:191], v[92:95], v[60:63]
	global_load_lds_dwordx4 v243, s[78:79]
	s_waitcnt lgkmcnt(6)
	v_mfma_f32_16x16x32_bf16 v[0:3], v[208:211], v[224:227], v[0:3]
	s_add_u32 s76, s76, 0x80
	s_addc_u32 s77, s77, 0
	s_waitcnt lgkmcnt(5)
	v_mfma_f32_16x16x32_bf16 v[4:7], v[208:211], v[228:231], v[4:7]
	s_waitcnt lgkmcnt(4)
	v_mfma_f32_16x16x32_bf16 v[8:11], v[208:211], v[232:235], v[8:11]
	s_add_u32 s78, s78, 0x80
	s_addc_u32 s79, s79, 0
	s_waitcnt lgkmcnt(3)
	v_mfma_f32_16x16x32_bf16 v[12:15], v[208:211], v[236:239], v[12:15]
	s_waitcnt lgkmcnt(2)
	v_mfma_f32_16x16x32_bf16 v[16:19], v[212:215], v[224:227], v[16:19]
	v_add_u32_e32 v96, 0x0, v102
	v_mfma_f32_16x16x32_bf16 v[20:23], v[212:215], v[228:231], v[20:23]
	global_load_dwordx4 v[64:67], v96, s[86:87] nt
	v_mfma_f32_16x16x32_bf16 v[24:27], v[212:215], v[232:235], v[24:27]
	v_mfma_f32_16x16x32_bf16 v[28:31], v[212:215], v[236:239], v[28:31]
	s_waitcnt lgkmcnt(1)
	v_mfma_f32_16x16x32_bf16 v[32:35], v[216:219], v[224:227], v[32:35]
	v_mfma_f32_16x16x32_bf16 v[36:39], v[216:219], v[228:231], v[36:39]
	v_mfma_f32_16x16x32_bf16 v[40:43], v[216:219], v[232:235], v[40:43]
	v_mfma_f32_16x16x32_bf16 v[44:47], v[216:219], v[236:239], v[44:47]
	s_waitcnt lgkmcnt(0)
	v_mfma_f32_16x16x32_bf16 v[48:51], v[220:223], v[224:227], v[48:51]
	v_mfma_f32_16x16x32_bf16 v[52:55], v[220:223], v[228:231], v[52:55]
	v_mfma_f32_16x16x32_bf16 v[56:59], v[220:223], v[232:235], v[56:59]
	v_mfma_f32_16x16x32_bf16 v[60:63], v[220:223], v[236:239], v[60:63]
	s_waitcnt vmcnt(1)
	s_barrier
	ds_read_b128 v[176:179], v244 offset:0
	ds_read_b128 v[80:83], v246 offset:0
	ds_read_b128 v[84:87], v246 offset:2048
	ds_read_b128 v[88:91], v246 offset:4096
	ds_read_b128 v[92:95], v246 offset:6144
	ds_read_b128 v[180:183], v244 offset:2048
	ds_read_b128 v[184:187], v244 offset:4096
	ds_read_b128 v[188:191], v244 offset:6144
	s_waitcnt lgkmcnt(6)
	v_mfma_f32_16x16x32_bf16 v[0:3], v[176:179], v[80:83], v[0:3]
	ds_read_b128 v[208:211], v245 offset:0
	s_add_i32 m0, s81, 32768
	s_waitcnt lgkmcnt(6)
	v_mfma_f32_16x16x32_bf16 v[4:7], v[176:179], v[84:87], v[4:7]
	ds_read_b128 v[224:227], v247 offset:0
	global_load_lds_dwordx4 v240, s[76:77]
	s_waitcnt lgkmcnt(6)
	v_mfma_f32_16x16x32_bf16 v[8:11], v[176:179], v[88:91], v[8:11]
	ds_read_b128 v[228:231], v247 offset:2048
	s_add_i32 m0, s81, 36864
	s_waitcnt lgkmcnt(6)
	v_mfma_f32_16x16x32_bf16 v[12:15], v[176:179], v[92:95], v[12:15]
	ds_read_b128 v[232:235], v247 offset:4096
	global_load_lds_dwordx4 v241, s[76:77]
	s_waitcnt lgkmcnt(6)
	v_mfma_f32_16x16x32_bf16 v[16:19], v[180:183], v[80:83], v[16:19]
	ds_read_b128 v[236:239], v247 offset:6144
	s_add_i32 m0, s81, 40960
	v_mfma_f32_16x16x32_bf16 v[20:23], v[180:183], v[84:87], v[20:23]
	ds_read_b128 v[212:215], v245 offset:2048
	global_load_lds_dwordx4 v242, s[76:77]
	v_mfma_f32_16x16x32_bf16 v[24:27], v[180:183], v[88:91], v[24:27]
	ds_read_b128 v[216:219], v245 offset:4096
	s_add_i32 m0, s81, 45056
	v_mfma_f32_16x16x32_bf16 v[28:31], v[180:183], v[92:95], v[28:31]
	ds_read_b128 v[220:223], v245 offset:6144
	global_load_lds_dwordx4 v243, s[76:77]
	s_waitcnt lgkmcnt(9)
	v_mfma_f32_16x16x32_bf16 v[32:35], v[184:187], v[80:83], v[32:35]
	s_add_i32 m0, s81, 49152
	v_mfma_f32_16x16x32_bf16 v[36:39], v[184:187], v[84:87], v[36:39]
	global_load_lds_dwordx4 v240, s[78:79]
	v_mfma_f32_16x16x32_bf16 v[40:43], v[184:187], v[88:91], v[40:43]
	s_add_i32 m0, s81, 53248
	v_mfma_f32_16x16x32_bf16 v[44:47], v[184:187], v[92:95], v[44:47]
	global_load_lds_dwordx4 v241, s[78:79]
	s_waitcnt lgkmcnt(8)
	v_mfma_f32_16x16x32_bf16 v[48:51], v[188:191], v[80:83], v[48:51]
	s_add_i32 m0, s81, 57344
	v_mfma_f32_16x16x32_bf16 v[52:55], v[188:191], v[84:87], v[52:55]
	global_load_lds_dwordx4 v242, s[78:79]
	v_mfma_f32_16x16x32_bf16 v[56:59], v[188:191], v[88:91], v[56:59]
	s_add_i32 m0, s81, 61440
	v_mfma_f32_16x16x32_bf16 v[60:63], v[188:191], v[92:95], v[60:63]
	global_load_lds_dwordx4 v243, s[78:79]
	s_waitcnt lgkmcnt(6)
	v_mfma_f32_16x16x32_bf16 v[0:3], v[208:211], v[224:227], v[0:3]
	s_add_u32 s76, s76, 0x80
	s_addc_u32 s77, s77, 0
	s_waitcnt lgkmcnt(5)
	v_mfma_f32_16x16x32_bf16 v[4:7], v[208:211], v[228:231], v[4:7]
	s_waitcnt lgkmcnt(4)
	v_mfma_f32_16x16x32_bf16 v[8:11], v[208:211], v[232:235], v[8:11]
	s_add_u32 s78, s78, 0x80
	s_addc_u32 s79, s79, 0
	s_waitcnt lgkmcnt(3)
	v_mfma_f32_16x16x32_bf16 v[12:15], v[208:211], v[236:239], v[12:15]
	s_waitcnt lgkmcnt(2)
	v_mfma_f32_16x16x32_bf16 v[16:19], v[212:215], v[224:227], v[16:19]
	v_add_u32_e32 v96, 0x0, v102
	v_mfma_f32_16x16x32_bf16 v[20:23], v[212:215], v[228:231], v[20:23]
	global_load_dwordx4 v[68:71], v96, s[86:87] offset:16 nt
	v_mfma_f32_16x16x32_bf16 v[24:27], v[212:215], v[232:235], v[24:27]
	v_mfma_f32_16x16x32_bf16 v[28:31], v[212:215], v[236:239], v[28:31]
	s_waitcnt lgkmcnt(1)
	v_mfma_f32_16x16x32_bf16 v[32:35], v[216:219], v[224:227], v[32:35]
	v_mfma_f32_16x16x32_bf16 v[36:39], v[216:219], v[228:231], v[36:39]
	v_mfma_f32_16x16x32_bf16 v[40:43], v[216:219], v[232:235], v[40:43]
	v_mfma_f32_16x16x32_bf16 v[44:47], v[216:219], v[236:239], v[44:47]
	s_waitcnt lgkmcnt(0)
	v_mfma_f32_16x16x32_bf16 v[48:51], v[220:223], v[224:227], v[48:51]
	v_mfma_f32_16x16x32_bf16 v[52:55], v[220:223], v[228:231], v[52:55]
	v_mfma_f32_16x16x32_bf16 v[56:59], v[220:223], v[232:235], v[56:59]
	v_mfma_f32_16x16x32_bf16 v[60:63], v[220:223], v[236:239], v[60:63]
	s_waitcnt vmcnt(1)
	s_barrier
	ds_read_b128 v[176:179], v244 offset:32768
	ds_read_b128 v[80:83], v246 offset:32768
	ds_read_b128 v[84:87], v246 offset:34816
	ds_read_b128 v[88:91], v246 offset:36864
	ds_read_b128 v[92:95], v246 offset:38912
	ds_read_b128 v[180:183], v244 offset:34816
	ds_read_b128 v[184:187], v244 offset:36864
	ds_read_b128 v[188:191], v244 offset:38912
	s_waitcnt lgkmcnt(6)
	v_mfma_f32_16x16x32_bf16 v[0:3], v[176:179], v[80:83], v[0:3]
	ds_read_b128 v[208:211], v245 offset:32768
	s_add_i32 m0, s81, 0
	s_waitcnt lgkmcnt(6)
	v_mfma_f32_16x16x32_bf16 v[4:7], v[176:179], v[84:87], v[4:7]
	ds_read_b128 v[224:227], v247 offset:32768
	global_load_lds_dwordx4 v240, s[76:77]
	s_waitcnt lgkmcnt(6)
	v_mfma_f32_16x16x32_bf16 v[8:11], v[176:179], v[88:91], v[8:11]
	ds_read_b128 v[228:231], v247 offset:34816
	s_add_i32 m0, s81, 4096
	s_waitcnt lgkmcnt(6)
	v_mfma_f32_16x16x32_bf16 v[12:15], v[176:179], v[92:95], v[12:15]
	ds_read_b128 v[232:235], v247 offset:36864
	global_load_lds_dwordx4 v241, s[76:77]
	s_waitcnt lgkmcnt(6)
	v_mfma_f32_16x16x32_bf16 v[16:19], v[180:183], v[80:83], v[16:19]
	ds_read_b128 v[236:239], v247 offset:38912
	s_add_i32 m0, s81, 8192
	v_mfma_f32_16x16x32_bf16 v[20:23], v[180:183], v[84:87], v[20:23]
	ds_read_b128 v[212:215], v245 offset:34816
	global_load_lds_dwordx4 v242, s[76:77]
	v_mfma_f32_16x16x32_bf16 v[24:27], v[180:183], v[88:91], v[24:27]
	ds_read_b128 v[216:219], v245 offset:36864
	s_add_i32 m0, s81, 12288
	v_mfma_f32_16x16x32_bf16 v[28:31], v[180:183], v[92:95], v[28:31]
	ds_read_b128 v[220:223], v245 offset:38912
	global_load_lds_dwordx4 v243, s[76:77]
	s_waitcnt lgkmcnt(9)
	v_mfma_f32_16x16x32_bf16 v[32:35], v[184:187], v[80:83], v[32:35]
	s_add_i32 m0, s81, 16384
	v_mfma_f32_16x16x32_bf16 v[36:39], v[184:187], v[84:87], v[36:39]
	global_load_lds_dwordx4 v240, s[78:79]
	v_mfma_f32_16x16x32_bf16 v[40:43], v[184:187], v[88:91], v[40:43]
	s_add_i32 m0, s81, 20480
	v_mfma_f32_16x16x32_bf16 v[44:47], v[184:187], v[92:95], v[44:47]
	global_load_lds_dwordx4 v241, s[78:79]
	s_waitcnt lgkmcnt(8)
	v_mfma_f32_16x16x32_bf16 v[48:51], v[188:191], v[80:83], v[48:51]
	s_add_i32 m0, s81, 24576
	v_mfma_f32_16x16x32_bf16 v[52:55], v[188:191], v[84:87], v[52:55]
	global_load_lds_dwordx4 v242, s[78:79]
	v_mfma_f32_16x16x32_bf16 v[56:59], v[188:191], v[88:91], v[56:59]
	s_add_i32 m0, s81, 28672
	v_mfma_f32_16x16x32_bf16 v[60:63], v[188:191], v[92:95], v[60:63]
	global_load_lds_dwordx4 v243, s[78:79]
	s_waitcnt lgkmcnt(6)
	v_mfma_f32_16x16x32_bf16 v[0:3], v[208:211], v[224:227], v[0:3]
	s_add_u32 s76, s76, 0x80
	s_addc_u32 s77, s77, 0
	s_waitcnt lgkmcnt(5)
	v_mfma_f32_16x16x32_bf16 v[4:7], v[208:211], v[228:231], v[4:7]
	s_waitcnt lgkmcnt(4)
	v_mfma_f32_16x16x32_bf16 v[8:11], v[208:211], v[232:235], v[8:11]
	s_add_u32 s78, s78, 0x80
	s_addc_u32 s79, s79, 0
	s_waitcnt lgkmcnt(3)
	v_mfma_f32_16x16x32_bf16 v[12:15], v[208:211], v[236:239], v[12:15]
	s_waitcnt lgkmcnt(2)
	v_mfma_f32_16x16x32_bf16 v[16:19], v[212:215], v[224:227], v[16:19]
	v_add_u32_e32 v96, 0x10000, v102
	v_mfma_f32_16x16x32_bf16 v[20:23], v[212:215], v[228:231], v[20:23]
	global_load_dwordx4 v[74:77], v96, s[86:87] nt
	v_mfma_f32_16x16x32_bf16 v[24:27], v[212:215], v[232:235], v[24:27]
	v_mfma_f32_16x16x32_bf16 v[28:31], v[212:215], v[236:239], v[28:31]
	s_waitcnt lgkmcnt(1)
	v_mfma_f32_16x16x32_bf16 v[32:35], v[216:219], v[224:227], v[32:35]
	v_mfma_f32_16x16x32_bf16 v[36:39], v[216:219], v[228:231], v[36:39]
	v_mfma_f32_16x16x32_bf16 v[40:43], v[216:219], v[232:235], v[40:43]
	v_mfma_f32_16x16x32_bf16 v[44:47], v[216:219], v[236:239], v[44:47]
	s_waitcnt lgkmcnt(0)
	v_mfma_f32_16x16x32_bf16 v[48:51], v[220:223], v[224:227], v[48:51]
	v_mfma_f32_16x16x32_bf16 v[52:55], v[220:223], v[228:231], v[52:55]
	v_mfma_f32_16x16x32_bf16 v[56:59], v[220:223], v[232:235], v[56:59]
	v_mfma_f32_16x16x32_bf16 v[60:63], v[220:223], v[236:239], v[60:63]
	s_waitcnt vmcnt(1)
	s_barrier
	ds_read_b128 v[176:179], v244 offset:0
	ds_read_b128 v[80:83], v246 offset:0
	ds_read_b128 v[84:87], v246 offset:2048
	ds_read_b128 v[88:91], v246 offset:4096
	ds_read_b128 v[92:95], v246 offset:6144
	ds_read_b128 v[180:183], v244 offset:2048
	ds_read_b128 v[184:187], v244 offset:4096
	ds_read_b128 v[188:191], v244 offset:6144
	s_waitcnt lgkmcnt(6)
	v_mfma_f32_16x16x32_bf16 v[0:3], v[176:179], v[80:83], v[0:3]
	ds_read_b128 v[208:211], v245 offset:0
	s_add_i32 m0, s81, 32768
	s_waitcnt lgkmcnt(6)
	v_mfma_f32_16x16x32_bf16 v[4:7], v[176:179], v[84:87], v[4:7]
	ds_read_b128 v[224:227], v247 offset:0
	global_load_lds_dwordx4 v240, s[76:77]
	s_waitcnt lgkmcnt(6)
	v_mfma_f32_16x16x32_bf16 v[8:11], v[176:179], v[88:91], v[8:11]
	ds_read_b128 v[228:231], v247 offset:2048
	s_add_i32 m0, s81, 36864
	s_waitcnt lgkmcnt(6)
	v_mfma_f32_16x16x32_bf16 v[12:15], v[176:179], v[92:95], v[12:15]
	ds_read_b128 v[232:235], v247 offset:4096
	global_load_lds_dwordx4 v241, s[76:77]
	s_waitcnt lgkmcnt(6)
	v_mfma_f32_16x16x32_bf16 v[16:19], v[180:183], v[80:83], v[16:19]
	ds_read_b128 v[236:239], v247 offset:6144
	s_add_i32 m0, s81, 40960
	v_mfma_f32_16x16x32_bf16 v[20:23], v[180:183], v[84:87], v[20:23]
	ds_read_b128 v[212:215], v245 offset:2048
	global_load_lds_dwordx4 v242, s[76:77]
	v_mfma_f32_16x16x32_bf16 v[24:27], v[180:183], v[88:91], v[24:27]
	ds_read_b128 v[216:219], v245 offset:4096
	s_add_i32 m0, s81, 45056
	v_mfma_f32_16x16x32_bf16 v[28:31], v[180:183], v[92:95], v[28:31]
	ds_read_b128 v[220:223], v245 offset:6144
	global_load_lds_dwordx4 v243, s[76:77]
	s_waitcnt lgkmcnt(9)
	v_mfma_f32_16x16x32_bf16 v[32:35], v[184:187], v[80:83], v[32:35]
	s_add_i32 m0, s81, 49152
	v_mfma_f32_16x16x32_bf16 v[36:39], v[184:187], v[84:87], v[36:39]
	global_load_lds_dwordx4 v240, s[78:79]
	v_mfma_f32_16x16x32_bf16 v[40:43], v[184:187], v[88:91], v[40:43]
	s_add_i32 m0, s81, 53248
	v_mfma_f32_16x16x32_bf16 v[44:47], v[184:187], v[92:95], v[44:47]
	global_load_lds_dwordx4 v241, s[78:79]
	s_waitcnt lgkmcnt(8)
	v_mfma_f32_16x16x32_bf16 v[48:51], v[188:191], v[80:83], v[48:51]
	s_add_i32 m0, s81, 57344
	v_mfma_f32_16x16x32_bf16 v[52:55], v[188:191], v[84:87], v[52:55]
	global_load_lds_dwordx4 v242, s[78:79]
	v_mfma_f32_16x16x32_bf16 v[56:59], v[188:191], v[88:91], v[56:59]
	s_add_i32 m0, s81, 61440
	v_mfma_f32_16x16x32_bf16 v[60:63], v[188:191], v[92:95], v[60:63]
	global_load_lds_dwordx4 v243, s[78:79]
	s_waitcnt lgkmcnt(6)
	v_mfma_f32_16x16x32_bf16 v[0:3], v[208:211], v[224:227], v[0:3]
	s_add_u32 s76, s76, 0x80
	s_addc_u32 s77, s77, 0
	s_waitcnt lgkmcnt(5)
	v_mfma_f32_16x16x32_bf16 v[4:7], v[208:211], v[228:231], v[4:7]
	s_waitcnt lgkmcnt(4)
	v_mfma_f32_16x16x32_bf16 v[8:11], v[208:211], v[232:235], v[8:11]
	s_add_u32 s78, s78, 0x80
	s_addc_u32 s79, s79, 0
	s_waitcnt lgkmcnt(3)
	v_mfma_f32_16x16x32_bf16 v[12:15], v[208:211], v[236:239], v[12:15]
	s_waitcnt lgkmcnt(2)
	v_mfma_f32_16x16x32_bf16 v[16:19], v[212:215], v[224:227], v[16:19]
	v_add_u32_e32 v96, 0x10000, v102
	v_mfma_f32_16x16x32_bf16 v[20:23], v[212:215], v[228:231], v[20:23]
	global_load_dwordx4 v[98:101], v96, s[86:87] offset:16 nt
	v_mfma_f32_16x16x32_bf16 v[24:27], v[212:215], v[232:235], v[24:27]
	v_mfma_f32_16x16x32_bf16 v[28:31], v[212:215], v[236:239], v[28:31]
	s_waitcnt lgkmcnt(1)
	v_mfma_f32_16x16x32_bf16 v[32:35], v[216:219], v[224:227], v[32:35]
	v_mfma_f32_16x16x32_bf16 v[36:39], v[216:219], v[228:231], v[36:39]
	v_mfma_f32_16x16x32_bf16 v[40:43], v[216:219], v[232:235], v[40:43]
	v_mfma_f32_16x16x32_bf16 v[44:47], v[216:219], v[236:239], v[44:47]
	s_waitcnt lgkmcnt(0)
	v_mfma_f32_16x16x32_bf16 v[48:51], v[220:223], v[224:227], v[48:51]
	v_mfma_f32_16x16x32_bf16 v[52:55], v[220:223], v[228:231], v[52:55]
	v_mfma_f32_16x16x32_bf16 v[56:59], v[220:223], v[232:235], v[56:59]
	v_mfma_f32_16x16x32_bf16 v[60:63], v[220:223], v[236:239], v[60:63]
	s_waitcnt vmcnt(1)
	s_barrier
	ds_read_b128 v[176:179], v244 offset:32768
	ds_read_b128 v[80:83], v246 offset:32768
	ds_read_b128 v[84:87], v246 offset:34816
	ds_read_b128 v[88:91], v246 offset:36864
	ds_read_b128 v[92:95], v246 offset:38912
	ds_read_b128 v[180:183], v244 offset:34816
	ds_read_b128 v[184:187], v244 offset:36864
	ds_read_b128 v[188:191], v244 offset:38912
	s_waitcnt lgkmcnt(6)
	v_mfma_f32_16x16x32_bf16 v[0:3], v[176:179], v[80:83], v[0:3]
	ds_read_b128 v[208:211], v245 offset:32768
	s_add_i32 m0, s81, 0
	s_waitcnt lgkmcnt(6)
	v_mfma_f32_16x16x32_bf16 v[4:7], v[176:179], v[84:87], v[4:7]
	ds_read_b128 v[224:227], v247 offset:32768
	global_load_lds_dwordx4 v240, s[76:77]
	s_waitcnt lgkmcnt(6)
	v_mfma_f32_16x16x32_bf16 v[8:11], v[176:179], v[88:91], v[8:11]
	ds_read_b128 v[228:231], v247 offset:34816
	s_add_i32 m0, s81, 4096
	s_waitcnt lgkmcnt(6)
	v_mfma_f32_16x16x32_bf16 v[12:15], v[176:179], v[92:95], v[12:15]
	ds_read_b128 v[232:235], v247 offset:36864
	global_load_lds_dwordx4 v241, s[76:77]
	s_waitcnt lgkmcnt(6)
	v_mfma_f32_16x16x32_bf16 v[16:19], v[180:183], v[80:83], v[16:19]
	ds_read_b128 v[236:239], v247 offset:38912
	s_add_i32 m0, s81, 8192
	v_mfma_f32_16x16x32_bf16 v[20:23], v[180:183], v[84:87], v[20:23]
	ds_read_b128 v[212:215], v245 offset:34816
	global_load_lds_dwordx4 v242, s[76:77]
	v_mfma_f32_16x16x32_bf16 v[24:27], v[180:183], v[88:91], v[24:27]
	ds_read_b128 v[216:219], v245 offset:36864
	s_add_i32 m0, s81, 12288
	v_mfma_f32_16x16x32_bf16 v[28:31], v[180:183], v[92:95], v[28:31]
	ds_read_b128 v[220:223], v245 offset:38912
	global_load_lds_dwordx4 v243, s[76:77]
	s_waitcnt lgkmcnt(9)
	v_mfma_f32_16x16x32_bf16 v[32:35], v[184:187], v[80:83], v[32:35]
	s_add_i32 m0, s81, 16384
	v_mfma_f32_16x16x32_bf16 v[36:39], v[184:187], v[84:87], v[36:39]
	global_load_lds_dwordx4 v240, s[78:79]
	v_mfma_f32_16x16x32_bf16 v[40:43], v[184:187], v[88:91], v[40:43]
	s_add_i32 m0, s81, 20480
	v_mfma_f32_16x16x32_bf16 v[44:47], v[184:187], v[92:95], v[44:47]
	global_load_lds_dwordx4 v241, s[78:79]
	s_waitcnt lgkmcnt(8)
	v_mfma_f32_16x16x32_bf16 v[48:51], v[188:191], v[80:83], v[48:51]
	s_add_i32 m0, s81, 24576
	v_mfma_f32_16x16x32_bf16 v[52:55], v[188:191], v[84:87], v[52:55]
	global_load_lds_dwordx4 v242, s[78:79]
	v_mfma_f32_16x16x32_bf16 v[56:59], v[188:191], v[88:91], v[56:59]
	s_add_i32 m0, s81, 28672
	v_mfma_f32_16x16x32_bf16 v[60:63], v[188:191], v[92:95], v[60:63]
	global_load_lds_dwordx4 v243, s[78:79]
	s_waitcnt lgkmcnt(6)
	v_mfma_f32_16x16x32_bf16 v[0:3], v[208:211], v[224:227], v[0:3]
	s_add_u32 s76, s76, 0x80
	s_addc_u32 s77, s77, 0
	s_waitcnt lgkmcnt(5)
	v_mfma_f32_16x16x32_bf16 v[4:7], v[208:211], v[228:231], v[4:7]
	s_waitcnt lgkmcnt(4)
	v_mfma_f32_16x16x32_bf16 v[8:11], v[208:211], v[232:235], v[8:11]
	s_add_u32 s78, s78, 0x80
	s_addc_u32 s79, s79, 0
	s_waitcnt lgkmcnt(3)
	v_mfma_f32_16x16x32_bf16 v[12:15], v[208:211], v[236:239], v[12:15]
	s_waitcnt lgkmcnt(2)
	v_mfma_f32_16x16x32_bf16 v[16:19], v[212:215], v[224:227], v[16:19]
	v_add_u32_e32 v96, 0x20000, v102
	v_mfma_f32_16x16x32_bf16 v[20:23], v[212:215], v[228:231], v[20:23]
	global_load_dwordx4 v[104:107], v96, s[86:87] nt
	v_mfma_f32_16x16x32_bf16 v[24:27], v[212:215], v[232:235], v[24:27]
	v_mfma_f32_16x16x32_bf16 v[28:31], v[212:215], v[236:239], v[28:31]
	s_waitcnt lgkmcnt(1)
	v_mfma_f32_16x16x32_bf16 v[32:35], v[216:219], v[224:227], v[32:35]
	v_mfma_f32_16x16x32_bf16 v[36:39], v[216:219], v[228:231], v[36:39]
	v_mfma_f32_16x16x32_bf16 v[40:43], v[216:219], v[232:235], v[40:43]
	v_mfma_f32_16x16x32_bf16 v[44:47], v[216:219], v[236:239], v[44:47]
	s_waitcnt lgkmcnt(0)
	v_mfma_f32_16x16x32_bf16 v[48:51], v[220:223], v[224:227], v[48:51]
	v_mfma_f32_16x16x32_bf16 v[52:55], v[220:223], v[228:231], v[52:55]
	v_mfma_f32_16x16x32_bf16 v[56:59], v[220:223], v[232:235], v[56:59]
	v_mfma_f32_16x16x32_bf16 v[60:63], v[220:223], v[236:239], v[60:63]
	s_waitcnt vmcnt(1)
	s_barrier
	ds_read_b128 v[176:179], v244 offset:0
	ds_read_b128 v[80:83], v246 offset:0
	ds_read_b128 v[84:87], v246 offset:2048
	ds_read_b128 v[88:91], v246 offset:4096
	ds_read_b128 v[92:95], v246 offset:6144
	ds_read_b128 v[180:183], v244 offset:2048
	ds_read_b128 v[184:187], v244 offset:4096
	ds_read_b128 v[188:191], v244 offset:6144
	s_waitcnt lgkmcnt(6)
	v_mfma_f32_16x16x32_bf16 v[0:3], v[176:179], v[80:83], v[0:3]
	ds_read_b128 v[208:211], v245 offset:0
	s_add_i32 m0, s81, 32768
	s_waitcnt lgkmcnt(6)
	v_mfma_f32_16x16x32_bf16 v[4:7], v[176:179], v[84:87], v[4:7]
	ds_read_b128 v[224:227], v247 offset:0
	global_load_lds_dwordx4 v240, s[76:77]
	s_waitcnt lgkmcnt(6)
	v_mfma_f32_16x16x32_bf16 v[8:11], v[176:179], v[88:91], v[8:11]
	ds_read_b128 v[228:231], v247 offset:2048
	s_add_i32 m0, s81, 36864
	s_waitcnt lgkmcnt(6)
	v_mfma_f32_16x16x32_bf16 v[12:15], v[176:179], v[92:95], v[12:15]
	ds_read_b128 v[232:235], v247 offset:4096
	global_load_lds_dwordx4 v241, s[76:77]
	s_waitcnt lgkmcnt(6)
	v_mfma_f32_16x16x32_bf16 v[16:19], v[180:183], v[80:83], v[16:19]
	ds_read_b128 v[236:239], v247 offset:6144
	s_add_i32 m0, s81, 40960
	v_mfma_f32_16x16x32_bf16 v[20:23], v[180:183], v[84:87], v[20:23]
	ds_read_b128 v[212:215], v245 offset:2048
	global_load_lds_dwordx4 v242, s[76:77]
	v_mfma_f32_16x16x32_bf16 v[24:27], v[180:183], v[88:91], v[24:27]
	ds_read_b128 v[216:219], v245 offset:4096
	s_add_i32 m0, s81, 45056
	v_mfma_f32_16x16x32_bf16 v[28:31], v[180:183], v[92:95], v[28:31]
	ds_read_b128 v[220:223], v245 offset:6144
	global_load_lds_dwordx4 v243, s[76:77]
	s_waitcnt lgkmcnt(9)
	v_mfma_f32_16x16x32_bf16 v[32:35], v[184:187], v[80:83], v[32:35]
	s_add_i32 m0, s81, 49152
	v_mfma_f32_16x16x32_bf16 v[36:39], v[184:187], v[84:87], v[36:39]
	global_load_lds_dwordx4 v240, s[78:79]
	v_mfma_f32_16x16x32_bf16 v[40:43], v[184:187], v[88:91], v[40:43]
	s_add_i32 m0, s81, 53248
	v_mfma_f32_16x16x32_bf16 v[44:47], v[184:187], v[92:95], v[44:47]
	global_load_lds_dwordx4 v241, s[78:79]
	s_waitcnt lgkmcnt(8)
	v_mfma_f32_16x16x32_bf16 v[48:51], v[188:191], v[80:83], v[48:51]
	s_add_i32 m0, s81, 57344
	v_mfma_f32_16x16x32_bf16 v[52:55], v[188:191], v[84:87], v[52:55]
	global_load_lds_dwordx4 v242, s[78:79]
	v_mfma_f32_16x16x32_bf16 v[56:59], v[188:191], v[88:91], v[56:59]
	s_add_i32 m0, s81, 61440
	v_mfma_f32_16x16x32_bf16 v[60:63], v[188:191], v[92:95], v[60:63]
	global_load_lds_dwordx4 v243, s[78:79]
	s_waitcnt lgkmcnt(6)
	v_mfma_f32_16x16x32_bf16 v[0:3], v[208:211], v[224:227], v[0:3]
	s_add_u32 s76, s76, 0x80
	s_addc_u32 s77, s77, 0
	s_waitcnt lgkmcnt(5)
	v_mfma_f32_16x16x32_bf16 v[4:7], v[208:211], v[228:231], v[4:7]
	s_waitcnt lgkmcnt(4)
	v_mfma_f32_16x16x32_bf16 v[8:11], v[208:211], v[232:235], v[8:11]
	s_add_u32 s78, s78, 0x80
	s_addc_u32 s79, s79, 0
	s_waitcnt lgkmcnt(3)
	v_mfma_f32_16x16x32_bf16 v[12:15], v[208:211], v[236:239], v[12:15]
	s_waitcnt lgkmcnt(2)
	v_mfma_f32_16x16x32_bf16 v[16:19], v[212:215], v[224:227], v[16:19]
	v_add_u32_e32 v96, 0x20000, v102
	v_mfma_f32_16x16x32_bf16 v[20:23], v[212:215], v[228:231], v[20:23]
	global_load_dwordx4 v[110:113], v96, s[86:87] offset:16 nt
	v_mfma_f32_16x16x32_bf16 v[24:27], v[212:215], v[232:235], v[24:27]
	v_mfma_f32_16x16x32_bf16 v[28:31], v[212:215], v[236:239], v[28:31]
	s_waitcnt lgkmcnt(1)
	v_mfma_f32_16x16x32_bf16 v[32:35], v[216:219], v[224:227], v[32:35]
	v_mfma_f32_16x16x32_bf16 v[36:39], v[216:219], v[228:231], v[36:39]
	v_mfma_f32_16x16x32_bf16 v[40:43], v[216:219], v[232:235], v[40:43]
	v_mfma_f32_16x16x32_bf16 v[44:47], v[216:219], v[236:239], v[44:47]
	s_waitcnt lgkmcnt(0)
	v_mfma_f32_16x16x32_bf16 v[48:51], v[220:223], v[224:227], v[48:51]
	v_mfma_f32_16x16x32_bf16 v[52:55], v[220:223], v[228:231], v[52:55]
	v_mfma_f32_16x16x32_bf16 v[56:59], v[220:223], v[232:235], v[56:59]
	v_mfma_f32_16x16x32_bf16 v[60:63], v[220:223], v[236:239], v[60:63]
	s_waitcnt vmcnt(1)
	s_barrier
	ds_read_b128 v[176:179], v244 offset:32768
	ds_read_b128 v[80:83], v246 offset:32768
	ds_read_b128 v[84:87], v246 offset:34816
	ds_read_b128 v[88:91], v246 offset:36864
	ds_read_b128 v[92:95], v246 offset:38912
	ds_read_b128 v[180:183], v244 offset:34816
	ds_read_b128 v[184:187], v244 offset:36864
	ds_read_b128 v[188:191], v244 offset:38912
	s_waitcnt lgkmcnt(6)
	v_mfma_f32_16x16x32_bf16 v[0:3], v[176:179], v[80:83], v[0:3]
	ds_read_b128 v[208:211], v245 offset:32768
	s_add_i32 m0, s81, 0
	s_waitcnt lgkmcnt(6)
	v_mfma_f32_16x16x32_bf16 v[4:7], v[176:179], v[84:87], v[4:7]
	ds_read_b128 v[224:227], v247 offset:32768
	global_load_lds_dwordx4 v240, s[76:77]
	s_waitcnt lgkmcnt(6)
	v_mfma_f32_16x16x32_bf16 v[8:11], v[176:179], v[88:91], v[8:11]
	ds_read_b128 v[228:231], v247 offset:34816
	s_add_i32 m0, s81, 4096
	s_waitcnt lgkmcnt(6)
	v_mfma_f32_16x16x32_bf16 v[12:15], v[176:179], v[92:95], v[12:15]
	ds_read_b128 v[232:235], v247 offset:36864
	global_load_lds_dwordx4 v241, s[76:77]
	s_waitcnt lgkmcnt(6)
	v_mfma_f32_16x16x32_bf16 v[16:19], v[180:183], v[80:83], v[16:19]
	ds_read_b128 v[236:239], v247 offset:38912
	s_add_i32 m0, s81, 8192
	v_mfma_f32_16x16x32_bf16 v[20:23], v[180:183], v[84:87], v[20:23]
	ds_read_b128 v[212:215], v245 offset:34816
	global_load_lds_dwordx4 v242, s[76:77]
	v_mfma_f32_16x16x32_bf16 v[24:27], v[180:183], v[88:91], v[24:27]
	ds_read_b128 v[216:219], v245 offset:36864
	s_add_i32 m0, s81, 12288
	v_mfma_f32_16x16x32_bf16 v[28:31], v[180:183], v[92:95], v[28:31]
	ds_read_b128 v[220:223], v245 offset:38912
	global_load_lds_dwordx4 v243, s[76:77]
	s_waitcnt lgkmcnt(9)
	v_mfma_f32_16x16x32_bf16 v[32:35], v[184:187], v[80:83], v[32:35]
	s_add_i32 m0, s81, 16384
	v_mfma_f32_16x16x32_bf16 v[36:39], v[184:187], v[84:87], v[36:39]
	global_load_lds_dwordx4 v240, s[78:79]
	v_mfma_f32_16x16x32_bf16 v[40:43], v[184:187], v[88:91], v[40:43]
	s_add_i32 m0, s81, 20480
	v_mfma_f32_16x16x32_bf16 v[44:47], v[184:187], v[92:95], v[44:47]
	global_load_lds_dwordx4 v241, s[78:79]
	s_waitcnt lgkmcnt(8)
	v_mfma_f32_16x16x32_bf16 v[48:51], v[188:191], v[80:83], v[48:51]
	s_add_i32 m0, s81, 24576
	v_mfma_f32_16x16x32_bf16 v[52:55], v[188:191], v[84:87], v[52:55]
	global_load_lds_dwordx4 v242, s[78:79]
	v_mfma_f32_16x16x32_bf16 v[56:59], v[188:191], v[88:91], v[56:59]
	s_add_i32 m0, s81, 28672
	v_mfma_f32_16x16x32_bf16 v[60:63], v[188:191], v[92:95], v[60:63]
	global_load_lds_dwordx4 v243, s[78:79]
	s_waitcnt lgkmcnt(6)
	v_mfma_f32_16x16x32_bf16 v[0:3], v[208:211], v[224:227], v[0:3]
	s_add_u32 s76, s76, 0x80
	s_addc_u32 s77, s77, 0
	s_waitcnt lgkmcnt(5)
	v_mfma_f32_16x16x32_bf16 v[4:7], v[208:211], v[228:231], v[4:7]
	s_waitcnt lgkmcnt(4)
	v_mfma_f32_16x16x32_bf16 v[8:11], v[208:211], v[232:235], v[8:11]
	s_add_u32 s78, s78, 0x80
	s_addc_u32 s79, s79, 0
	s_waitcnt lgkmcnt(3)
	v_mfma_f32_16x16x32_bf16 v[12:15], v[208:211], v[236:239], v[12:15]
	s_waitcnt lgkmcnt(2)
	v_mfma_f32_16x16x32_bf16 v[16:19], v[212:215], v[224:227], v[16:19]
	v_add_u32_e32 v96, 0x30000, v102
	v_mfma_f32_16x16x32_bf16 v[20:23], v[212:215], v[228:231], v[20:23]
	global_load_dwordx4 v[116:119], v96, s[86:87] nt
	v_mfma_f32_16x16x32_bf16 v[24:27], v[212:215], v[232:235], v[24:27]
	v_mfma_f32_16x16x32_bf16 v[28:31], v[212:215], v[236:239], v[28:31]
	s_waitcnt lgkmcnt(1)
	v_mfma_f32_16x16x32_bf16 v[32:35], v[216:219], v[224:227], v[32:35]
	v_mfma_f32_16x16x32_bf16 v[36:39], v[216:219], v[228:231], v[36:39]
	v_mfma_f32_16x16x32_bf16 v[40:43], v[216:219], v[232:235], v[40:43]
	v_mfma_f32_16x16x32_bf16 v[44:47], v[216:219], v[236:239], v[44:47]
	s_waitcnt lgkmcnt(0)
	v_mfma_f32_16x16x32_bf16 v[48:51], v[220:223], v[224:227], v[48:51]
	v_mfma_f32_16x16x32_bf16 v[52:55], v[220:223], v[228:231], v[52:55]
	v_mfma_f32_16x16x32_bf16 v[56:59], v[220:223], v[232:235], v[56:59]
	v_mfma_f32_16x16x32_bf16 v[60:63], v[220:223], v[236:239], v[60:63]
	s_waitcnt vmcnt(1)
	s_barrier
	ds_read_b128 v[176:179], v244 offset:0
	ds_read_b128 v[80:83], v246 offset:0
	ds_read_b128 v[84:87], v246 offset:2048
	ds_read_b128 v[88:91], v246 offset:4096
	ds_read_b128 v[92:95], v246 offset:6144
	ds_read_b128 v[180:183], v244 offset:2048
	ds_read_b128 v[184:187], v244 offset:4096
	ds_read_b128 v[188:191], v244 offset:6144
	s_waitcnt lgkmcnt(6)
	v_mfma_f32_16x16x32_bf16 v[0:3], v[176:179], v[80:83], v[0:3]
	ds_read_b128 v[208:211], v245 offset:0
	s_add_i32 m0, s81, 32768
	s_waitcnt lgkmcnt(6)
	v_mfma_f32_16x16x32_bf16 v[4:7], v[176:179], v[84:87], v[4:7]
	ds_read_b128 v[224:227], v247 offset:0
	global_load_lds_dwordx4 v240, s[76:77]
	s_waitcnt lgkmcnt(6)
	v_mfma_f32_16x16x32_bf16 v[8:11], v[176:179], v[88:91], v[8:11]
	ds_read_b128 v[228:231], v247 offset:2048
	s_add_i32 m0, s81, 36864
	s_waitcnt lgkmcnt(6)
	v_mfma_f32_16x16x32_bf16 v[12:15], v[176:179], v[92:95], v[12:15]
	ds_read_b128 v[232:235], v247 offset:4096
	global_load_lds_dwordx4 v241, s[76:77]
	s_waitcnt lgkmcnt(6)
	v_mfma_f32_16x16x32_bf16 v[16:19], v[180:183], v[80:83], v[16:19]
	ds_read_b128 v[236:239], v247 offset:6144
	s_add_i32 m0, s81, 40960
	v_mfma_f32_16x16x32_bf16 v[20:23], v[180:183], v[84:87], v[20:23]
	ds_read_b128 v[212:215], v245 offset:2048
	global_load_lds_dwordx4 v242, s[76:77]
	v_mfma_f32_16x16x32_bf16 v[24:27], v[180:183], v[88:91], v[24:27]
	ds_read_b128 v[216:219], v245 offset:4096
	s_add_i32 m0, s81, 45056
	v_mfma_f32_16x16x32_bf16 v[28:31], v[180:183], v[92:95], v[28:31]
	ds_read_b128 v[220:223], v245 offset:6144
	global_load_lds_dwordx4 v243, s[76:77]
	s_waitcnt lgkmcnt(9)
	v_mfma_f32_16x16x32_bf16 v[32:35], v[184:187], v[80:83], v[32:35]
	s_add_i32 m0, s81, 49152
	v_mfma_f32_16x16x32_bf16 v[36:39], v[184:187], v[84:87], v[36:39]
	global_load_lds_dwordx4 v240, s[78:79]
	v_mfma_f32_16x16x32_bf16 v[40:43], v[184:187], v[88:91], v[40:43]
	s_add_i32 m0, s81, 53248
	v_mfma_f32_16x16x32_bf16 v[44:47], v[184:187], v[92:95], v[44:47]
	global_load_lds_dwordx4 v241, s[78:79]
	s_waitcnt lgkmcnt(8)
	v_mfma_f32_16x16x32_bf16 v[48:51], v[188:191], v[80:83], v[48:51]
	s_add_i32 m0, s81, 57344
	v_mfma_f32_16x16x32_bf16 v[52:55], v[188:191], v[84:87], v[52:55]
	global_load_lds_dwordx4 v242, s[78:79]
	v_mfma_f32_16x16x32_bf16 v[56:59], v[188:191], v[88:91], v[56:59]
	s_add_i32 m0, s81, 61440
	v_mfma_f32_16x16x32_bf16 v[60:63], v[188:191], v[92:95], v[60:63]
	global_load_lds_dwordx4 v243, s[78:79]
	s_waitcnt lgkmcnt(6)
	v_mfma_f32_16x16x32_bf16 v[0:3], v[208:211], v[224:227], v[0:3]
	s_add_u32 s76, s76, 0x80
	s_addc_u32 s77, s77, 0
	s_waitcnt lgkmcnt(5)
	v_mfma_f32_16x16x32_bf16 v[4:7], v[208:211], v[228:231], v[4:7]
	s_waitcnt lgkmcnt(4)
	v_mfma_f32_16x16x32_bf16 v[8:11], v[208:211], v[232:235], v[8:11]
	s_add_u32 s78, s78, 0x80
	s_addc_u32 s79, s79, 0
	s_waitcnt lgkmcnt(3)
	v_mfma_f32_16x16x32_bf16 v[12:15], v[208:211], v[236:239], v[12:15]
	s_waitcnt lgkmcnt(2)
	v_mfma_f32_16x16x32_bf16 v[16:19], v[212:215], v[224:227], v[16:19]
	v_add_u32_e32 v96, 0x30000, v102
	v_mfma_f32_16x16x32_bf16 v[20:23], v[212:215], v[228:231], v[20:23]
	global_load_dwordx4 v[120:123], v96, s[86:87] offset:16 nt
	v_mfma_f32_16x16x32_bf16 v[24:27], v[212:215], v[232:235], v[24:27]
	v_mfma_f32_16x16x32_bf16 v[28:31], v[212:215], v[236:239], v[28:31]
	s_waitcnt lgkmcnt(1)
	v_mfma_f32_16x16x32_bf16 v[32:35], v[216:219], v[224:227], v[32:35]
	v_mfma_f32_16x16x32_bf16 v[36:39], v[216:219], v[228:231], v[36:39]
	v_mfma_f32_16x16x32_bf16 v[40:43], v[216:219], v[232:235], v[40:43]
	v_mfma_f32_16x16x32_bf16 v[44:47], v[216:219], v[236:239], v[44:47]
	s_waitcnt lgkmcnt(0)
	v_mfma_f32_16x16x32_bf16 v[48:51], v[220:223], v[224:227], v[48:51]
	v_mfma_f32_16x16x32_bf16 v[52:55], v[220:223], v[228:231], v[52:55]
	v_mfma_f32_16x16x32_bf16 v[56:59], v[220:223], v[232:235], v[56:59]
	v_mfma_f32_16x16x32_bf16 v[60:63], v[220:223], v[236:239], v[60:63]
	s_waitcnt vmcnt(1)
	s_barrier
	ds_read_b128 v[176:179], v244 offset:32768
	ds_read_b128 v[80:83], v246 offset:32768
	ds_read_b128 v[84:87], v246 offset:34816
	ds_read_b128 v[88:91], v246 offset:36864
	ds_read_b128 v[92:95], v246 offset:38912
	ds_read_b128 v[180:183], v244 offset:34816
	ds_read_b128 v[184:187], v244 offset:36864
	ds_read_b128 v[188:191], v244 offset:38912
	s_waitcnt lgkmcnt(6)
	v_mfma_f32_16x16x32_bf16 v[0:3], v[176:179], v[80:83], v[0:3]
	ds_read_b128 v[208:211], v245 offset:32768
	s_add_i32 m0, s81, 0
	s_waitcnt lgkmcnt(6)
	v_mfma_f32_16x16x32_bf16 v[4:7], v[176:179], v[84:87], v[4:7]
	ds_read_b128 v[224:227], v247 offset:32768
	global_load_lds_dwordx4 v240, s[76:77]
	s_waitcnt lgkmcnt(6)
	v_mfma_f32_16x16x32_bf16 v[8:11], v[176:179], v[88:91], v[8:11]
	ds_read_b128 v[228:231], v247 offset:34816
	s_add_i32 m0, s81, 4096
	s_waitcnt lgkmcnt(6)
	v_mfma_f32_16x16x32_bf16 v[12:15], v[176:179], v[92:95], v[12:15]
	ds_read_b128 v[232:235], v247 offset:36864
	global_load_lds_dwordx4 v241, s[76:77]
	s_waitcnt lgkmcnt(6)
	v_mfma_f32_16x16x32_bf16 v[16:19], v[180:183], v[80:83], v[16:19]
	ds_read_b128 v[236:239], v247 offset:38912
	s_add_i32 m0, s81, 8192
	v_mfma_f32_16x16x32_bf16 v[20:23], v[180:183], v[84:87], v[20:23]
	ds_read_b128 v[212:215], v245 offset:34816
	global_load_lds_dwordx4 v242, s[76:77]
	v_mfma_f32_16x16x32_bf16 v[24:27], v[180:183], v[88:91], v[24:27]
	ds_read_b128 v[216:219], v245 offset:36864
	s_add_i32 m0, s81, 12288
	v_mfma_f32_16x16x32_bf16 v[28:31], v[180:183], v[92:95], v[28:31]
	ds_read_b128 v[220:223], v245 offset:38912
	global_load_lds_dwordx4 v243, s[76:77]
	s_waitcnt lgkmcnt(9)
	v_mfma_f32_16x16x32_bf16 v[32:35], v[184:187], v[80:83], v[32:35]
	s_add_i32 m0, s81, 16384
	v_mfma_f32_16x16x32_bf16 v[36:39], v[184:187], v[84:87], v[36:39]
	global_load_lds_dwordx4 v240, s[78:79]
	v_mfma_f32_16x16x32_bf16 v[40:43], v[184:187], v[88:91], v[40:43]
	s_add_i32 m0, s81, 20480
	v_mfma_f32_16x16x32_bf16 v[44:47], v[184:187], v[92:95], v[44:47]
	global_load_lds_dwordx4 v241, s[78:79]
	s_waitcnt lgkmcnt(8)
	v_mfma_f32_16x16x32_bf16 v[48:51], v[188:191], v[80:83], v[48:51]
	s_add_i32 m0, s81, 24576
	v_mfma_f32_16x16x32_bf16 v[52:55], v[188:191], v[84:87], v[52:55]
	global_load_lds_dwordx4 v242, s[78:79]
	v_mfma_f32_16x16x32_bf16 v[56:59], v[188:191], v[88:91], v[56:59]
	s_add_i32 m0, s81, 28672
	v_mfma_f32_16x16x32_bf16 v[60:63], v[188:191], v[92:95], v[60:63]
	global_load_lds_dwordx4 v243, s[78:79]
	s_waitcnt lgkmcnt(6)
	v_mfma_f32_16x16x32_bf16 v[0:3], v[208:211], v[224:227], v[0:3]
	s_add_u32 s76, s76, 0x80
	s_addc_u32 s77, s77, 0
	s_waitcnt lgkmcnt(5)
	v_mfma_f32_16x16x32_bf16 v[4:7], v[208:211], v[228:231], v[4:7]
	s_waitcnt lgkmcnt(4)
	v_mfma_f32_16x16x32_bf16 v[8:11], v[208:211], v[232:235], v[8:11]
	s_add_u32 s78, s78, 0x80
	s_addc_u32 s79, s79, 0
	s_waitcnt lgkmcnt(3)
	v_mfma_f32_16x16x32_bf16 v[12:15], v[208:211], v[236:239], v[12:15]
	s_waitcnt lgkmcnt(2)
	v_mfma_f32_16x16x32_bf16 v[16:19], v[212:215], v[224:227], v[16:19]
	v_add_u32_e32 v96, 0x40000, v102
	v_mfma_f32_16x16x32_bf16 v[20:23], v[212:215], v[228:231], v[20:23]
	global_load_dwordx4 v[126:129], v96, s[86:87] nt
	v_mfma_f32_16x16x32_bf16 v[24:27], v[212:215], v[232:235], v[24:27]
	v_mfma_f32_16x16x32_bf16 v[28:31], v[212:215], v[236:239], v[28:31]
	s_waitcnt lgkmcnt(1)
	v_mfma_f32_16x16x32_bf16 v[32:35], v[216:219], v[224:227], v[32:35]
	v_mfma_f32_16x16x32_bf16 v[36:39], v[216:219], v[228:231], v[36:39]
	v_mfma_f32_16x16x32_bf16 v[40:43], v[216:219], v[232:235], v[40:43]
	v_mfma_f32_16x16x32_bf16 v[44:47], v[216:219], v[236:239], v[44:47]
	s_waitcnt lgkmcnt(0)
	v_mfma_f32_16x16x32_bf16 v[48:51], v[220:223], v[224:227], v[48:51]
	v_mfma_f32_16x16x32_bf16 v[52:55], v[220:223], v[228:231], v[52:55]
	v_mfma_f32_16x16x32_bf16 v[56:59], v[220:223], v[232:235], v[56:59]
	v_mfma_f32_16x16x32_bf16 v[60:63], v[220:223], v[236:239], v[60:63]
	s_waitcnt vmcnt(1)
	s_barrier
	ds_read_b128 v[176:179], v244 offset:0
	ds_read_b128 v[80:83], v246 offset:0
	ds_read_b128 v[84:87], v246 offset:2048
	ds_read_b128 v[88:91], v246 offset:4096
	ds_read_b128 v[92:95], v246 offset:6144
	ds_read_b128 v[180:183], v244 offset:2048
	ds_read_b128 v[184:187], v244 offset:4096
	ds_read_b128 v[188:191], v244 offset:6144
	s_waitcnt lgkmcnt(6)
	v_mfma_f32_16x16x32_bf16 v[0:3], v[176:179], v[80:83], v[0:3]
	ds_read_b128 v[208:211], v245 offset:0
	s_add_i32 m0, s81, 32768
	s_waitcnt lgkmcnt(6)
	v_mfma_f32_16x16x32_bf16 v[4:7], v[176:179], v[84:87], v[4:7]
	ds_read_b128 v[224:227], v247 offset:0
	global_load_lds_dwordx4 v240, s[76:77]
	s_waitcnt lgkmcnt(6)
	v_mfma_f32_16x16x32_bf16 v[8:11], v[176:179], v[88:91], v[8:11]
	ds_read_b128 v[228:231], v247 offset:2048
	s_add_i32 m0, s81, 36864
	s_waitcnt lgkmcnt(6)
	v_mfma_f32_16x16x32_bf16 v[12:15], v[176:179], v[92:95], v[12:15]
	ds_read_b128 v[232:235], v247 offset:4096
	global_load_lds_dwordx4 v241, s[76:77]
	s_waitcnt lgkmcnt(6)
	v_mfma_f32_16x16x32_bf16 v[16:19], v[180:183], v[80:83], v[16:19]
	ds_read_b128 v[236:239], v247 offset:6144
	s_add_i32 m0, s81, 40960
	v_mfma_f32_16x16x32_bf16 v[20:23], v[180:183], v[84:87], v[20:23]
	ds_read_b128 v[212:215], v245 offset:2048
	global_load_lds_dwordx4 v242, s[76:77]
	v_mfma_f32_16x16x32_bf16 v[24:27], v[180:183], v[88:91], v[24:27]
	ds_read_b128 v[216:219], v245 offset:4096
	s_add_i32 m0, s81, 45056
	v_mfma_f32_16x16x32_bf16 v[28:31], v[180:183], v[92:95], v[28:31]
	ds_read_b128 v[220:223], v245 offset:6144
	global_load_lds_dwordx4 v243, s[76:77]
	s_waitcnt lgkmcnt(9)
	v_mfma_f32_16x16x32_bf16 v[32:35], v[184:187], v[80:83], v[32:35]
	s_add_i32 m0, s81, 49152
	v_mfma_f32_16x16x32_bf16 v[36:39], v[184:187], v[84:87], v[36:39]
	global_load_lds_dwordx4 v240, s[78:79]
	v_mfma_f32_16x16x32_bf16 v[40:43], v[184:187], v[88:91], v[40:43]
	s_add_i32 m0, s81, 53248
	v_mfma_f32_16x16x32_bf16 v[44:47], v[184:187], v[92:95], v[44:47]
	global_load_lds_dwordx4 v241, s[78:79]
	s_waitcnt lgkmcnt(8)
	v_mfma_f32_16x16x32_bf16 v[48:51], v[188:191], v[80:83], v[48:51]
	s_add_i32 m0, s81, 57344
	v_mfma_f32_16x16x32_bf16 v[52:55], v[188:191], v[84:87], v[52:55]
	global_load_lds_dwordx4 v242, s[78:79]
	v_mfma_f32_16x16x32_bf16 v[56:59], v[188:191], v[88:91], v[56:59]
	s_add_i32 m0, s81, 61440
	v_mfma_f32_16x16x32_bf16 v[60:63], v[188:191], v[92:95], v[60:63]
	global_load_lds_dwordx4 v243, s[78:79]
	s_waitcnt lgkmcnt(6)
	v_mfma_f32_16x16x32_bf16 v[0:3], v[208:211], v[224:227], v[0:3]
	s_add_u32 s76, s76, 0x80
	s_addc_u32 s77, s77, 0
	s_waitcnt lgkmcnt(5)
	v_mfma_f32_16x16x32_bf16 v[4:7], v[208:211], v[228:231], v[4:7]
	s_waitcnt lgkmcnt(4)
	v_mfma_f32_16x16x32_bf16 v[8:11], v[208:211], v[232:235], v[8:11]
	s_add_u32 s78, s78, 0x80
	s_addc_u32 s79, s79, 0
	s_waitcnt lgkmcnt(3)
	v_mfma_f32_16x16x32_bf16 v[12:15], v[208:211], v[236:239], v[12:15]
	s_waitcnt lgkmcnt(2)
	v_mfma_f32_16x16x32_bf16 v[16:19], v[212:215], v[224:227], v[16:19]
	v_add_u32_e32 v96, 0x40000, v102
	v_mfma_f32_16x16x32_bf16 v[20:23], v[212:215], v[228:231], v[20:23]
	global_load_dwordx4 v[168:171], v96, s[86:87] offset:16 nt
	v_mfma_f32_16x16x32_bf16 v[24:27], v[212:215], v[232:235], v[24:27]
	v_mfma_f32_16x16x32_bf16 v[28:31], v[212:215], v[236:239], v[28:31]
	s_waitcnt lgkmcnt(1)
	v_mfma_f32_16x16x32_bf16 v[32:35], v[216:219], v[224:227], v[32:35]
	v_mfma_f32_16x16x32_bf16 v[36:39], v[216:219], v[228:231], v[36:39]
	v_mfma_f32_16x16x32_bf16 v[40:43], v[216:219], v[232:235], v[40:43]
	v_mfma_f32_16x16x32_bf16 v[44:47], v[216:219], v[236:239], v[44:47]
	s_waitcnt lgkmcnt(0)
	v_mfma_f32_16x16x32_bf16 v[48:51], v[220:223], v[224:227], v[48:51]
	v_mfma_f32_16x16x32_bf16 v[52:55], v[220:223], v[228:231], v[52:55]
	v_mfma_f32_16x16x32_bf16 v[56:59], v[220:223], v[232:235], v[56:59]
	v_mfma_f32_16x16x32_bf16 v[60:63], v[220:223], v[236:239], v[60:63]
	s_waitcnt vmcnt(1)
	s_barrier
	ds_read_b128 v[176:179], v244 offset:32768
	ds_read_b128 v[80:83], v246 offset:32768
	ds_read_b128 v[84:87], v246 offset:34816
	ds_read_b128 v[88:91], v246 offset:36864
	ds_read_b128 v[92:95], v246 offset:38912
	ds_read_b128 v[180:183], v244 offset:34816
	ds_read_b128 v[184:187], v244 offset:36864
	ds_read_b128 v[188:191], v244 offset:38912
	s_waitcnt lgkmcnt(6)
	v_mfma_f32_16x16x32_bf16 v[0:3], v[176:179], v[80:83], v[0:3]
	ds_read_b128 v[208:211], v245 offset:32768
	s_add_i32 m0, s81, 0
	s_waitcnt lgkmcnt(6)
	v_mfma_f32_16x16x32_bf16 v[4:7], v[176:179], v[84:87], v[4:7]
	ds_read_b128 v[224:227], v247 offset:32768
	global_load_lds_dwordx4 v240, s[76:77]
	s_waitcnt lgkmcnt(6)
	v_mfma_f32_16x16x32_bf16 v[8:11], v[176:179], v[88:91], v[8:11]
	ds_read_b128 v[228:231], v247 offset:34816
	s_add_i32 m0, s81, 4096
	s_waitcnt lgkmcnt(6)
	v_mfma_f32_16x16x32_bf16 v[12:15], v[176:179], v[92:95], v[12:15]
	ds_read_b128 v[232:235], v247 offset:36864
	global_load_lds_dwordx4 v241, s[76:77]
	s_waitcnt lgkmcnt(6)
	v_mfma_f32_16x16x32_bf16 v[16:19], v[180:183], v[80:83], v[16:19]
	ds_read_b128 v[236:239], v247 offset:38912
	s_add_i32 m0, s81, 8192
	v_mfma_f32_16x16x32_bf16 v[20:23], v[180:183], v[84:87], v[20:23]
	ds_read_b128 v[212:215], v245 offset:34816
	global_load_lds_dwordx4 v242, s[76:77]
	v_mfma_f32_16x16x32_bf16 v[24:27], v[180:183], v[88:91], v[24:27]
	ds_read_b128 v[216:219], v245 offset:36864
	s_add_i32 m0, s81, 12288
	v_mfma_f32_16x16x32_bf16 v[28:31], v[180:183], v[92:95], v[28:31]
	ds_read_b128 v[220:223], v245 offset:38912
	global_load_lds_dwordx4 v243, s[76:77]
	s_waitcnt lgkmcnt(9)
	v_mfma_f32_16x16x32_bf16 v[32:35], v[184:187], v[80:83], v[32:35]
	s_add_i32 m0, s81, 16384
	v_mfma_f32_16x16x32_bf16 v[36:39], v[184:187], v[84:87], v[36:39]
	global_load_lds_dwordx4 v240, s[78:79]
	v_mfma_f32_16x16x32_bf16 v[40:43], v[184:187], v[88:91], v[40:43]
	s_add_i32 m0, s81, 20480
	v_mfma_f32_16x16x32_bf16 v[44:47], v[184:187], v[92:95], v[44:47]
	global_load_lds_dwordx4 v241, s[78:79]
	s_waitcnt lgkmcnt(8)
	v_mfma_f32_16x16x32_bf16 v[48:51], v[188:191], v[80:83], v[48:51]
	s_add_i32 m0, s81, 24576
	v_mfma_f32_16x16x32_bf16 v[52:55], v[188:191], v[84:87], v[52:55]
	global_load_lds_dwordx4 v242, s[78:79]
	v_mfma_f32_16x16x32_bf16 v[56:59], v[188:191], v[88:91], v[56:59]
	s_add_i32 m0, s81, 28672
	v_mfma_f32_16x16x32_bf16 v[60:63], v[188:191], v[92:95], v[60:63]
	global_load_lds_dwordx4 v243, s[78:79]
	s_waitcnt lgkmcnt(6)
	v_mfma_f32_16x16x32_bf16 v[0:3], v[208:211], v[224:227], v[0:3]
	s_add_u32 s76, s76, 0x80
	s_addc_u32 s77, s77, 0
	s_waitcnt lgkmcnt(5)
	v_mfma_f32_16x16x32_bf16 v[4:7], v[208:211], v[228:231], v[4:7]
	s_waitcnt lgkmcnt(4)
	v_mfma_f32_16x16x32_bf16 v[8:11], v[208:211], v[232:235], v[8:11]
	s_add_u32 s78, s78, 0x80
	s_addc_u32 s79, s79, 0
	s_waitcnt lgkmcnt(3)
	v_mfma_f32_16x16x32_bf16 v[12:15], v[208:211], v[236:239], v[12:15]
	s_waitcnt lgkmcnt(2)
	v_mfma_f32_16x16x32_bf16 v[16:19], v[212:215], v[224:227], v[16:19]
	v_add_u32_e32 v96, 0x50000, v102
	v_mfma_f32_16x16x32_bf16 v[20:23], v[212:215], v[228:231], v[20:23]
	global_load_dwordx4 v[192:195], v96, s[86:87] nt
	v_mfma_f32_16x16x32_bf16 v[24:27], v[212:215], v[232:235], v[24:27]
	v_mfma_f32_16x16x32_bf16 v[28:31], v[212:215], v[236:239], v[28:31]
	s_waitcnt lgkmcnt(1)
	v_mfma_f32_16x16x32_bf16 v[32:35], v[216:219], v[224:227], v[32:35]
	v_mfma_f32_16x16x32_bf16 v[36:39], v[216:219], v[228:231], v[36:39]
	v_mfma_f32_16x16x32_bf16 v[40:43], v[216:219], v[232:235], v[40:43]
	v_mfma_f32_16x16x32_bf16 v[44:47], v[216:219], v[236:239], v[44:47]
	s_waitcnt lgkmcnt(0)
	v_mfma_f32_16x16x32_bf16 v[48:51], v[220:223], v[224:227], v[48:51]
	v_mfma_f32_16x16x32_bf16 v[52:55], v[220:223], v[228:231], v[52:55]
	v_mfma_f32_16x16x32_bf16 v[56:59], v[220:223], v[232:235], v[56:59]
	v_mfma_f32_16x16x32_bf16 v[60:63], v[220:223], v[236:239], v[60:63]
	s_waitcnt vmcnt(1)
	s_barrier
	ds_read_b128 v[176:179], v244 offset:0
	ds_read_b128 v[80:83], v246 offset:0
	ds_read_b128 v[84:87], v246 offset:2048
	ds_read_b128 v[88:91], v246 offset:4096
	ds_read_b128 v[92:95], v246 offset:6144
	ds_read_b128 v[180:183], v244 offset:2048
	ds_read_b128 v[184:187], v244 offset:4096
	ds_read_b128 v[188:191], v244 offset:6144
	s_waitcnt lgkmcnt(6)
	v_mfma_f32_16x16x32_bf16 v[0:3], v[176:179], v[80:83], v[0:3]
	ds_read_b128 v[208:211], v245 offset:0
	s_add_i32 m0, s81, 32768
	s_waitcnt lgkmcnt(6)
	v_mfma_f32_16x16x32_bf16 v[4:7], v[176:179], v[84:87], v[4:7]
	ds_read_b128 v[224:227], v247 offset:0
	global_load_lds_dwordx4 v240, s[76:77]
	s_waitcnt lgkmcnt(6)
	v_mfma_f32_16x16x32_bf16 v[8:11], v[176:179], v[88:91], v[8:11]
	ds_read_b128 v[228:231], v247 offset:2048
	s_add_i32 m0, s81, 36864
	s_waitcnt lgkmcnt(6)
	v_mfma_f32_16x16x32_bf16 v[12:15], v[176:179], v[92:95], v[12:15]
	ds_read_b128 v[232:235], v247 offset:4096
	global_load_lds_dwordx4 v241, s[76:77]
	s_waitcnt lgkmcnt(6)
	v_mfma_f32_16x16x32_bf16 v[16:19], v[180:183], v[80:83], v[16:19]
	ds_read_b128 v[236:239], v247 offset:6144
	s_add_i32 m0, s81, 40960
	v_mfma_f32_16x16x32_bf16 v[20:23], v[180:183], v[84:87], v[20:23]
	ds_read_b128 v[212:215], v245 offset:2048
	global_load_lds_dwordx4 v242, s[76:77]
	v_mfma_f32_16x16x32_bf16 v[24:27], v[180:183], v[88:91], v[24:27]
	ds_read_b128 v[216:219], v245 offset:4096
	s_add_i32 m0, s81, 45056
	v_mfma_f32_16x16x32_bf16 v[28:31], v[180:183], v[92:95], v[28:31]
	ds_read_b128 v[220:223], v245 offset:6144
	global_load_lds_dwordx4 v243, s[76:77]
	s_waitcnt lgkmcnt(9)
	v_mfma_f32_16x16x32_bf16 v[32:35], v[184:187], v[80:83], v[32:35]
	s_add_i32 m0, s81, 49152
	v_mfma_f32_16x16x32_bf16 v[36:39], v[184:187], v[84:87], v[36:39]
	global_load_lds_dwordx4 v240, s[78:79]
	v_mfma_f32_16x16x32_bf16 v[40:43], v[184:187], v[88:91], v[40:43]
	s_add_i32 m0, s81, 53248
	v_mfma_f32_16x16x32_bf16 v[44:47], v[184:187], v[92:95], v[44:47]
	global_load_lds_dwordx4 v241, s[78:79]
	s_waitcnt lgkmcnt(8)
	v_mfma_f32_16x16x32_bf16 v[48:51], v[188:191], v[80:83], v[48:51]
	s_add_i32 m0, s81, 57344
	v_mfma_f32_16x16x32_bf16 v[52:55], v[188:191], v[84:87], v[52:55]
	global_load_lds_dwordx4 v242, s[78:79]
	v_mfma_f32_16x16x32_bf16 v[56:59], v[188:191], v[88:91], v[56:59]
	s_add_i32 m0, s81, 61440
	v_mfma_f32_16x16x32_bf16 v[60:63], v[188:191], v[92:95], v[60:63]
	global_load_lds_dwordx4 v243, s[78:79]
	s_waitcnt lgkmcnt(6)
	v_mfma_f32_16x16x32_bf16 v[0:3], v[208:211], v[224:227], v[0:3]
	s_add_u32 s76, s76, 0x80
	s_addc_u32 s77, s77, 0
	s_waitcnt lgkmcnt(5)
	v_mfma_f32_16x16x32_bf16 v[4:7], v[208:211], v[228:231], v[4:7]
	s_waitcnt lgkmcnt(4)
	v_mfma_f32_16x16x32_bf16 v[8:11], v[208:211], v[232:235], v[8:11]
	s_add_u32 s78, s78, 0x80
	s_addc_u32 s79, s79, 0
	s_waitcnt lgkmcnt(3)
	v_mfma_f32_16x16x32_bf16 v[12:15], v[208:211], v[236:239], v[12:15]
	s_waitcnt lgkmcnt(2)
	v_mfma_f32_16x16x32_bf16 v[16:19], v[212:215], v[224:227], v[16:19]
	v_add_u32_e32 v96, 0x50000, v102
	v_mfma_f32_16x16x32_bf16 v[20:23], v[212:215], v[228:231], v[20:23]
	global_load_dwordx4 v[196:199], v96, s[86:87] offset:16 nt
	v_mfma_f32_16x16x32_bf16 v[24:27], v[212:215], v[232:235], v[24:27]
	v_mfma_f32_16x16x32_bf16 v[28:31], v[212:215], v[236:239], v[28:31]
	s_waitcnt lgkmcnt(1)
	v_mfma_f32_16x16x32_bf16 v[32:35], v[216:219], v[224:227], v[32:35]
	v_mfma_f32_16x16x32_bf16 v[36:39], v[216:219], v[228:231], v[36:39]
	v_mfma_f32_16x16x32_bf16 v[40:43], v[216:219], v[232:235], v[40:43]
	v_mfma_f32_16x16x32_bf16 v[44:47], v[216:219], v[236:239], v[44:47]
	s_waitcnt lgkmcnt(0)
	v_mfma_f32_16x16x32_bf16 v[48:51], v[220:223], v[224:227], v[48:51]
	v_mfma_f32_16x16x32_bf16 v[52:55], v[220:223], v[228:231], v[52:55]
	v_mfma_f32_16x16x32_bf16 v[56:59], v[220:223], v[232:235], v[56:59]
	v_mfma_f32_16x16x32_bf16 v[60:63], v[220:223], v[236:239], v[60:63]
	s_waitcnt vmcnt(1)
	s_barrier
	ds_read_b128 v[176:179], v244 offset:32768
	ds_read_b128 v[80:83], v246 offset:32768
	ds_read_b128 v[84:87], v246 offset:34816
	ds_read_b128 v[88:91], v246 offset:36864
	ds_read_b128 v[92:95], v246 offset:38912
	ds_read_b128 v[180:183], v244 offset:34816
	ds_read_b128 v[184:187], v244 offset:36864
	ds_read_b128 v[188:191], v244 offset:38912
	s_waitcnt lgkmcnt(6)
	v_mfma_f32_16x16x32_bf16 v[0:3], v[176:179], v[80:83], v[0:3]
	ds_read_b128 v[208:211], v245 offset:32768
	s_add_i32 m0, s81, 0
	s_waitcnt lgkmcnt(6)
	v_mfma_f32_16x16x32_bf16 v[4:7], v[176:179], v[84:87], v[4:7]
	ds_read_b128 v[224:227], v247 offset:32768
	global_load_lds_dwordx4 v240, s[76:77]
	s_waitcnt lgkmcnt(6)
	v_mfma_f32_16x16x32_bf16 v[8:11], v[176:179], v[88:91], v[8:11]
	ds_read_b128 v[228:231], v247 offset:34816
	s_add_i32 m0, s81, 4096
	s_waitcnt lgkmcnt(6)
	v_mfma_f32_16x16x32_bf16 v[12:15], v[176:179], v[92:95], v[12:15]
	ds_read_b128 v[232:235], v247 offset:36864
	global_load_lds_dwordx4 v241, s[76:77]
	s_waitcnt lgkmcnt(6)
	v_mfma_f32_16x16x32_bf16 v[16:19], v[180:183], v[80:83], v[16:19]
	ds_read_b128 v[236:239], v247 offset:38912
	s_add_i32 m0, s81, 8192
	v_mfma_f32_16x16x32_bf16 v[20:23], v[180:183], v[84:87], v[20:23]
	ds_read_b128 v[212:215], v245 offset:34816
	global_load_lds_dwordx4 v242, s[76:77]
	v_mfma_f32_16x16x32_bf16 v[24:27], v[180:183], v[88:91], v[24:27]
	ds_read_b128 v[216:219], v245 offset:36864
	s_add_i32 m0, s81, 12288
	v_mfma_f32_16x16x32_bf16 v[28:31], v[180:183], v[92:95], v[28:31]
	ds_read_b128 v[220:223], v245 offset:38912
	global_load_lds_dwordx4 v243, s[76:77]
	s_waitcnt lgkmcnt(9)
	v_mfma_f32_16x16x32_bf16 v[32:35], v[184:187], v[80:83], v[32:35]
	s_add_i32 m0, s81, 16384
	v_mfma_f32_16x16x32_bf16 v[36:39], v[184:187], v[84:87], v[36:39]
	global_load_lds_dwordx4 v240, s[78:79]
	v_mfma_f32_16x16x32_bf16 v[40:43], v[184:187], v[88:91], v[40:43]
	s_add_i32 m0, s81, 20480
	v_mfma_f32_16x16x32_bf16 v[44:47], v[184:187], v[92:95], v[44:47]
	global_load_lds_dwordx4 v241, s[78:79]
	s_waitcnt lgkmcnt(8)
	v_mfma_f32_16x16x32_bf16 v[48:51], v[188:191], v[80:83], v[48:51]
	s_add_i32 m0, s81, 24576
	v_mfma_f32_16x16x32_bf16 v[52:55], v[188:191], v[84:87], v[52:55]
	global_load_lds_dwordx4 v242, s[78:79]
	v_mfma_f32_16x16x32_bf16 v[56:59], v[188:191], v[88:91], v[56:59]
	s_add_i32 m0, s81, 28672
	v_mfma_f32_16x16x32_bf16 v[60:63], v[188:191], v[92:95], v[60:63]
	global_load_lds_dwordx4 v243, s[78:79]
	s_waitcnt lgkmcnt(6)
	v_mfma_f32_16x16x32_bf16 v[0:3], v[208:211], v[224:227], v[0:3]
	s_add_u32 s76, s76, 0x80
	s_addc_u32 s77, s77, 0
	s_waitcnt lgkmcnt(5)
	v_mfma_f32_16x16x32_bf16 v[4:7], v[208:211], v[228:231], v[4:7]
	s_waitcnt lgkmcnt(4)
	v_mfma_f32_16x16x32_bf16 v[8:11], v[208:211], v[232:235], v[8:11]
	s_add_u32 s78, s78, 0x80
	s_addc_u32 s79, s79, 0
	s_waitcnt lgkmcnt(3)
	v_mfma_f32_16x16x32_bf16 v[12:15], v[208:211], v[236:239], v[12:15]
	s_waitcnt lgkmcnt(2)
	v_mfma_f32_16x16x32_bf16 v[16:19], v[212:215], v[224:227], v[16:19]
	v_add_u32_e32 v96, 0x60000, v102
	v_mfma_f32_16x16x32_bf16 v[20:23], v[212:215], v[228:231], v[20:23]
	global_load_dwordx4 v[200:203], v96, s[86:87] nt
	v_mfma_f32_16x16x32_bf16 v[24:27], v[212:215], v[232:235], v[24:27]
	v_mfma_f32_16x16x32_bf16 v[28:31], v[212:215], v[236:239], v[28:31]
	s_waitcnt lgkmcnt(1)
	v_mfma_f32_16x16x32_bf16 v[32:35], v[216:219], v[224:227], v[32:35]
	v_mfma_f32_16x16x32_bf16 v[36:39], v[216:219], v[228:231], v[36:39]
	v_mfma_f32_16x16x32_bf16 v[40:43], v[216:219], v[232:235], v[40:43]
	v_mfma_f32_16x16x32_bf16 v[44:47], v[216:219], v[236:239], v[44:47]
	s_waitcnt lgkmcnt(0)
	v_mfma_f32_16x16x32_bf16 v[48:51], v[220:223], v[224:227], v[48:51]
	v_mfma_f32_16x16x32_bf16 v[52:55], v[220:223], v[228:231], v[52:55]
	v_mfma_f32_16x16x32_bf16 v[56:59], v[220:223], v[232:235], v[56:59]
	v_mfma_f32_16x16x32_bf16 v[60:63], v[220:223], v[236:239], v[60:63]
	s_waitcnt vmcnt(1)
	s_barrier
	ds_read_b128 v[176:179], v244 offset:0
	ds_read_b128 v[80:83], v246 offset:0
	ds_read_b128 v[84:87], v246 offset:2048
	ds_read_b128 v[88:91], v246 offset:4096
	ds_read_b128 v[92:95], v246 offset:6144
	ds_read_b128 v[180:183], v244 offset:2048
	ds_read_b128 v[184:187], v244 offset:4096
	ds_read_b128 v[188:191], v244 offset:6144
	s_waitcnt lgkmcnt(6)
	v_mfma_f32_16x16x32_bf16 v[0:3], v[176:179], v[80:83], v[0:3]
	ds_read_b128 v[208:211], v245 offset:0
	s_add_i32 m0, s81, 32768
	s_waitcnt lgkmcnt(6)
	v_mfma_f32_16x16x32_bf16 v[4:7], v[176:179], v[84:87], v[4:7]
	ds_read_b128 v[224:227], v247 offset:0
	global_load_lds_dwordx4 v240, s[76:77]
	s_waitcnt lgkmcnt(6)
	v_mfma_f32_16x16x32_bf16 v[8:11], v[176:179], v[88:91], v[8:11]
	ds_read_b128 v[228:231], v247 offset:2048
	s_add_i32 m0, s81, 36864
	s_waitcnt lgkmcnt(6)
	v_mfma_f32_16x16x32_bf16 v[12:15], v[176:179], v[92:95], v[12:15]
	ds_read_b128 v[232:235], v247 offset:4096
	global_load_lds_dwordx4 v241, s[76:77]
	s_waitcnt lgkmcnt(6)
	v_mfma_f32_16x16x32_bf16 v[16:19], v[180:183], v[80:83], v[16:19]
	ds_read_b128 v[236:239], v247 offset:6144
	s_add_i32 m0, s81, 40960
	v_mfma_f32_16x16x32_bf16 v[20:23], v[180:183], v[84:87], v[20:23]
	ds_read_b128 v[212:215], v245 offset:2048
	global_load_lds_dwordx4 v242, s[76:77]
	v_mfma_f32_16x16x32_bf16 v[24:27], v[180:183], v[88:91], v[24:27]
	ds_read_b128 v[216:219], v245 offset:4096
	s_add_i32 m0, s81, 45056
	v_mfma_f32_16x16x32_bf16 v[28:31], v[180:183], v[92:95], v[28:31]
	ds_read_b128 v[220:223], v245 offset:6144
	global_load_lds_dwordx4 v243, s[76:77]
	s_waitcnt lgkmcnt(9)
	v_mfma_f32_16x16x32_bf16 v[32:35], v[184:187], v[80:83], v[32:35]
	s_add_i32 m0, s81, 49152
	v_mfma_f32_16x16x32_bf16 v[36:39], v[184:187], v[84:87], v[36:39]
	global_load_lds_dwordx4 v240, s[78:79]
	v_mfma_f32_16x16x32_bf16 v[40:43], v[184:187], v[88:91], v[40:43]
	s_add_i32 m0, s81, 53248
	v_mfma_f32_16x16x32_bf16 v[44:47], v[184:187], v[92:95], v[44:47]
	global_load_lds_dwordx4 v241, s[78:79]
	s_waitcnt lgkmcnt(8)
	v_mfma_f32_16x16x32_bf16 v[48:51], v[188:191], v[80:83], v[48:51]
	s_add_i32 m0, s81, 57344
	v_mfma_f32_16x16x32_bf16 v[52:55], v[188:191], v[84:87], v[52:55]
	global_load_lds_dwordx4 v242, s[78:79]
	v_mfma_f32_16x16x32_bf16 v[56:59], v[188:191], v[88:91], v[56:59]
	s_add_i32 m0, s81, 61440
	v_mfma_f32_16x16x32_bf16 v[60:63], v[188:191], v[92:95], v[60:63]
	global_load_lds_dwordx4 v243, s[78:79]
	s_waitcnt lgkmcnt(6)
	v_mfma_f32_16x16x32_bf16 v[0:3], v[208:211], v[224:227], v[0:3]
	s_add_u32 s76, s76, 0x80
	s_addc_u32 s77, s77, 0
	s_waitcnt lgkmcnt(5)
	v_mfma_f32_16x16x32_bf16 v[4:7], v[208:211], v[228:231], v[4:7]
	s_waitcnt lgkmcnt(4)
	v_mfma_f32_16x16x32_bf16 v[8:11], v[208:211], v[232:235], v[8:11]
	s_add_u32 s78, s78, 0x80
	s_addc_u32 s79, s79, 0
	s_waitcnt lgkmcnt(3)
	v_mfma_f32_16x16x32_bf16 v[12:15], v[208:211], v[236:239], v[12:15]
	s_waitcnt lgkmcnt(2)
	v_mfma_f32_16x16x32_bf16 v[16:19], v[212:215], v[224:227], v[16:19]
	v_add_u32_e32 v96, 0x60000, v102
	v_mfma_f32_16x16x32_bf16 v[20:23], v[212:215], v[228:231], v[20:23]
	global_load_dwordx4 v[250:253], v96, s[86:87] offset:16 nt
	v_mfma_f32_16x16x32_bf16 v[24:27], v[212:215], v[232:235], v[24:27]
	v_mfma_f32_16x16x32_bf16 v[28:31], v[212:215], v[236:239], v[28:31]
	s_waitcnt lgkmcnt(1)
	v_mfma_f32_16x16x32_bf16 v[32:35], v[216:219], v[224:227], v[32:35]
	v_mfma_f32_16x16x32_bf16 v[36:39], v[216:219], v[228:231], v[36:39]
	v_mfma_f32_16x16x32_bf16 v[40:43], v[216:219], v[232:235], v[40:43]
	v_mfma_f32_16x16x32_bf16 v[44:47], v[216:219], v[236:239], v[44:47]
	s_waitcnt lgkmcnt(0)
	v_mfma_f32_16x16x32_bf16 v[48:51], v[220:223], v[224:227], v[48:51]
	v_mfma_f32_16x16x32_bf16 v[52:55], v[220:223], v[228:231], v[52:55]
	v_mfma_f32_16x16x32_bf16 v[56:59], v[220:223], v[232:235], v[56:59]
	v_mfma_f32_16x16x32_bf16 v[60:63], v[220:223], v[236:239], v[60:63]
	s_waitcnt vmcnt(1)
	s_barrier
	ds_read_b128 v[176:179], v244 offset:32768
	ds_read_b128 v[80:83], v246 offset:32768
	ds_read_b128 v[84:87], v246 offset:34816
	ds_read_b128 v[88:91], v246 offset:36864
	ds_read_b128 v[92:95], v246 offset:38912
	ds_read_b128 v[180:183], v244 offset:34816
	ds_read_b128 v[184:187], v244 offset:36864
	ds_read_b128 v[188:191], v244 offset:38912
	s_waitcnt lgkmcnt(6)
	v_mfma_f32_16x16x32_bf16 v[0:3], v[176:179], v[80:83], v[0:3]
	ds_read_b128 v[208:211], v245 offset:32768
	s_waitcnt lgkmcnt(6)
	v_mfma_f32_16x16x32_bf16 v[4:7], v[176:179], v[84:87], v[4:7]
	ds_read_b128 v[224:227], v247 offset:32768
	s_waitcnt lgkmcnt(6)
	v_mfma_f32_16x16x32_bf16 v[8:11], v[176:179], v[88:91], v[8:11]
	ds_read_b128 v[228:231], v247 offset:34816
	s_waitcnt lgkmcnt(6)
	v_mfma_f32_16x16x32_bf16 v[12:15], v[176:179], v[92:95], v[12:15]
	ds_read_b128 v[232:235], v247 offset:36864
	s_waitcnt lgkmcnt(6)
	v_mfma_f32_16x16x32_bf16 v[16:19], v[180:183], v[80:83], v[16:19]
	ds_read_b128 v[236:239], v247 offset:38912
	v_mfma_f32_16x16x32_bf16 v[20:23], v[180:183], v[84:87], v[20:23]
	ds_read_b128 v[212:215], v245 offset:34816
	v_mfma_f32_16x16x32_bf16 v[24:27], v[180:183], v[88:91], v[24:27]
	ds_read_b128 v[216:219], v245 offset:36864
	v_mfma_f32_16x16x32_bf16 v[28:31], v[180:183], v[92:95], v[28:31]
	ds_read_b128 v[220:223], v245 offset:38912
	s_waitcnt lgkmcnt(9)
	v_mfma_f32_16x16x32_bf16 v[32:35], v[184:187], v[80:83], v[32:35]
	v_mfma_f32_16x16x32_bf16 v[36:39], v[184:187], v[84:87], v[36:39]
	v_mfma_f32_16x16x32_bf16 v[40:43], v[184:187], v[88:91], v[40:43]
	v_mfma_f32_16x16x32_bf16 v[44:47], v[184:187], v[92:95], v[44:47]
	s_waitcnt lgkmcnt(8)
	v_mfma_f32_16x16x32_bf16 v[48:51], v[188:191], v[80:83], v[48:51]
	v_mfma_f32_16x16x32_bf16 v[52:55], v[188:191], v[84:87], v[52:55]
	v_mfma_f32_16x16x32_bf16 v[56:59], v[188:191], v[88:91], v[56:59]
	v_mfma_f32_16x16x32_bf16 v[60:63], v[188:191], v[92:95], v[60:63]
	s_waitcnt lgkmcnt(6)
	v_mfma_f32_16x16x32_bf16 v[0:3], v[208:211], v[224:227], v[0:3]
	s_waitcnt lgkmcnt(5)
	v_mfma_f32_16x16x32_bf16 v[4:7], v[208:211], v[228:231], v[4:7]
	s_waitcnt lgkmcnt(4)
	v_mfma_f32_16x16x32_bf16 v[8:11], v[208:211], v[232:235], v[8:11]
	s_waitcnt lgkmcnt(3)
	v_mfma_f32_16x16x32_bf16 v[12:15], v[208:211], v[236:239], v[12:15]
	s_waitcnt lgkmcnt(2)
	v_mfma_f32_16x16x32_bf16 v[16:19], v[212:215], v[224:227], v[16:19]
	v_mfma_f32_16x16x32_bf16 v[20:23], v[212:215], v[228:231], v[20:23]
	v_mfma_f32_16x16x32_bf16 v[24:27], v[212:215], v[232:235], v[24:27]
	v_mfma_f32_16x16x32_bf16 v[28:31], v[212:215], v[236:239], v[28:31]
	s_waitcnt lgkmcnt(1)
	v_mfma_f32_16x16x32_bf16 v[32:35], v[216:219], v[224:227], v[32:35]
	v_mfma_f32_16x16x32_bf16 v[36:39], v[216:219], v[228:231], v[36:39]
	v_mfma_f32_16x16x32_bf16 v[40:43], v[216:219], v[232:235], v[40:43]
	v_mfma_f32_16x16x32_bf16 v[44:47], v[216:219], v[236:239], v[44:47]
	s_waitcnt lgkmcnt(0)
	v_mfma_f32_16x16x32_bf16 v[48:51], v[220:223], v[224:227], v[48:51]
	v_mfma_f32_16x16x32_bf16 v[52:55], v[220:223], v[228:231], v[52:55]
	v_mfma_f32_16x16x32_bf16 v[56:59], v[220:223], v[232:235], v[56:59]
	v_mfma_f32_16x16x32_bf16 v[60:63], v[220:223], v[236:239], v[60:63]
	s_branch .Lot_stage
.Lot_main_l1:
	s_waitcnt vmcnt(0)
	s_barrier
	ds_read_b128 v[176:179], v244 offset:0
	ds_read_b128 v[80:83], v246 offset:0
	ds_read_b128 v[84:87], v246 offset:2048
	ds_read_b128 v[88:91], v246 offset:4096
	ds_read_b128 v[92:95], v246 offset:6144
	ds_read_b128 v[180:183], v244 offset:2048
	ds_read_b128 v[184:187], v244 offset:4096
	ds_read_b128 v[188:191], v244 offset:6144
	s_waitcnt lgkmcnt(6)
	v_mfma_f32_16x16x32_bf16 v[0:3], v[176:179], v[80:83], v[0:3]
	ds_read_b128 v[208:211], v245 offset:0
	s_add_i32 m0, s81, 32768
	s_waitcnt lgkmcnt(6)
	v_mfma_f32_16x16x32_bf16 v[4:7], v[176:179], v[84:87], v[4:7]
	ds_read_b128 v[224:227], v247 offset:0
	global_load_lds_dwordx4 v240, s[76:77]
	s_waitcnt lgkmcnt(6)
	v_mfma_f32_16x16x32_bf16 v[8:11], v[176:179], v[88:91], v[8:11]
	ds_read_b128 v[228:231], v247 offset:2048
	s_add_i32 m0, s81, 36864
	s_waitcnt lgkmcnt(6)
	v_mfma_f32_16x16x32_bf16 v[12:15], v[176:179], v[92:95], v[12:15]
	ds_read_b128 v[232:235], v247 offset:4096
	global_load_lds_dwordx4 v241, s[76:77]
	s_waitcnt lgkmcnt(6)
	v_mfma_f32_16x16x32_bf16 v[16:19], v[180:183], v[80:83], v[16:19]
	ds_read_b128 v[236:239], v247 offset:6144
	s_add_i32 m0, s81, 40960
	v_mfma_f32_16x16x32_bf16 v[20:23], v[180:183], v[84:87], v[20:23]
	ds_read_b128 v[212:215], v245 offset:2048
	global_load_lds_dwordx4 v242, s[76:77]
	v_mfma_f32_16x16x32_bf16 v[24:27], v[180:183], v[88:91], v[24:27]
	ds_read_b128 v[216:219], v245 offset:4096
	s_add_i32 m0, s81, 45056
	v_mfma_f32_16x16x32_bf16 v[28:31], v[180:183], v[92:95], v[28:31]
	ds_read_b128 v[220:223], v245 offset:6144
	global_load_lds_dwordx4 v243, s[76:77]
	s_waitcnt lgkmcnt(9)
	v_mfma_f32_16x16x32_bf16 v[32:35], v[184:187], v[80:83], v[32:35]
	s_add_i32 m0, s81, 49152
	v_mfma_f32_16x16x32_bf16 v[36:39], v[184:187], v[84:87], v[36:39]
	global_load_lds_dwordx4 v240, s[78:79]
	v_mfma_f32_16x16x32_bf16 v[40:43], v[184:187], v[88:91], v[40:43]
	s_add_i32 m0, s81, 53248
	v_mfma_f32_16x16x32_bf16 v[44:47], v[184:187], v[92:95], v[44:47]
	global_load_lds_dwordx4 v241, s[78:79]
	s_waitcnt lgkmcnt(8)
	v_mfma_f32_16x16x32_bf16 v[48:51], v[188:191], v[80:83], v[48:51]
	s_add_i32 m0, s81, 57344
	v_mfma_f32_16x16x32_bf16 v[52:55], v[188:191], v[84:87], v[52:55]
	global_load_lds_dwordx4 v242, s[78:79]
	v_mfma_f32_16x16x32_bf16 v[56:59], v[188:191], v[88:91], v[56:59]
	s_add_i32 m0, s81, 61440
	v_mfma_f32_16x16x32_bf16 v[60:63], v[188:191], v[92:95], v[60:63]
	global_load_lds_dwordx4 v243, s[78:79]
	s_waitcnt lgkmcnt(6)
	v_mfma_f32_16x16x32_bf16 v[0:3], v[208:211], v[224:227], v[0:3]
	s_add_u32 s76, s76, 0x80
	s_addc_u32 s77, s77, 0
	s_waitcnt lgkmcnt(5)
	v_mfma_f32_16x16x32_bf16 v[4:7], v[208:211], v[228:231], v[4:7]
	s_waitcnt lgkmcnt(4)
	v_mfma_f32_16x16x32_bf16 v[8:11], v[208:211], v[232:235], v[8:11]
	s_add_u32 s78, s78, 0x80
	s_addc_u32 s79, s79, 0
	s_waitcnt lgkmcnt(3)
	v_mfma_f32_16x16x32_bf16 v[12:15], v[208:211], v[236:239], v[12:15]
	s_waitcnt lgkmcnt(2)
	v_mfma_f32_16x16x32_bf16 v[16:19], v[212:215], v[224:227], v[16:19]
	v_mfma_f32_16x16x32_bf16 v[20:23], v[212:215], v[228:231], v[20:23]
	v_mfma_f32_16x16x32_bf16 v[24:27], v[212:215], v[232:235], v[24:27]
	v_mfma_f32_16x16x32_bf16 v[28:31], v[212:215], v[236:239], v[28:31]
	s_waitcnt lgkmcnt(1)
	v_mfma_f32_16x16x32_bf16 v[32:35], v[216:219], v[224:227], v[32:35]
	v_mfma_f32_16x16x32_bf16 v[36:39], v[216:219], v[228:231], v[36:39]
	v_mfma_f32_16x16x32_bf16 v[40:43], v[216:219], v[232:235], v[40:43]
	v_mfma_f32_16x16x32_bf16 v[44:47], v[216:219], v[236:239], v[44:47]
	s_waitcnt lgkmcnt(0)
	v_mfma_f32_16x16x32_bf16 v[48:51], v[220:223], v[224:227], v[48:51]
	v_mfma_f32_16x16x32_bf16 v[52:55], v[220:223], v[228:231], v[52:55]
	v_mfma_f32_16x16x32_bf16 v[56:59], v[220:223], v[232:235], v[56:59]
	v_mfma_f32_16x16x32_bf16 v[60:63], v[220:223], v[236:239], v[60:63]
	s_waitcnt vmcnt(0)
	s_barrier
	ds_read_b128 v[176:179], v244 offset:32768
	ds_read_b128 v[80:83], v246 offset:32768
	ds_read_b128 v[84:87], v246 offset:34816
	ds_read_b128 v[88:91], v246 offset:36864
	ds_read_b128 v[92:95], v246 offset:38912
	ds_read_b128 v[180:183], v244 offset:34816
	ds_read_b128 v[184:187], v244 offset:36864
	ds_read_b128 v[188:191], v244 offset:38912
	s_waitcnt lgkmcnt(6)
	v_mfma_f32_16x16x32_bf16 v[0:3], v[176:179], v[80:83], v[0:3]
	ds_read_b128 v[208:211], v245 offset:32768
	s_add_i32 m0, s81, 0
	s_waitcnt lgkmcnt(6)
	v_mfma_f32_16x16x32_bf16 v[4:7], v[176:179], v[84:87], v[4:7]
	ds_read_b128 v[224:227], v247 offset:32768
	global_load_lds_dwordx4 v240, s[76:77]
	s_waitcnt lgkmcnt(6)
	v_mfma_f32_16x16x32_bf16 v[8:11], v[176:179], v[88:91], v[8:11]
	ds_read_b128 v[228:231], v247 offset:34816
	s_add_i32 m0, s81, 4096
	s_waitcnt lgkmcnt(6)
	v_mfma_f32_16x16x32_bf16 v[12:15], v[176:179], v[92:95], v[12:15]
	ds_read_b128 v[232:235], v247 offset:36864
	global_load_lds_dwordx4 v241, s[76:77]
	s_waitcnt lgkmcnt(6)
	v_mfma_f32_16x16x32_bf16 v[16:19], v[180:183], v[80:83], v[16:19]
	ds_read_b128 v[236:239], v247 offset:38912
	s_add_i32 m0, s81, 8192
	v_mfma_f32_16x16x32_bf16 v[20:23], v[180:183], v[84:87], v[20:23]
	ds_read_b128 v[212:215], v245 offset:34816
	global_load_lds_dwordx4 v242, s[76:77]
	v_mfma_f32_16x16x32_bf16 v[24:27], v[180:183], v[88:91], v[24:27]
	ds_read_b128 v[216:219], v245 offset:36864
	s_add_i32 m0, s81, 12288
	v_mfma_f32_16x16x32_bf16 v[28:31], v[180:183], v[92:95], v[28:31]
	ds_read_b128 v[220:223], v245 offset:38912
	global_load_lds_dwordx4 v243, s[76:77]
	s_waitcnt lgkmcnt(9)
	v_mfma_f32_16x16x32_bf16 v[32:35], v[184:187], v[80:83], v[32:35]
	s_add_i32 m0, s81, 16384
	v_mfma_f32_16x16x32_bf16 v[36:39], v[184:187], v[84:87], v[36:39]
	global_load_lds_dwordx4 v240, s[78:79]
	v_mfma_f32_16x16x32_bf16 v[40:43], v[184:187], v[88:91], v[40:43]
	s_add_i32 m0, s81, 20480
	v_mfma_f32_16x16x32_bf16 v[44:47], v[184:187], v[92:95], v[44:47]
	global_load_lds_dwordx4 v241, s[78:79]
	s_waitcnt lgkmcnt(8)
	v_mfma_f32_16x16x32_bf16 v[48:51], v[188:191], v[80:83], v[48:51]
	s_add_i32 m0, s81, 24576
	v_mfma_f32_16x16x32_bf16 v[52:55], v[188:191], v[84:87], v[52:55]
	global_load_lds_dwordx4 v242, s[78:79]
	v_mfma_f32_16x16x32_bf16 v[56:59], v[188:191], v[88:91], v[56:59]
	s_add_i32 m0, s81, 28672
	v_mfma_f32_16x16x32_bf16 v[60:63], v[188:191], v[92:95], v[60:63]
	global_load_lds_dwordx4 v243, s[78:79]
	s_waitcnt lgkmcnt(6)
	v_mfma_f32_16x16x32_bf16 v[0:3], v[208:211], v[224:227], v[0:3]
	s_add_u32 s76, s76, 0x80
	s_addc_u32 s77, s77, 0
	s_waitcnt lgkmcnt(5)
	v_mfma_f32_16x16x32_bf16 v[4:7], v[208:211], v[228:231], v[4:7]
	s_waitcnt lgkmcnt(4)
	v_mfma_f32_16x16x32_bf16 v[8:11], v[208:211], v[232:235], v[8:11]
	s_add_u32 s78, s78, 0x80
	s_addc_u32 s79, s79, 0
	s_waitcnt lgkmcnt(3)
	v_mfma_f32_16x16x32_bf16 v[12:15], v[208:211], v[236:239], v[12:15]
	s_waitcnt lgkmcnt(2)
	v_mfma_f32_16x16x32_bf16 v[16:19], v[212:215], v[224:227], v[16:19]
	v_mfma_f32_16x16x32_bf16 v[20:23], v[212:215], v[228:231], v[20:23]
	v_mfma_f32_16x16x32_bf16 v[24:27], v[212:215], v[232:235], v[24:27]
	v_mfma_f32_16x16x32_bf16 v[28:31], v[212:215], v[236:239], v[28:31]
	s_waitcnt lgkmcnt(1)
	v_mfma_f32_16x16x32_bf16 v[32:35], v[216:219], v[224:227], v[32:35]
	v_mfma_f32_16x16x32_bf16 v[36:39], v[216:219], v[228:231], v[36:39]
	v_mfma_f32_16x16x32_bf16 v[40:43], v[216:219], v[232:235], v[40:43]
	v_mfma_f32_16x16x32_bf16 v[44:47], v[216:219], v[236:239], v[44:47]
	s_waitcnt lgkmcnt(0)
	v_mfma_f32_16x16x32_bf16 v[48:51], v[220:223], v[224:227], v[48:51]
	v_mfma_f32_16x16x32_bf16 v[52:55], v[220:223], v[228:231], v[52:55]
	v_mfma_f32_16x16x32_bf16 v[56:59], v[220:223], v[232:235], v[56:59]
	v_mfma_f32_16x16x32_bf16 v[60:63], v[220:223], v[236:239], v[60:63]
	s_waitcnt vmcnt(0)
	s_barrier
	ds_read_b128 v[176:179], v244 offset:0
	ds_read_b128 v[80:83], v246 offset:0
	ds_read_b128 v[84:87], v246 offset:2048
	ds_read_b128 v[88:91], v246 offset:4096
	ds_read_b128 v[92:95], v246 offset:6144
	ds_read_b128 v[180:183], v244 offset:2048
	ds_read_b128 v[184:187], v244 offset:4096
	ds_read_b128 v[188:191], v244 offset:6144
	s_waitcnt lgkmcnt(6)
	v_mfma_f32_16x16x32_bf16 v[0:3], v[176:179], v[80:83], v[0:3]
	ds_read_b128 v[208:211], v245 offset:0
	s_add_i32 m0, s81, 32768
	s_waitcnt lgkmcnt(6)
	v_mfma_f32_16x16x32_bf16 v[4:7], v[176:179], v[84:87], v[4:7]
	ds_read_b128 v[224:227], v247 offset:0
	global_load_lds_dwordx4 v240, s[76:77]
	s_waitcnt lgkmcnt(6)
	v_mfma_f32_16x16x32_bf16 v[8:11], v[176:179], v[88:91], v[8:11]
	ds_read_b128 v[228:231], v247 offset:2048
	s_add_i32 m0, s81, 36864
	s_waitcnt lgkmcnt(6)
	v_mfma_f32_16x16x32_bf16 v[12:15], v[176:179], v[92:95], v[12:15]
	ds_read_b128 v[232:235], v247 offset:4096
	global_load_lds_dwordx4 v241, s[76:77]
	s_waitcnt lgkmcnt(6)
	v_mfma_f32_16x16x32_bf16 v[16:19], v[180:183], v[80:83], v[16:19]
	ds_read_b128 v[236:239], v247 offset:6144
	s_add_i32 m0, s81, 40960
	v_mfma_f32_16x16x32_bf16 v[20:23], v[180:183], v[84:87], v[20:23]
	ds_read_b128 v[212:215], v245 offset:2048
	global_load_lds_dwordx4 v242, s[76:77]
	v_mfma_f32_16x16x32_bf16 v[24:27], v[180:183], v[88:91], v[24:27]
	ds_read_b128 v[216:219], v245 offset:4096
	s_add_i32 m0, s81, 45056
	v_mfma_f32_16x16x32_bf16 v[28:31], v[180:183], v[92:95], v[28:31]
	ds_read_b128 v[220:223], v245 offset:6144
	global_load_lds_dwordx4 v243, s[76:77]
	s_waitcnt lgkmcnt(9)
	v_mfma_f32_16x16x32_bf16 v[32:35], v[184:187], v[80:83], v[32:35]
	s_add_i32 m0, s81, 49152
	v_mfma_f32_16x16x32_bf16 v[36:39], v[184:187], v[84:87], v[36:39]
	global_load_lds_dwordx4 v240, s[78:79]
	v_mfma_f32_16x16x32_bf16 v[40:43], v[184:187], v[88:91], v[40:43]
	s_add_i32 m0, s81, 53248
	v_mfma_f32_16x16x32_bf16 v[44:47], v[184:187], v[92:95], v[44:47]
	global_load_lds_dwordx4 v241, s[78:79]
	s_waitcnt lgkmcnt(8)
	v_mfma_f32_16x16x32_bf16 v[48:51], v[188:191], v[80:83], v[48:51]
	s_add_i32 m0, s81, 57344
	v_mfma_f32_16x16x32_bf16 v[52:55], v[188:191], v[84:87], v[52:55]
	global_load_lds_dwordx4 v242, s[78:79]
	v_mfma_f32_16x16x32_bf16 v[56:59], v[188:191], v[88:91], v[56:59]
	s_add_i32 m0, s81, 61440
	v_mfma_f32_16x16x32_bf16 v[60:63], v[188:191], v[92:95], v[60:63]
	global_load_lds_dwordx4 v243, s[78:79]
	s_waitcnt lgkmcnt(6)
	v_mfma_f32_16x16x32_bf16 v[0:3], v[208:211], v[224:227], v[0:3]
	s_add_u32 s76, s76, 0x80
	s_addc_u32 s77, s77, 0
	s_waitcnt lgkmcnt(5)
	v_mfma_f32_16x16x32_bf16 v[4:7], v[208:211], v[228:231], v[4:7]
	s_waitcnt lgkmcnt(4)
	v_mfma_f32_16x16x32_bf16 v[8:11], v[208:211], v[232:235], v[8:11]
	s_add_u32 s78, s78, 0x80
	s_addc_u32 s79, s79, 0
	s_waitcnt lgkmcnt(3)
	v_mfma_f32_16x16x32_bf16 v[12:15], v[208:211], v[236:239], v[12:15]
	s_waitcnt lgkmcnt(2)
	v_mfma_f32_16x16x32_bf16 v[16:19], v[212:215], v[224:227], v[16:19]
	v_mfma_f32_16x16x32_bf16 v[20:23], v[212:215], v[228:231], v[20:23]
	v_mfma_f32_16x16x32_bf16 v[24:27], v[212:215], v[232:235], v[24:27]
	v_mfma_f32_16x16x32_bf16 v[28:31], v[212:215], v[236:239], v[28:31]
	s_waitcnt lgkmcnt(1)
	v_mfma_f32_16x16x32_bf16 v[32:35], v[216:219], v[224:227], v[32:35]
	v_mfma_f32_16x16x32_bf16 v[36:39], v[216:219], v[228:231], v[36:39]
	v_mfma_f32_16x16x32_bf16 v[40:43], v[216:219], v[232:235], v[40:43]
	v_mfma_f32_16x16x32_bf16 v[44:47], v[216:219], v[236:239], v[44:47]
	s_waitcnt lgkmcnt(0)
	v_mfma_f32_16x16x32_bf16 v[48:51], v[220:223], v[224:227], v[48:51]
	v_mfma_f32_16x16x32_bf16 v[52:55], v[220:223], v[228:231], v[52:55]
	v_mfma_f32_16x16x32_bf16 v[56:59], v[220:223], v[232:235], v[56:59]
	v_mfma_f32_16x16x32_bf16 v[60:63], v[220:223], v[236:239], v[60:63]
	s_waitcnt vmcnt(0)
	s_barrier
	ds_read_b128 v[176:179], v244 offset:32768
	ds_read_b128 v[80:83], v246 offset:32768
	ds_read_b128 v[84:87], v246 offset:34816
	ds_read_b128 v[88:91], v246 offset:36864
	ds_read_b128 v[92:95], v246 offset:38912
	ds_read_b128 v[180:183], v244 offset:34816
	ds_read_b128 v[184:187], v244 offset:36864
	ds_read_b128 v[188:191], v244 offset:38912
	s_waitcnt lgkmcnt(6)
	v_mfma_f32_16x16x32_bf16 v[0:3], v[176:179], v[80:83], v[0:3]
	ds_read_b128 v[208:211], v245 offset:32768
	s_add_i32 m0, s81, 0
	s_waitcnt lgkmcnt(6)
	v_mfma_f32_16x16x32_bf16 v[4:7], v[176:179], v[84:87], v[4:7]
	ds_read_b128 v[224:227], v247 offset:32768
	global_load_lds_dwordx4 v240, s[76:77]
	s_waitcnt lgkmcnt(6)
	v_mfma_f32_16x16x32_bf16 v[8:11], v[176:179], v[88:91], v[8:11]
	ds_read_b128 v[228:231], v247 offset:34816
	s_add_i32 m0, s81, 4096
	s_waitcnt lgkmcnt(6)
	v_mfma_f32_16x16x32_bf16 v[12:15], v[176:179], v[92:95], v[12:15]
	ds_read_b128 v[232:235], v247 offset:36864
	global_load_lds_dwordx4 v241, s[76:77]
	s_waitcnt lgkmcnt(6)
	v_mfma_f32_16x16x32_bf16 v[16:19], v[180:183], v[80:83], v[16:19]
	ds_read_b128 v[236:239], v247 offset:38912
	s_add_i32 m0, s81, 8192
	v_mfma_f32_16x16x32_bf16 v[20:23], v[180:183], v[84:87], v[20:23]
	ds_read_b128 v[212:215], v245 offset:34816
	global_load_lds_dwordx4 v242, s[76:77]
	v_mfma_f32_16x16x32_bf16 v[24:27], v[180:183], v[88:91], v[24:27]
	ds_read_b128 v[216:219], v245 offset:36864
	s_add_i32 m0, s81, 12288
	v_mfma_f32_16x16x32_bf16 v[28:31], v[180:183], v[92:95], v[28:31]
	ds_read_b128 v[220:223], v245 offset:38912
	global_load_lds_dwordx4 v243, s[76:77]
	s_waitcnt lgkmcnt(9)
	v_mfma_f32_16x16x32_bf16 v[32:35], v[184:187], v[80:83], v[32:35]
	s_add_i32 m0, s81, 16384
	v_mfma_f32_16x16x32_bf16 v[36:39], v[184:187], v[84:87], v[36:39]
	global_load_lds_dwordx4 v240, s[78:79]
	v_mfma_f32_16x16x32_bf16 v[40:43], v[184:187], v[88:91], v[40:43]
	s_add_i32 m0, s81, 20480
	v_mfma_f32_16x16x32_bf16 v[44:47], v[184:187], v[92:95], v[44:47]
	global_load_lds_dwordx4 v241, s[78:79]
	s_waitcnt lgkmcnt(8)
	v_mfma_f32_16x16x32_bf16 v[48:51], v[188:191], v[80:83], v[48:51]
	s_add_i32 m0, s81, 24576
	v_mfma_f32_16x16x32_bf16 v[52:55], v[188:191], v[84:87], v[52:55]
	global_load_lds_dwordx4 v242, s[78:79]
	v_mfma_f32_16x16x32_bf16 v[56:59], v[188:191], v[88:91], v[56:59]
	s_add_i32 m0, s81, 28672
	v_mfma_f32_16x16x32_bf16 v[60:63], v[188:191], v[92:95], v[60:63]
	global_load_lds_dwordx4 v243, s[78:79]
	s_waitcnt lgkmcnt(6)
	v_mfma_f32_16x16x32_bf16 v[0:3], v[208:211], v[224:227], v[0:3]
	s_add_u32 s76, s76, 0x80
	s_addc_u32 s77, s77, 0
	s_waitcnt lgkmcnt(5)
	v_mfma_f32_16x16x32_bf16 v[4:7], v[208:211], v[228:231], v[4:7]
	s_waitcnt lgkmcnt(4)
	v_mfma_f32_16x16x32_bf16 v[8:11], v[208:211], v[232:235], v[8:11]
	s_add_u32 s78, s78, 0x80
	s_addc_u32 s79, s79, 0
	s_waitcnt lgkmcnt(3)
	v_mfma_f32_16x16x32_bf16 v[12:15], v[208:211], v[236:239], v[12:15]
	s_waitcnt lgkmcnt(2)
	v_mfma_f32_16x16x32_bf16 v[16:19], v[212:215], v[224:227], v[16:19]
	v_mfma_f32_16x16x32_bf16 v[20:23], v[212:215], v[228:231], v[20:23]
	v_mfma_f32_16x16x32_bf16 v[24:27], v[212:215], v[232:235], v[24:27]
	v_mfma_f32_16x16x32_bf16 v[28:31], v[212:215], v[236:239], v[28:31]
	s_waitcnt lgkmcnt(1)
	v_mfma_f32_16x16x32_bf16 v[32:35], v[216:219], v[224:227], v[32:35]
	v_mfma_f32_16x16x32_bf16 v[36:39], v[216:219], v[228:231], v[36:39]
	v_mfma_f32_16x16x32_bf16 v[40:43], v[216:219], v[232:235], v[40:43]
	v_mfma_f32_16x16x32_bf16 v[44:47], v[216:219], v[236:239], v[44:47]
	s_waitcnt lgkmcnt(0)
	v_mfma_f32_16x16x32_bf16 v[48:51], v[220:223], v[224:227], v[48:51]
	v_mfma_f32_16x16x32_bf16 v[52:55], v[220:223], v[228:231], v[52:55]
	v_mfma_f32_16x16x32_bf16 v[56:59], v[220:223], v[232:235], v[56:59]
	v_mfma_f32_16x16x32_bf16 v[60:63], v[220:223], v[236:239], v[60:63]
	s_waitcnt vmcnt(0)
	s_barrier
	ds_read_b128 v[176:179], v244 offset:0
	ds_read_b128 v[80:83], v246 offset:0
	ds_read_b128 v[84:87], v246 offset:2048
	ds_read_b128 v[88:91], v246 offset:4096
	ds_read_b128 v[92:95], v246 offset:6144
	ds_read_b128 v[180:183], v244 offset:2048
	ds_read_b128 v[184:187], v244 offset:4096
	ds_read_b128 v[188:191], v244 offset:6144
	s_waitcnt lgkmcnt(6)
	v_mfma_f32_16x16x32_bf16 v[0:3], v[176:179], v[80:83], v[0:3]
	ds_read_b128 v[208:211], v245 offset:0
	s_add_i32 m0, s81, 32768
	s_waitcnt lgkmcnt(6)
	v_mfma_f32_16x16x32_bf16 v[4:7], v[176:179], v[84:87], v[4:7]
	ds_read_b128 v[224:227], v247 offset:0
	global_load_lds_dwordx4 v240, s[76:77]
	s_waitcnt lgkmcnt(6)
	v_mfma_f32_16x16x32_bf16 v[8:11], v[176:179], v[88:91], v[8:11]
	ds_read_b128 v[228:231], v247 offset:2048
	s_add_i32 m0, s81, 36864
	s_waitcnt lgkmcnt(6)
	v_mfma_f32_16x16x32_bf16 v[12:15], v[176:179], v[92:95], v[12:15]
	ds_read_b128 v[232:235], v247 offset:4096
	global_load_lds_dwordx4 v241, s[76:77]
	s_waitcnt lgkmcnt(6)
	v_mfma_f32_16x16x32_bf16 v[16:19], v[180:183], v[80:83], v[16:19]
	ds_read_b128 v[236:239], v247 offset:6144
	s_add_i32 m0, s81, 40960
	v_mfma_f32_16x16x32_bf16 v[20:23], v[180:183], v[84:87], v[20:23]
	ds_read_b128 v[212:215], v245 offset:2048
	global_load_lds_dwordx4 v242, s[76:77]
	v_mfma_f32_16x16x32_bf16 v[24:27], v[180:183], v[88:91], v[24:27]
	ds_read_b128 v[216:219], v245 offset:4096
	s_add_i32 m0, s81, 45056
	v_mfma_f32_16x16x32_bf16 v[28:31], v[180:183], v[92:95], v[28:31]
	ds_read_b128 v[220:223], v245 offset:6144
	global_load_lds_dwordx4 v243, s[76:77]
	s_waitcnt lgkmcnt(9)
	v_mfma_f32_16x16x32_bf16 v[32:35], v[184:187], v[80:83], v[32:35]
	s_add_i32 m0, s81, 49152
	v_mfma_f32_16x16x32_bf16 v[36:39], v[184:187], v[84:87], v[36:39]
	global_load_lds_dwordx4 v240, s[78:79]
	v_mfma_f32_16x16x32_bf16 v[40:43], v[184:187], v[88:91], v[40:43]
	s_add_i32 m0, s81, 53248
	v_mfma_f32_16x16x32_bf16 v[44:47], v[184:187], v[92:95], v[44:47]
	global_load_lds_dwordx4 v241, s[78:79]
	s_waitcnt lgkmcnt(8)
	v_mfma_f32_16x16x32_bf16 v[48:51], v[188:191], v[80:83], v[48:51]
	s_add_i32 m0, s81, 57344
	v_mfma_f32_16x16x32_bf16 v[52:55], v[188:191], v[84:87], v[52:55]
	global_load_lds_dwordx4 v242, s[78:79]
	v_mfma_f32_16x16x32_bf16 v[56:59], v[188:191], v[88:91], v[56:59]
	s_add_i32 m0, s81, 61440
	v_mfma_f32_16x16x32_bf16 v[60:63], v[188:191], v[92:95], v[60:63]
	global_load_lds_dwordx4 v243, s[78:79]
	s_waitcnt lgkmcnt(6)
	v_mfma_f32_16x16x32_bf16 v[0:3], v[208:211], v[224:227], v[0:3]
	s_add_u32 s76, s76, 0x80
	s_addc_u32 s77, s77, 0
	s_waitcnt lgkmcnt(5)
	v_mfma_f32_16x16x32_bf16 v[4:7], v[208:211], v[228:231], v[4:7]
	s_waitcnt lgkmcnt(4)
	v_mfma_f32_16x16x32_bf16 v[8:11], v[208:211], v[232:235], v[8:11]
	s_add_u32 s78, s78, 0x80
	s_addc_u32 s79, s79, 0
	s_waitcnt lgkmcnt(3)
	v_mfma_f32_16x16x32_bf16 v[12:15], v[208:211], v[236:239], v[12:15]
	s_waitcnt lgkmcnt(2)
	v_mfma_f32_16x16x32_bf16 v[16:19], v[212:215], v[224:227], v[16:19]
	v_mfma_f32_16x16x32_bf16 v[20:23], v[212:215], v[228:231], v[20:23]
	v_mfma_f32_16x16x32_bf16 v[24:27], v[212:215], v[232:235], v[24:27]
	v_mfma_f32_16x16x32_bf16 v[28:31], v[212:215], v[236:239], v[28:31]
	s_waitcnt lgkmcnt(1)
	v_mfma_f32_16x16x32_bf16 v[32:35], v[216:219], v[224:227], v[32:35]
	v_mfma_f32_16x16x32_bf16 v[36:39], v[216:219], v[228:231], v[36:39]
	v_mfma_f32_16x16x32_bf16 v[40:43], v[216:219], v[232:235], v[40:43]
	v_mfma_f32_16x16x32_bf16 v[44:47], v[216:219], v[236:239], v[44:47]
	s_waitcnt lgkmcnt(0)
	v_mfma_f32_16x16x32_bf16 v[48:51], v[220:223], v[224:227], v[48:51]
	v_mfma_f32_16x16x32_bf16 v[52:55], v[220:223], v[228:231], v[52:55]
	v_mfma_f32_16x16x32_bf16 v[56:59], v[220:223], v[232:235], v[56:59]
	v_mfma_f32_16x16x32_bf16 v[60:63], v[220:223], v[236:239], v[60:63]
	s_waitcnt vmcnt(0)
	s_barrier
	ds_read_b128 v[176:179], v244 offset:32768
	ds_read_b128 v[80:83], v246 offset:32768
	ds_read_b128 v[84:87], v246 offset:34816
	ds_read_b128 v[88:91], v246 offset:36864
	ds_read_b128 v[92:95], v246 offset:38912
	ds_read_b128 v[180:183], v244 offset:34816
	ds_read_b128 v[184:187], v244 offset:36864
	ds_read_b128 v[188:191], v244 offset:38912
	s_waitcnt lgkmcnt(6)
	v_mfma_f32_16x16x32_bf16 v[0:3], v[176:179], v[80:83], v[0:3]
	ds_read_b128 v[208:211], v245 offset:32768
	s_add_i32 m0, s81, 0
	s_waitcnt lgkmcnt(6)
	v_mfma_f32_16x16x32_bf16 v[4:7], v[176:179], v[84:87], v[4:7]
	ds_read_b128 v[224:227], v247 offset:32768
	global_load_lds_dwordx4 v240, s[76:77]
	s_waitcnt lgkmcnt(6)
	v_mfma_f32_16x16x32_bf16 v[8:11], v[176:179], v[88:91], v[8:11]
	ds_read_b128 v[228:231], v247 offset:34816
	s_add_i32 m0, s81, 4096
	s_waitcnt lgkmcnt(6)
	v_mfma_f32_16x16x32_bf16 v[12:15], v[176:179], v[92:95], v[12:15]
	ds_read_b128 v[232:235], v247 offset:36864
	global_load_lds_dwordx4 v241, s[76:77]
	s_waitcnt lgkmcnt(6)
	v_mfma_f32_16x16x32_bf16 v[16:19], v[180:183], v[80:83], v[16:19]
	ds_read_b128 v[236:239], v247 offset:38912
	s_add_i32 m0, s81, 8192
	v_mfma_f32_16x16x32_bf16 v[20:23], v[180:183], v[84:87], v[20:23]
	ds_read_b128 v[212:215], v245 offset:34816
	global_load_lds_dwordx4 v242, s[76:77]
	v_mfma_f32_16x16x32_bf16 v[24:27], v[180:183], v[88:91], v[24:27]
	ds_read_b128 v[216:219], v245 offset:36864
	s_add_i32 m0, s81, 12288
	v_mfma_f32_16x16x32_bf16 v[28:31], v[180:183], v[92:95], v[28:31]
	ds_read_b128 v[220:223], v245 offset:38912
	global_load_lds_dwordx4 v243, s[76:77]
	s_waitcnt lgkmcnt(9)
	v_mfma_f32_16x16x32_bf16 v[32:35], v[184:187], v[80:83], v[32:35]
	s_add_i32 m0, s81, 16384
	v_mfma_f32_16x16x32_bf16 v[36:39], v[184:187], v[84:87], v[36:39]
	global_load_lds_dwordx4 v240, s[78:79]
	v_mfma_f32_16x16x32_bf16 v[40:43], v[184:187], v[88:91], v[40:43]
	s_add_i32 m0, s81, 20480
	v_mfma_f32_16x16x32_bf16 v[44:47], v[184:187], v[92:95], v[44:47]
	global_load_lds_dwordx4 v241, s[78:79]
	s_waitcnt lgkmcnt(8)
	v_mfma_f32_16x16x32_bf16 v[48:51], v[188:191], v[80:83], v[48:51]
	s_add_i32 m0, s81, 24576
	v_mfma_f32_16x16x32_bf16 v[52:55], v[188:191], v[84:87], v[52:55]
	global_load_lds_dwordx4 v242, s[78:79]
	v_mfma_f32_16x16x32_bf16 v[56:59], v[188:191], v[88:91], v[56:59]
	s_add_i32 m0, s81, 28672
	v_mfma_f32_16x16x32_bf16 v[60:63], v[188:191], v[92:95], v[60:63]
	global_load_lds_dwordx4 v243, s[78:79]
	s_waitcnt lgkmcnt(6)
	v_mfma_f32_16x16x32_bf16 v[0:3], v[208:211], v[224:227], v[0:3]
	s_add_u32 s76, s76, 0x80
	s_addc_u32 s77, s77, 0
	s_waitcnt lgkmcnt(5)
	v_mfma_f32_16x16x32_bf16 v[4:7], v[208:211], v[228:231], v[4:7]
	s_waitcnt lgkmcnt(4)
	v_mfma_f32_16x16x32_bf16 v[8:11], v[208:211], v[232:235], v[8:11]
	s_add_u32 s78, s78, 0x80
	s_addc_u32 s79, s79, 0
	s_waitcnt lgkmcnt(3)
	v_mfma_f32_16x16x32_bf16 v[12:15], v[208:211], v[236:239], v[12:15]
	s_waitcnt lgkmcnt(2)
	v_mfma_f32_16x16x32_bf16 v[16:19], v[212:215], v[224:227], v[16:19]
	v_mfma_f32_16x16x32_bf16 v[20:23], v[212:215], v[228:231], v[20:23]
	v_mfma_f32_16x16x32_bf16 v[24:27], v[212:215], v[232:235], v[24:27]
	v_mfma_f32_16x16x32_bf16 v[28:31], v[212:215], v[236:239], v[28:31]
	s_waitcnt lgkmcnt(1)
	v_mfma_f32_16x16x32_bf16 v[32:35], v[216:219], v[224:227], v[32:35]
	v_mfma_f32_16x16x32_bf16 v[36:39], v[216:219], v[228:231], v[36:39]
	v_mfma_f32_16x16x32_bf16 v[40:43], v[216:219], v[232:235], v[40:43]
	v_mfma_f32_16x16x32_bf16 v[44:47], v[216:219], v[236:239], v[44:47]
	s_waitcnt lgkmcnt(0)
	v_mfma_f32_16x16x32_bf16 v[48:51], v[220:223], v[224:227], v[48:51]
	v_mfma_f32_16x16x32_bf16 v[52:55], v[220:223], v[228:231], v[52:55]
	v_mfma_f32_16x16x32_bf16 v[56:59], v[220:223], v[232:235], v[56:59]
	v_mfma_f32_16x16x32_bf16 v[60:63], v[220:223], v[236:239], v[60:63]
	s_waitcnt vmcnt(0)
	s_barrier
	ds_read_b128 v[176:179], v244 offset:0
	ds_read_b128 v[80:83], v246 offset:0
	ds_read_b128 v[84:87], v246 offset:2048
	ds_read_b128 v[88:91], v246 offset:4096
	ds_read_b128 v[92:95], v246 offset:6144
	ds_read_b128 v[180:183], v244 offset:2048
	ds_read_b128 v[184:187], v244 offset:4096
	ds_read_b128 v[188:191], v244 offset:6144
	s_waitcnt lgkmcnt(6)
	v_mfma_f32_16x16x32_bf16 v[0:3], v[176:179], v[80:83], v[0:3]
	ds_read_b128 v[208:211], v245 offset:0
	s_add_i32 m0, s81, 32768
	s_waitcnt lgkmcnt(6)
	v_mfma_f32_16x16x32_bf16 v[4:7], v[176:179], v[84:87], v[4:7]
	ds_read_b128 v[224:227], v247 offset:0
	global_load_lds_dwordx4 v240, s[76:77]
	s_waitcnt lgkmcnt(6)
	v_mfma_f32_16x16x32_bf16 v[8:11], v[176:179], v[88:91], v[8:11]
	ds_read_b128 v[228:231], v247 offset:2048
	s_add_i32 m0, s81, 36864
	s_waitcnt lgkmcnt(6)
	v_mfma_f32_16x16x32_bf16 v[12:15], v[176:179], v[92:95], v[12:15]
	ds_read_b128 v[232:235], v247 offset:4096
	global_load_lds_dwordx4 v241, s[76:77]
	s_waitcnt lgkmcnt(6)
	v_mfma_f32_16x16x32_bf16 v[16:19], v[180:183], v[80:83], v[16:19]
	ds_read_b128 v[236:239], v247 offset:6144
	s_add_i32 m0, s81, 40960
	v_mfma_f32_16x16x32_bf16 v[20:23], v[180:183], v[84:87], v[20:23]
	ds_read_b128 v[212:215], v245 offset:2048
	global_load_lds_dwordx4 v242, s[76:77]
	v_mfma_f32_16x16x32_bf16 v[24:27], v[180:183], v[88:91], v[24:27]
	ds_read_b128 v[216:219], v245 offset:4096
	s_add_i32 m0, s81, 45056
	v_mfma_f32_16x16x32_bf16 v[28:31], v[180:183], v[92:95], v[28:31]
	ds_read_b128 v[220:223], v245 offset:6144
	global_load_lds_dwordx4 v243, s[76:77]
	s_waitcnt lgkmcnt(9)
	v_mfma_f32_16x16x32_bf16 v[32:35], v[184:187], v[80:83], v[32:35]
	s_add_i32 m0, s81, 49152
	v_mfma_f32_16x16x32_bf16 v[36:39], v[184:187], v[84:87], v[36:39]
	global_load_lds_dwordx4 v240, s[78:79]
	v_mfma_f32_16x16x32_bf16 v[40:43], v[184:187], v[88:91], v[40:43]
	s_add_i32 m0, s81, 53248
	v_mfma_f32_16x16x32_bf16 v[44:47], v[184:187], v[92:95], v[44:47]
	global_load_lds_dwordx4 v241, s[78:79]
	s_waitcnt lgkmcnt(8)
	v_mfma_f32_16x16x32_bf16 v[48:51], v[188:191], v[80:83], v[48:51]
	s_add_i32 m0, s81, 57344
	v_mfma_f32_16x16x32_bf16 v[52:55], v[188:191], v[84:87], v[52:55]
	global_load_lds_dwordx4 v242, s[78:79]
	v_mfma_f32_16x16x32_bf16 v[56:59], v[188:191], v[88:91], v[56:59]
	s_add_i32 m0, s81, 61440
	v_mfma_f32_16x16x32_bf16 v[60:63], v[188:191], v[92:95], v[60:63]
	global_load_lds_dwordx4 v243, s[78:79]
	s_waitcnt lgkmcnt(6)
	v_mfma_f32_16x16x32_bf16 v[0:3], v[208:211], v[224:227], v[0:3]
	s_add_u32 s76, s76, 0x80
	s_addc_u32 s77, s77, 0
	s_waitcnt lgkmcnt(5)
	v_mfma_f32_16x16x32_bf16 v[4:7], v[208:211], v[228:231], v[4:7]
	s_waitcnt lgkmcnt(4)
	v_mfma_f32_16x16x32_bf16 v[8:11], v[208:211], v[232:235], v[8:11]
	s_add_u32 s78, s78, 0x80
	s_addc_u32 s79, s79, 0
	s_waitcnt lgkmcnt(3)
	v_mfma_f32_16x16x32_bf16 v[12:15], v[208:211], v[236:239], v[12:15]
	s_waitcnt lgkmcnt(2)
	v_mfma_f32_16x16x32_bf16 v[16:19], v[212:215], v[224:227], v[16:19]
	v_add_u32_e32 v96, 0x0, v108
	v_mfma_f32_16x16x32_bf16 v[20:23], v[212:215], v[228:231], v[20:23]
	global_load_dwordx4 v[64:67], v96, s[86:87] nt
	v_mfma_f32_16x16x32_bf16 v[24:27], v[212:215], v[232:235], v[24:27]
	v_mfma_f32_16x16x32_bf16 v[28:31], v[212:215], v[236:239], v[28:31]
	s_waitcnt lgkmcnt(1)
	v_mfma_f32_16x16x32_bf16 v[32:35], v[216:219], v[224:227], v[32:35]
	v_mfma_f32_16x16x32_bf16 v[36:39], v[216:219], v[228:231], v[36:39]
	v_mfma_f32_16x16x32_bf16 v[40:43], v[216:219], v[232:235], v[40:43]
	v_mfma_f32_16x16x32_bf16 v[44:47], v[216:219], v[236:239], v[44:47]
	s_waitcnt lgkmcnt(0)
	v_mfma_f32_16x16x32_bf16 v[48:51], v[220:223], v[224:227], v[48:51]
	v_mfma_f32_16x16x32_bf16 v[52:55], v[220:223], v[228:231], v[52:55]
	v_mfma_f32_16x16x32_bf16 v[56:59], v[220:223], v[232:235], v[56:59]
	v_mfma_f32_16x16x32_bf16 v[60:63], v[220:223], v[236:239], v[60:63]
	s_waitcnt vmcnt(1)
	s_barrier
	ds_read_b128 v[176:179], v244 offset:32768
	ds_read_b128 v[80:83], v246 offset:32768
	ds_read_b128 v[84:87], v246 offset:34816
	ds_read_b128 v[88:91], v246 offset:36864
	ds_read_b128 v[92:95], v246 offset:38912
	ds_read_b128 v[180:183], v244 offset:34816
	ds_read_b128 v[184:187], v244 offset:36864
	ds_read_b128 v[188:191], v244 offset:38912
	s_waitcnt lgkmcnt(6)
	v_mfma_f32_16x16x32_bf16 v[0:3], v[176:179], v[80:83], v[0:3]
	ds_read_b128 v[208:211], v245 offset:32768
	s_add_i32 m0, s81, 0
	s_waitcnt lgkmcnt(6)
	v_mfma_f32_16x16x32_bf16 v[4:7], v[176:179], v[84:87], v[4:7]
	ds_read_b128 v[224:227], v247 offset:32768
	global_load_lds_dwordx4 v240, s[76:77]
	s_waitcnt lgkmcnt(6)
	v_mfma_f32_16x16x32_bf16 v[8:11], v[176:179], v[88:91], v[8:11]
	ds_read_b128 v[228:231], v247 offset:34816
	s_add_i32 m0, s81, 4096
	s_waitcnt lgkmcnt(6)
	v_mfma_f32_16x16x32_bf16 v[12:15], v[176:179], v[92:95], v[12:15]
	ds_read_b128 v[232:235], v247 offset:36864
	global_load_lds_dwordx4 v241, s[76:77]
	s_waitcnt lgkmcnt(6)
	v_mfma_f32_16x16x32_bf16 v[16:19], v[180:183], v[80:83], v[16:19]
	ds_read_b128 v[236:239], v247 offset:38912
	s_add_i32 m0, s81, 8192
	v_mfma_f32_16x16x32_bf16 v[20:23], v[180:183], v[84:87], v[20:23]
	ds_read_b128 v[212:215], v245 offset:34816
	global_load_lds_dwordx4 v242, s[76:77]
	v_mfma_f32_16x16x32_bf16 v[24:27], v[180:183], v[88:91], v[24:27]
	ds_read_b128 v[216:219], v245 offset:36864
	s_add_i32 m0, s81, 12288
	v_mfma_f32_16x16x32_bf16 v[28:31], v[180:183], v[92:95], v[28:31]
	ds_read_b128 v[220:223], v245 offset:38912
	global_load_lds_dwordx4 v243, s[76:77]
	s_waitcnt lgkmcnt(9)
	v_mfma_f32_16x16x32_bf16 v[32:35], v[184:187], v[80:83], v[32:35]
	s_add_i32 m0, s81, 16384
	v_mfma_f32_16x16x32_bf16 v[36:39], v[184:187], v[84:87], v[36:39]
	global_load_lds_dwordx4 v240, s[78:79]
	v_mfma_f32_16x16x32_bf16 v[40:43], v[184:187], v[88:91], v[40:43]
	s_add_i32 m0, s81, 20480
	v_mfma_f32_16x16x32_bf16 v[44:47], v[184:187], v[92:95], v[44:47]
	global_load_lds_dwordx4 v241, s[78:79]
	s_waitcnt lgkmcnt(8)
	v_mfma_f32_16x16x32_bf16 v[48:51], v[188:191], v[80:83], v[48:51]
	s_add_i32 m0, s81, 24576
	v_mfma_f32_16x16x32_bf16 v[52:55], v[188:191], v[84:87], v[52:55]
	global_load_lds_dwordx4 v242, s[78:79]
	v_mfma_f32_16x16x32_bf16 v[56:59], v[188:191], v[88:91], v[56:59]
	s_add_i32 m0, s81, 28672
	v_mfma_f32_16x16x32_bf16 v[60:63], v[188:191], v[92:95], v[60:63]
	global_load_lds_dwordx4 v243, s[78:79]
	s_waitcnt lgkmcnt(6)
	v_mfma_f32_16x16x32_bf16 v[0:3], v[208:211], v[224:227], v[0:3]
	s_add_u32 s76, s76, 0x80
	s_addc_u32 s77, s77, 0
	s_waitcnt lgkmcnt(5)
	v_mfma_f32_16x16x32_bf16 v[4:7], v[208:211], v[228:231], v[4:7]
	s_waitcnt lgkmcnt(4)
	v_mfma_f32_16x16x32_bf16 v[8:11], v[208:211], v[232:235], v[8:11]
	s_add_u32 s78, s78, 0x80
	s_addc_u32 s79, s79, 0
	s_waitcnt lgkmcnt(3)
	v_mfma_f32_16x16x32_bf16 v[12:15], v[208:211], v[236:239], v[12:15]
	s_waitcnt lgkmcnt(2)
	v_mfma_f32_16x16x32_bf16 v[16:19], v[212:215], v[224:227], v[16:19]
	v_add_u32_e32 v96, 0x8000, v108
	v_mfma_f32_16x16x32_bf16 v[20:23], v[212:215], v[228:231], v[20:23]
	global_load_dwordx4 v[68:71], v96, s[86:87] nt
	v_mfma_f32_16x16x32_bf16 v[24:27], v[212:215], v[232:235], v[24:27]
	v_mfma_f32_16x16x32_bf16 v[28:31], v[212:215], v[236:239], v[28:31]
	s_waitcnt lgkmcnt(1)
	v_mfma_f32_16x16x32_bf16 v[32:35], v[216:219], v[224:227], v[32:35]
	v_mfma_f32_16x16x32_bf16 v[36:39], v[216:219], v[228:231], v[36:39]
	v_mfma_f32_16x16x32_bf16 v[40:43], v[216:219], v[232:235], v[40:43]
	v_mfma_f32_16x16x32_bf16 v[44:47], v[216:219], v[236:239], v[44:47]
	s_waitcnt lgkmcnt(0)
	v_mfma_f32_16x16x32_bf16 v[48:51], v[220:223], v[224:227], v[48:51]
	v_mfma_f32_16x16x32_bf16 v[52:55], v[220:223], v[228:231], v[52:55]
	v_mfma_f32_16x16x32_bf16 v[56:59], v[220:223], v[232:235], v[56:59]
	v_mfma_f32_16x16x32_bf16 v[60:63], v[220:223], v[236:239], v[60:63]
	s_waitcnt vmcnt(1)
	s_barrier
	ds_read_b128 v[176:179], v244 offset:0
	ds_read_b128 v[80:83], v246 offset:0
	ds_read_b128 v[84:87], v246 offset:2048
	ds_read_b128 v[88:91], v246 offset:4096
	ds_read_b128 v[92:95], v246 offset:6144
	ds_read_b128 v[180:183], v244 offset:2048
	ds_read_b128 v[184:187], v244 offset:4096
	ds_read_b128 v[188:191], v244 offset:6144
	s_waitcnt lgkmcnt(6)
	v_mfma_f32_16x16x32_bf16 v[0:3], v[176:179], v[80:83], v[0:3]
	ds_read_b128 v[208:211], v245 offset:0
	s_add_i32 m0, s81, 32768
	s_waitcnt lgkmcnt(6)
	v_mfma_f32_16x16x32_bf16 v[4:7], v[176:179], v[84:87], v[4:7]
	ds_read_b128 v[224:227], v247 offset:0
	global_load_lds_dwordx4 v240, s[76:77]
	s_waitcnt lgkmcnt(6)
	v_mfma_f32_16x16x32_bf16 v[8:11], v[176:179], v[88:91], v[8:11]
	ds_read_b128 v[228:231], v247 offset:2048
	s_add_i32 m0, s81, 36864
	s_waitcnt lgkmcnt(6)
	v_mfma_f32_16x16x32_bf16 v[12:15], v[176:179], v[92:95], v[12:15]
	ds_read_b128 v[232:235], v247 offset:4096
	global_load_lds_dwordx4 v241, s[76:77]
	s_waitcnt lgkmcnt(6)
	v_mfma_f32_16x16x32_bf16 v[16:19], v[180:183], v[80:83], v[16:19]
	ds_read_b128 v[236:239], v247 offset:6144
	s_add_i32 m0, s81, 40960
	v_mfma_f32_16x16x32_bf16 v[20:23], v[180:183], v[84:87], v[20:23]
	ds_read_b128 v[212:215], v245 offset:2048
	global_load_lds_dwordx4 v242, s[76:77]
	v_mfma_f32_16x16x32_bf16 v[24:27], v[180:183], v[88:91], v[24:27]
	ds_read_b128 v[216:219], v245 offset:4096
	s_add_i32 m0, s81, 45056
	v_mfma_f32_16x16x32_bf16 v[28:31], v[180:183], v[92:95], v[28:31]
	ds_read_b128 v[220:223], v245 offset:6144
	global_load_lds_dwordx4 v243, s[76:77]
	s_waitcnt lgkmcnt(9)
	v_mfma_f32_16x16x32_bf16 v[32:35], v[184:187], v[80:83], v[32:35]
	s_add_i32 m0, s81, 49152
	v_mfma_f32_16x16x32_bf16 v[36:39], v[184:187], v[84:87], v[36:39]
	global_load_lds_dwordx4 v240, s[78:79]
	v_mfma_f32_16x16x32_bf16 v[40:43], v[184:187], v[88:91], v[40:43]
	s_add_i32 m0, s81, 53248
	v_mfma_f32_16x16x32_bf16 v[44:47], v[184:187], v[92:95], v[44:47]
	global_load_lds_dwordx4 v241, s[78:79]
	s_waitcnt lgkmcnt(8)
	v_mfma_f32_16x16x32_bf16 v[48:51], v[188:191], v[80:83], v[48:51]
	s_add_i32 m0, s81, 57344
	v_mfma_f32_16x16x32_bf16 v[52:55], v[188:191], v[84:87], v[52:55]
	global_load_lds_dwordx4 v242, s[78:79]
	v_mfma_f32_16x16x32_bf16 v[56:59], v[188:191], v[88:91], v[56:59]
	s_add_i32 m0, s81, 61440
	v_mfma_f32_16x16x32_bf16 v[60:63], v[188:191], v[92:95], v[60:63]
	global_load_lds_dwordx4 v243, s[78:79]
	s_waitcnt lgkmcnt(6)
	v_mfma_f32_16x16x32_bf16 v[0:3], v[208:211], v[224:227], v[0:3]
	s_add_u32 s76, s76, 0x80
	s_addc_u32 s77, s77, 0
	s_waitcnt lgkmcnt(5)
	v_mfma_f32_16x16x32_bf16 v[4:7], v[208:211], v[228:231], v[4:7]
	s_waitcnt lgkmcnt(4)
	v_mfma_f32_16x16x32_bf16 v[8:11], v[208:211], v[232:235], v[8:11]
	s_add_u32 s78, s78, 0x80
	s_addc_u32 s79, s79, 0
	s_waitcnt lgkmcnt(3)
	v_mfma_f32_16x16x32_bf16 v[12:15], v[208:211], v[236:239], v[12:15]
	s_waitcnt lgkmcnt(2)
	v_mfma_f32_16x16x32_bf16 v[16:19], v[212:215], v[224:227], v[16:19]
	v_add_u32_e32 v96, 0x10000, v108
	v_mfma_f32_16x16x32_bf16 v[20:23], v[212:215], v[228:231], v[20:23]
	global_load_dwordx4 v[192:195], v96, s[86:87] nt
	v_mfma_f32_16x16x32_bf16 v[24:27], v[212:215], v[232:235], v[24:27]
	v_mfma_f32_16x16x32_bf16 v[28:31], v[212:215], v[236:239], v[28:31]
	s_waitcnt lgkmcnt(1)
	v_mfma_f32_16x16x32_bf16 v[32:35], v[216:219], v[224:227], v[32:35]
	v_mfma_f32_16x16x32_bf16 v[36:39], v[216:219], v[228:231], v[36:39]
	v_mfma_f32_16x16x32_bf16 v[40:43], v[216:219], v[232:235], v[40:43]
	v_mfma_f32_16x16x32_bf16 v[44:47], v[216:219], v[236:239], v[44:47]
	s_waitcnt lgkmcnt(0)
	v_mfma_f32_16x16x32_bf16 v[48:51], v[220:223], v[224:227], v[48:51]
	v_mfma_f32_16x16x32_bf16 v[52:55], v[220:223], v[228:231], v[52:55]
	v_mfma_f32_16x16x32_bf16 v[56:59], v[220:223], v[232:235], v[56:59]
	v_mfma_f32_16x16x32_bf16 v[60:63], v[220:223], v[236:239], v[60:63]
	s_waitcnt vmcnt(1)
	s_barrier
	ds_read_b128 v[176:179], v244 offset:32768
	ds_read_b128 v[80:83], v246 offset:32768
	ds_read_b128 v[84:87], v246 offset:34816
	ds_read_b128 v[88:91], v246 offset:36864
	ds_read_b128 v[92:95], v246 offset:38912
	ds_read_b128 v[180:183], v244 offset:34816
	ds_read_b128 v[184:187], v244 offset:36864
	ds_read_b128 v[188:191], v244 offset:38912
	s_waitcnt lgkmcnt(6)
	v_mfma_f32_16x16x32_bf16 v[0:3], v[176:179], v[80:83], v[0:3]
	ds_read_b128 v[208:211], v245 offset:32768
	s_add_i32 m0, s81, 0
	s_waitcnt lgkmcnt(6)
	v_mfma_f32_16x16x32_bf16 v[4:7], v[176:179], v[84:87], v[4:7]
	ds_read_b128 v[224:227], v247 offset:32768
	global_load_lds_dwordx4 v240, s[76:77]
	s_waitcnt lgkmcnt(6)
	v_mfma_f32_16x16x32_bf16 v[8:11], v[176:179], v[88:91], v[8:11]
	ds_read_b128 v[228:231], v247 offset:34816
	s_add_i32 m0, s81, 4096
	s_waitcnt lgkmcnt(6)
	v_mfma_f32_16x16x32_bf16 v[12:15], v[176:179], v[92:95], v[12:15]
	ds_read_b128 v[232:235], v247 offset:36864
	global_load_lds_dwordx4 v241, s[76:77]
	s_waitcnt lgkmcnt(6)
	v_mfma_f32_16x16x32_bf16 v[16:19], v[180:183], v[80:83], v[16:19]
	ds_read_b128 v[236:239], v247 offset:38912
	s_add_i32 m0, s81, 8192
	v_mfma_f32_16x16x32_bf16 v[20:23], v[180:183], v[84:87], v[20:23]
	ds_read_b128 v[212:215], v245 offset:34816
	global_load_lds_dwordx4 v242, s[76:77]
	v_mfma_f32_16x16x32_bf16 v[24:27], v[180:183], v[88:91], v[24:27]
	ds_read_b128 v[216:219], v245 offset:36864
	s_add_i32 m0, s81, 12288
	v_mfma_f32_16x16x32_bf16 v[28:31], v[180:183], v[92:95], v[28:31]
	ds_read_b128 v[220:223], v245 offset:38912
	global_load_lds_dwordx4 v243, s[76:77]
	s_waitcnt lgkmcnt(9)
	v_mfma_f32_16x16x32_bf16 v[32:35], v[184:187], v[80:83], v[32:35]
	s_add_i32 m0, s81, 16384
	v_mfma_f32_16x16x32_bf16 v[36:39], v[184:187], v[84:87], v[36:39]
	global_load_lds_dwordx4 v240, s[78:79]
	v_mfma_f32_16x16x32_bf16 v[40:43], v[184:187], v[88:91], v[40:43]
	s_add_i32 m0, s81, 20480
	v_mfma_f32_16x16x32_bf16 v[44:47], v[184:187], v[92:95], v[44:47]
	global_load_lds_dwordx4 v241, s[78:79]
	s_waitcnt lgkmcnt(8)
	v_mfma_f32_16x16x32_bf16 v[48:51], v[188:191], v[80:83], v[48:51]
	s_add_i32 m0, s81, 24576
	v_mfma_f32_16x16x32_bf16 v[52:55], v[188:191], v[84:87], v[52:55]
	global_load_lds_dwordx4 v242, s[78:79]
	v_mfma_f32_16x16x32_bf16 v[56:59], v[188:191], v[88:91], v[56:59]
	s_add_i32 m0, s81, 28672
	v_mfma_f32_16x16x32_bf16 v[60:63], v[188:191], v[92:95], v[60:63]
	global_load_lds_dwordx4 v243, s[78:79]
	s_waitcnt lgkmcnt(6)
	v_mfma_f32_16x16x32_bf16 v[0:3], v[208:211], v[224:227], v[0:3]
	s_add_u32 s76, s76, 0x80
	s_addc_u32 s77, s77, 0
	s_waitcnt lgkmcnt(5)
	v_mfma_f32_16x16x32_bf16 v[4:7], v[208:211], v[228:231], v[4:7]
	s_waitcnt lgkmcnt(4)
	v_mfma_f32_16x16x32_bf16 v[8:11], v[208:211], v[232:235], v[8:11]
	s_add_u32 s78, s78, 0x80
	s_addc_u32 s79, s79, 0
	s_waitcnt lgkmcnt(3)
	v_mfma_f32_16x16x32_bf16 v[12:15], v[208:211], v[236:239], v[12:15]
	s_waitcnt lgkmcnt(2)
	v_mfma_f32_16x16x32_bf16 v[16:19], v[212:215], v[224:227], v[16:19]
	v_add_u32_e32 v96, 0x18000, v108
	v_mfma_f32_16x16x32_bf16 v[20:23], v[212:215], v[228:231], v[20:23]
	global_load_dwordx4 v[196:199], v96, s[86:87] nt
	v_mfma_f32_16x16x32_bf16 v[24:27], v[212:215], v[232:235], v[24:27]
	v_mfma_f32_16x16x32_bf16 v[28:31], v[212:215], v[236:239], v[28:31]
	s_waitcnt lgkmcnt(1)
	v_mfma_f32_16x16x32_bf16 v[32:35], v[216:219], v[224:227], v[32:35]
	v_mfma_f32_16x16x32_bf16 v[36:39], v[216:219], v[228:231], v[36:39]
	v_mfma_f32_16x16x32_bf16 v[40:43], v[216:219], v[232:235], v[40:43]
	v_mfma_f32_16x16x32_bf16 v[44:47], v[216:219], v[236:239], v[44:47]
	s_waitcnt lgkmcnt(0)
	v_mfma_f32_16x16x32_bf16 v[48:51], v[220:223], v[224:227], v[48:51]
	v_mfma_f32_16x16x32_bf16 v[52:55], v[220:223], v[228:231], v[52:55]
	v_mfma_f32_16x16x32_bf16 v[56:59], v[220:223], v[232:235], v[56:59]
	v_mfma_f32_16x16x32_bf16 v[60:63], v[220:223], v[236:239], v[60:63]
	s_waitcnt vmcnt(1)
	s_barrier
	ds_read_b128 v[176:179], v244 offset:0
	ds_read_b128 v[80:83], v246 offset:0
	ds_read_b128 v[84:87], v246 offset:2048
	ds_read_b128 v[88:91], v246 offset:4096
	ds_read_b128 v[92:95], v246 offset:6144
	ds_read_b128 v[180:183], v244 offset:2048
	ds_read_b128 v[184:187], v244 offset:4096
	ds_read_b128 v[188:191], v244 offset:6144
	s_waitcnt lgkmcnt(6)
	v_mfma_f32_16x16x32_bf16 v[0:3], v[176:179], v[80:83], v[0:3]
	ds_read_b128 v[208:211], v245 offset:0
	s_add_i32 m0, s81, 32768
	s_waitcnt lgkmcnt(6)
	v_mfma_f32_16x16x32_bf16 v[4:7], v[176:179], v[84:87], v[4:7]
	ds_read_b128 v[224:227], v247 offset:0
	global_load_lds_dwordx4 v240, s[76:77]
	s_waitcnt lgkmcnt(6)
	v_mfma_f32_16x16x32_bf16 v[8:11], v[176:179], v[88:91], v[8:11]
	ds_read_b128 v[228:231], v247 offset:2048
	s_add_i32 m0, s81, 36864
	s_waitcnt lgkmcnt(6)
	v_mfma_f32_16x16x32_bf16 v[12:15], v[176:179], v[92:95], v[12:15]
	ds_read_b128 v[232:235], v247 offset:4096
	global_load_lds_dwordx4 v241, s[76:77]
	s_waitcnt lgkmcnt(6)
	v_mfma_f32_16x16x32_bf16 v[16:19], v[180:183], v[80:83], v[16:19]
	ds_read_b128 v[236:239], v247 offset:6144
	s_add_i32 m0, s81, 40960
	v_mfma_f32_16x16x32_bf16 v[20:23], v[180:183], v[84:87], v[20:23]
	ds_read_b128 v[212:215], v245 offset:2048
	global_load_lds_dwordx4 v242, s[76:77]
	v_mfma_f32_16x16x32_bf16 v[24:27], v[180:183], v[88:91], v[24:27]
	ds_read_b128 v[216:219], v245 offset:4096
	s_add_i32 m0, s81, 45056
	v_mfma_f32_16x16x32_bf16 v[28:31], v[180:183], v[92:95], v[28:31]
	ds_read_b128 v[220:223], v245 offset:6144
	global_load_lds_dwordx4 v243, s[76:77]
	s_waitcnt lgkmcnt(9)
	v_mfma_f32_16x16x32_bf16 v[32:35], v[184:187], v[80:83], v[32:35]
	s_add_i32 m0, s81, 49152
	v_mfma_f32_16x16x32_bf16 v[36:39], v[184:187], v[84:87], v[36:39]
	global_load_lds_dwordx4 v240, s[78:79]
	v_mfma_f32_16x16x32_bf16 v[40:43], v[184:187], v[88:91], v[40:43]
	s_add_i32 m0, s81, 53248
	v_mfma_f32_16x16x32_bf16 v[44:47], v[184:187], v[92:95], v[44:47]
	global_load_lds_dwordx4 v241, s[78:79]
	s_waitcnt lgkmcnt(8)
	v_mfma_f32_16x16x32_bf16 v[48:51], v[188:191], v[80:83], v[48:51]
	s_add_i32 m0, s81, 57344
	v_mfma_f32_16x16x32_bf16 v[52:55], v[188:191], v[84:87], v[52:55]
	global_load_lds_dwordx4 v242, s[78:79]
	v_mfma_f32_16x16x32_bf16 v[56:59], v[188:191], v[88:91], v[56:59]
	s_add_i32 m0, s81, 61440
	v_mfma_f32_16x16x32_bf16 v[60:63], v[188:191], v[92:95], v[60:63]
	global_load_lds_dwordx4 v243, s[78:79]
	s_waitcnt lgkmcnt(6)
	v_mfma_f32_16x16x32_bf16 v[0:3], v[208:211], v[224:227], v[0:3]
	s_add_u32 s76, s76, 0x80
	s_addc_u32 s77, s77, 0
	s_waitcnt lgkmcnt(5)
	v_mfma_f32_16x16x32_bf16 v[4:7], v[208:211], v[228:231], v[4:7]
	s_waitcnt lgkmcnt(4)
	v_mfma_f32_16x16x32_bf16 v[8:11], v[208:211], v[232:235], v[8:11]
	s_add_u32 s78, s78, 0x80
	s_addc_u32 s79, s79, 0
	s_waitcnt lgkmcnt(3)
	v_mfma_f32_16x16x32_bf16 v[12:15], v[208:211], v[236:239], v[12:15]
	s_waitcnt lgkmcnt(2)
	v_mfma_f32_16x16x32_bf16 v[16:19], v[212:215], v[224:227], v[16:19]
	v_add_u32_e32 v96, 0x20000, v108
	v_mfma_f32_16x16x32_bf16 v[20:23], v[212:215], v[228:231], v[20:23]
	global_load_dwordx4 v[200:203], v96, s[86:87] nt
	v_mfma_f32_16x16x32_bf16 v[24:27], v[212:215], v[232:235], v[24:27]
	v_mfma_f32_16x16x32_bf16 v[28:31], v[212:215], v[236:239], v[28:31]
	s_waitcnt lgkmcnt(1)
	v_mfma_f32_16x16x32_bf16 v[32:35], v[216:219], v[224:227], v[32:35]
	v_mfma_f32_16x16x32_bf16 v[36:39], v[216:219], v[228:231], v[36:39]
	v_mfma_f32_16x16x32_bf16 v[40:43], v[216:219], v[232:235], v[40:43]
	v_mfma_f32_16x16x32_bf16 v[44:47], v[216:219], v[236:239], v[44:47]
	s_waitcnt lgkmcnt(0)
	v_mfma_f32_16x16x32_bf16 v[48:51], v[220:223], v[224:227], v[48:51]
	v_mfma_f32_16x16x32_bf16 v[52:55], v[220:223], v[228:231], v[52:55]
	v_mfma_f32_16x16x32_bf16 v[56:59], v[220:223], v[232:235], v[56:59]
	v_mfma_f32_16x16x32_bf16 v[60:63], v[220:223], v[236:239], v[60:63]
	s_waitcnt vmcnt(1)
	s_barrier
	ds_read_b128 v[176:179], v244 offset:32768
	ds_read_b128 v[80:83], v246 offset:32768
	ds_read_b128 v[84:87], v246 offset:34816
	ds_read_b128 v[88:91], v246 offset:36864
	ds_read_b128 v[92:95], v246 offset:38912
	ds_read_b128 v[180:183], v244 offset:34816
	ds_read_b128 v[184:187], v244 offset:36864
	ds_read_b128 v[188:191], v244 offset:38912
	s_waitcnt lgkmcnt(6)
	v_mfma_f32_16x16x32_bf16 v[0:3], v[176:179], v[80:83], v[0:3]
	ds_read_b128 v[208:211], v245 offset:32768
	s_add_i32 m0, s81, 0
	s_waitcnt lgkmcnt(6)
	v_mfma_f32_16x16x32_bf16 v[4:7], v[176:179], v[84:87], v[4:7]
	ds_read_b128 v[224:227], v247 offset:32768
	global_load_lds_dwordx4 v240, s[76:77]
	s_waitcnt lgkmcnt(6)
	v_mfma_f32_16x16x32_bf16 v[8:11], v[176:179], v[88:91], v[8:11]
	ds_read_b128 v[228:231], v247 offset:34816
	s_add_i32 m0, s81, 4096
	s_waitcnt lgkmcnt(6)
	v_mfma_f32_16x16x32_bf16 v[12:15], v[176:179], v[92:95], v[12:15]
	ds_read_b128 v[232:235], v247 offset:36864
	global_load_lds_dwordx4 v241, s[76:77]
	s_waitcnt lgkmcnt(6)
	v_mfma_f32_16x16x32_bf16 v[16:19], v[180:183], v[80:83], v[16:19]
	ds_read_b128 v[236:239], v247 offset:38912
	s_add_i32 m0, s81, 8192
	v_mfma_f32_16x16x32_bf16 v[20:23], v[180:183], v[84:87], v[20:23]
	ds_read_b128 v[212:215], v245 offset:34816
	global_load_lds_dwordx4 v242, s[76:77]
	v_mfma_f32_16x16x32_bf16 v[24:27], v[180:183], v[88:91], v[24:27]
	ds_read_b128 v[216:219], v245 offset:36864
	s_add_i32 m0, s81, 12288
	v_mfma_f32_16x16x32_bf16 v[28:31], v[180:183], v[92:95], v[28:31]
	ds_read_b128 v[220:223], v245 offset:38912
	global_load_lds_dwordx4 v243, s[76:77]
	s_waitcnt lgkmcnt(9)
	v_mfma_f32_16x16x32_bf16 v[32:35], v[184:187], v[80:83], v[32:35]
	s_add_i32 m0, s81, 16384
	v_mfma_f32_16x16x32_bf16 v[36:39], v[184:187], v[84:87], v[36:39]
	global_load_lds_dwordx4 v240, s[78:79]
	v_mfma_f32_16x16x32_bf16 v[40:43], v[184:187], v[88:91], v[40:43]
	s_add_i32 m0, s81, 20480
	v_mfma_f32_16x16x32_bf16 v[44:47], v[184:187], v[92:95], v[44:47]
	global_load_lds_dwordx4 v241, s[78:79]
	s_waitcnt lgkmcnt(8)
	v_mfma_f32_16x16x32_bf16 v[48:51], v[188:191], v[80:83], v[48:51]
	s_add_i32 m0, s81, 24576
	v_mfma_f32_16x16x32_bf16 v[52:55], v[188:191], v[84:87], v[52:55]
	global_load_lds_dwordx4 v242, s[78:79]
	v_mfma_f32_16x16x32_bf16 v[56:59], v[188:191], v[88:91], v[56:59]
	s_add_i32 m0, s81, 28672
	v_mfma_f32_16x16x32_bf16 v[60:63], v[188:191], v[92:95], v[60:63]
	global_load_lds_dwordx4 v243, s[78:79]
	s_waitcnt lgkmcnt(6)
	v_mfma_f32_16x16x32_bf16 v[0:3], v[208:211], v[224:227], v[0:3]
	s_add_u32 s76, s76, 0x80
	s_addc_u32 s77, s77, 0
	s_waitcnt lgkmcnt(5)
	v_mfma_f32_16x16x32_bf16 v[4:7], v[208:211], v[228:231], v[4:7]
	s_waitcnt lgkmcnt(4)
	v_mfma_f32_16x16x32_bf16 v[8:11], v[208:211], v[232:235], v[8:11]
	s_add_u32 s78, s78, 0x80
	s_addc_u32 s79, s79, 0
	s_waitcnt lgkmcnt(3)
	v_mfma_f32_16x16x32_bf16 v[12:15], v[208:211], v[236:239], v[12:15]
	s_waitcnt lgkmcnt(2)
	v_mfma_f32_16x16x32_bf16 v[16:19], v[212:215], v[224:227], v[16:19]
	v_add_u32_e32 v96, 0x28000, v108
	v_mfma_f32_16x16x32_bf16 v[20:23], v[212:215], v[228:231], v[20:23]
	global_load_dwordx4 v[110:113], v96, s[86:87] nt
	v_mfma_f32_16x16x32_bf16 v[24:27], v[212:215], v[232:235], v[24:27]
	v_mfma_f32_16x16x32_bf16 v[28:31], v[212:215], v[236:239], v[28:31]
	s_waitcnt lgkmcnt(1)
	v_mfma_f32_16x16x32_bf16 v[32:35], v[216:219], v[224:227], v[32:35]
	v_mfma_f32_16x16x32_bf16 v[36:39], v[216:219], v[228:231], v[36:39]
	v_mfma_f32_16x16x32_bf16 v[40:43], v[216:219], v[232:235], v[40:43]
	v_mfma_f32_16x16x32_bf16 v[44:47], v[216:219], v[236:239], v[44:47]
	s_waitcnt lgkmcnt(0)
	v_mfma_f32_16x16x32_bf16 v[48:51], v[220:223], v[224:227], v[48:51]
	v_mfma_f32_16x16x32_bf16 v[52:55], v[220:223], v[228:231], v[52:55]
	v_mfma_f32_16x16x32_bf16 v[56:59], v[220:223], v[232:235], v[56:59]
	v_mfma_f32_16x16x32_bf16 v[60:63], v[220:223], v[236:239], v[60:63]
	s_waitcnt vmcnt(1)
	s_barrier
	ds_read_b128 v[176:179], v244 offset:0
	ds_read_b128 v[80:83], v246 offset:0
	ds_read_b128 v[84:87], v246 offset:2048
	ds_read_b128 v[88:91], v246 offset:4096
	ds_read_b128 v[92:95], v246 offset:6144
	ds_read_b128 v[180:183], v244 offset:2048
	ds_read_b128 v[184:187], v244 offset:4096
	ds_read_b128 v[188:191], v244 offset:6144
	s_waitcnt lgkmcnt(6)
	v_mfma_f32_16x16x32_bf16 v[0:3], v[176:179], v[80:83], v[0:3]
	ds_read_b128 v[208:211], v245 offset:0
	s_add_i32 m0, s81, 32768
	s_waitcnt lgkmcnt(6)
	v_mfma_f32_16x16x32_bf16 v[4:7], v[176:179], v[84:87], v[4:7]
	ds_read_b128 v[224:227], v247 offset:0
	global_load_lds_dwordx4 v240, s[76:77]
	s_waitcnt lgkmcnt(6)
	v_mfma_f32_16x16x32_bf16 v[8:11], v[176:179], v[88:91], v[8:11]
	ds_read_b128 v[228:231], v247 offset:2048
	s_add_i32 m0, s81, 36864
	s_waitcnt lgkmcnt(6)
	v_mfma_f32_16x16x32_bf16 v[12:15], v[176:179], v[92:95], v[12:15]
	ds_read_b128 v[232:235], v247 offset:4096
	global_load_lds_dwordx4 v241, s[76:77]
	s_waitcnt lgkmcnt(6)
	v_mfma_f32_16x16x32_bf16 v[16:19], v[180:183], v[80:83], v[16:19]
	ds_read_b128 v[236:239], v247 offset:6144
	s_add_i32 m0, s81, 40960
	v_mfma_f32_16x16x32_bf16 v[20:23], v[180:183], v[84:87], v[20:23]
	ds_read_b128 v[212:215], v245 offset:2048
	global_load_lds_dwordx4 v242, s[76:77]
	v_mfma_f32_16x16x32_bf16 v[24:27], v[180:183], v[88:91], v[24:27]
	ds_read_b128 v[216:219], v245 offset:4096
	s_add_i32 m0, s81, 45056
	v_mfma_f32_16x16x32_bf16 v[28:31], v[180:183], v[92:95], v[28:31]
	ds_read_b128 v[220:223], v245 offset:6144
	global_load_lds_dwordx4 v243, s[76:77]
	s_waitcnt lgkmcnt(9)
	v_mfma_f32_16x16x32_bf16 v[32:35], v[184:187], v[80:83], v[32:35]
	s_add_i32 m0, s81, 49152
	v_mfma_f32_16x16x32_bf16 v[36:39], v[184:187], v[84:87], v[36:39]
	global_load_lds_dwordx4 v240, s[78:79]
	v_mfma_f32_16x16x32_bf16 v[40:43], v[184:187], v[88:91], v[40:43]
	s_add_i32 m0, s81, 53248
	v_mfma_f32_16x16x32_bf16 v[44:47], v[184:187], v[92:95], v[44:47]
	global_load_lds_dwordx4 v241, s[78:79]
	s_waitcnt lgkmcnt(8)
	v_mfma_f32_16x16x32_bf16 v[48:51], v[188:191], v[80:83], v[48:51]
	s_add_i32 m0, s81, 57344
	v_mfma_f32_16x16x32_bf16 v[52:55], v[188:191], v[84:87], v[52:55]
	global_load_lds_dwordx4 v242, s[78:79]
	v_mfma_f32_16x16x32_bf16 v[56:59], v[188:191], v[88:91], v[56:59]
	s_add_i32 m0, s81, 61440
	v_mfma_f32_16x16x32_bf16 v[60:63], v[188:191], v[92:95], v[60:63]
	global_load_lds_dwordx4 v243, s[78:79]
	s_waitcnt lgkmcnt(6)
	v_mfma_f32_16x16x32_bf16 v[0:3], v[208:211], v[224:227], v[0:3]
	s_add_u32 s76, s76, 0x80
	s_addc_u32 s77, s77, 0
	s_waitcnt lgkmcnt(5)
	v_mfma_f32_16x16x32_bf16 v[4:7], v[208:211], v[228:231], v[4:7]
	s_waitcnt lgkmcnt(4)
	v_mfma_f32_16x16x32_bf16 v[8:11], v[208:211], v[232:235], v[8:11]
	s_add_u32 s78, s78, 0x80
	s_addc_u32 s79, s79, 0
	s_waitcnt lgkmcnt(3)
	v_mfma_f32_16x16x32_bf16 v[12:15], v[208:211], v[236:239], v[12:15]
	s_waitcnt lgkmcnt(2)
	v_mfma_f32_16x16x32_bf16 v[16:19], v[212:215], v[224:227], v[16:19]
	v_add_u32_e32 v96, 0x30000, v108
	v_mfma_f32_16x16x32_bf16 v[20:23], v[212:215], v[228:231], v[20:23]
	global_load_dwordx4 v[116:119], v96, s[86:87] nt
	v_mfma_f32_16x16x32_bf16 v[24:27], v[212:215], v[232:235], v[24:27]
	v_mfma_f32_16x16x32_bf16 v[28:31], v[212:215], v[236:239], v[28:31]
	s_waitcnt lgkmcnt(1)
	v_mfma_f32_16x16x32_bf16 v[32:35], v[216:219], v[224:227], v[32:35]
	v_mfma_f32_16x16x32_bf16 v[36:39], v[216:219], v[228:231], v[36:39]
	v_mfma_f32_16x16x32_bf16 v[40:43], v[216:219], v[232:235], v[40:43]
	v_mfma_f32_16x16x32_bf16 v[44:47], v[216:219], v[236:239], v[44:47]
	s_waitcnt lgkmcnt(0)
	v_mfma_f32_16x16x32_bf16 v[48:51], v[220:223], v[224:227], v[48:51]
	v_mfma_f32_16x16x32_bf16 v[52:55], v[220:223], v[228:231], v[52:55]
	v_mfma_f32_16x16x32_bf16 v[56:59], v[220:223], v[232:235], v[56:59]
	v_mfma_f32_16x16x32_bf16 v[60:63], v[220:223], v[236:239], v[60:63]
	s_waitcnt vmcnt(1)
	s_barrier
	ds_read_b128 v[176:179], v244 offset:32768
	ds_read_b128 v[80:83], v246 offset:32768
	ds_read_b128 v[84:87], v246 offset:34816
	ds_read_b128 v[88:91], v246 offset:36864
	ds_read_b128 v[92:95], v246 offset:38912
	ds_read_b128 v[180:183], v244 offset:34816
	ds_read_b128 v[184:187], v244 offset:36864
	ds_read_b128 v[188:191], v244 offset:38912
	s_waitcnt lgkmcnt(6)
	v_mfma_f32_16x16x32_bf16 v[0:3], v[176:179], v[80:83], v[0:3]
	ds_read_b128 v[208:211], v245 offset:32768
	s_add_i32 m0, s81, 0
	s_waitcnt lgkmcnt(6)
	v_mfma_f32_16x16x32_bf16 v[4:7], v[176:179], v[84:87], v[4:7]
	ds_read_b128 v[224:227], v247 offset:32768
	global_load_lds_dwordx4 v240, s[76:77]
	s_waitcnt lgkmcnt(6)
	v_mfma_f32_16x16x32_bf16 v[8:11], v[176:179], v[88:91], v[8:11]
	ds_read_b128 v[228:231], v247 offset:34816
	s_add_i32 m0, s81, 4096
	s_waitcnt lgkmcnt(6)
	v_mfma_f32_16x16x32_bf16 v[12:15], v[176:179], v[92:95], v[12:15]
	ds_read_b128 v[232:235], v247 offset:36864
	global_load_lds_dwordx4 v241, s[76:77]
	s_waitcnt lgkmcnt(6)
	v_mfma_f32_16x16x32_bf16 v[16:19], v[180:183], v[80:83], v[16:19]
	ds_read_b128 v[236:239], v247 offset:38912
	s_add_i32 m0, s81, 8192
	v_mfma_f32_16x16x32_bf16 v[20:23], v[180:183], v[84:87], v[20:23]
	ds_read_b128 v[212:215], v245 offset:34816
	global_load_lds_dwordx4 v242, s[76:77]
	v_mfma_f32_16x16x32_bf16 v[24:27], v[180:183], v[88:91], v[24:27]
	ds_read_b128 v[216:219], v245 offset:36864
	s_add_i32 m0, s81, 12288
	v_mfma_f32_16x16x32_bf16 v[28:31], v[180:183], v[92:95], v[28:31]
	ds_read_b128 v[220:223], v245 offset:38912
	global_load_lds_dwordx4 v243, s[76:77]
	s_waitcnt lgkmcnt(9)
	v_mfma_f32_16x16x32_bf16 v[32:35], v[184:187], v[80:83], v[32:35]
	s_add_i32 m0, s81, 16384
	v_mfma_f32_16x16x32_bf16 v[36:39], v[184:187], v[84:87], v[36:39]
	global_load_lds_dwordx4 v240, s[78:79]
	v_mfma_f32_16x16x32_bf16 v[40:43], v[184:187], v[88:91], v[40:43]
	s_add_i32 m0, s81, 20480
	v_mfma_f32_16x16x32_bf16 v[44:47], v[184:187], v[92:95], v[44:47]
	global_load_lds_dwordx4 v241, s[78:79]
	s_waitcnt lgkmcnt(8)
	v_mfma_f32_16x16x32_bf16 v[48:51], v[188:191], v[80:83], v[48:51]
	s_add_i32 m0, s81, 24576
	v_mfma_f32_16x16x32_bf16 v[52:55], v[188:191], v[84:87], v[52:55]
	global_load_lds_dwordx4 v242, s[78:79]
	v_mfma_f32_16x16x32_bf16 v[56:59], v[188:191], v[88:91], v[56:59]
	s_add_i32 m0, s81, 28672
	v_mfma_f32_16x16x32_bf16 v[60:63], v[188:191], v[92:95], v[60:63]
	global_load_lds_dwordx4 v243, s[78:79]
	s_waitcnt lgkmcnt(6)
	v_mfma_f32_16x16x32_bf16 v[0:3], v[208:211], v[224:227], v[0:3]
	s_add_u32 s76, s76, 0x80
	s_addc_u32 s77, s77, 0
	s_waitcnt lgkmcnt(5)
	v_mfma_f32_16x16x32_bf16 v[4:7], v[208:211], v[228:231], v[4:7]
	s_waitcnt lgkmcnt(4)
	v_mfma_f32_16x16x32_bf16 v[8:11], v[208:211], v[232:235], v[8:11]
	s_add_u32 s78, s78, 0x80
	s_addc_u32 s79, s79, 0
	s_waitcnt lgkmcnt(3)
	v_mfma_f32_16x16x32_bf16 v[12:15], v[208:211], v[236:239], v[12:15]
	s_waitcnt lgkmcnt(2)
	v_mfma_f32_16x16x32_bf16 v[16:19], v[212:215], v[224:227], v[16:19]
	v_add_u32_e32 v96, 0x38000, v108
	v_mfma_f32_16x16x32_bf16 v[20:23], v[212:215], v[228:231], v[20:23]
	global_load_dwordx4 v[120:123], v96, s[86:87] nt
	v_mfma_f32_16x16x32_bf16 v[24:27], v[212:215], v[232:235], v[24:27]
	v_mfma_f32_16x16x32_bf16 v[28:31], v[212:215], v[236:239], v[28:31]
	s_waitcnt lgkmcnt(1)
	v_mfma_f32_16x16x32_bf16 v[32:35], v[216:219], v[224:227], v[32:35]
	v_mfma_f32_16x16x32_bf16 v[36:39], v[216:219], v[228:231], v[36:39]
	v_mfma_f32_16x16x32_bf16 v[40:43], v[216:219], v[232:235], v[40:43]
	v_mfma_f32_16x16x32_bf16 v[44:47], v[216:219], v[236:239], v[44:47]
	s_waitcnt lgkmcnt(0)
	v_mfma_f32_16x16x32_bf16 v[48:51], v[220:223], v[224:227], v[48:51]
	v_mfma_f32_16x16x32_bf16 v[52:55], v[220:223], v[228:231], v[52:55]
	v_mfma_f32_16x16x32_bf16 v[56:59], v[220:223], v[232:235], v[56:59]
	v_mfma_f32_16x16x32_bf16 v[60:63], v[220:223], v[236:239], v[60:63]
	s_waitcnt vmcnt(1)
	s_barrier
	ds_read_b128 v[176:179], v244 offset:0
	ds_read_b128 v[80:83], v246 offset:0
	ds_read_b128 v[84:87], v246 offset:2048
	ds_read_b128 v[88:91], v246 offset:4096
	ds_read_b128 v[92:95], v246 offset:6144
	ds_read_b128 v[180:183], v244 offset:2048
	ds_read_b128 v[184:187], v244 offset:4096
	ds_read_b128 v[188:191], v244 offset:6144
	s_waitcnt lgkmcnt(6)
	v_mfma_f32_16x16x32_bf16 v[0:3], v[176:179], v[80:83], v[0:3]
	ds_read_b128 v[208:211], v245 offset:0
	s_add_i32 m0, s81, 32768
	s_waitcnt lgkmcnt(6)
	v_mfma_f32_16x16x32_bf16 v[4:7], v[176:179], v[84:87], v[4:7]
	ds_read_b128 v[224:227], v247 offset:0
	global_load_lds_dwordx4 v240, s[76:77]
	s_waitcnt lgkmcnt(6)
	v_mfma_f32_16x16x32_bf16 v[8:11], v[176:179], v[88:91], v[8:11]
	ds_read_b128 v[228:231], v247 offset:2048
	s_add_i32 m0, s81, 36864
	s_waitcnt lgkmcnt(6)
	v_mfma_f32_16x16x32_bf16 v[12:15], v[176:179], v[92:95], v[12:15]
	ds_read_b128 v[232:235], v247 offset:4096
	global_load_lds_dwordx4 v241, s[76:77]
	s_waitcnt lgkmcnt(6)
	v_mfma_f32_16x16x32_bf16 v[16:19], v[180:183], v[80:83], v[16:19]
	ds_read_b128 v[236:239], v247 offset:6144
	s_add_i32 m0, s81, 40960
	v_mfma_f32_16x16x32_bf16 v[20:23], v[180:183], v[84:87], v[20:23]
	ds_read_b128 v[212:215], v245 offset:2048
	global_load_lds_dwordx4 v242, s[76:77]
	v_mfma_f32_16x16x32_bf16 v[24:27], v[180:183], v[88:91], v[24:27]
	ds_read_b128 v[216:219], v245 offset:4096
	s_add_i32 m0, s81, 45056
	v_mfma_f32_16x16x32_bf16 v[28:31], v[180:183], v[92:95], v[28:31]
	ds_read_b128 v[220:223], v245 offset:6144
	global_load_lds_dwordx4 v243, s[76:77]
	s_waitcnt lgkmcnt(9)
	v_mfma_f32_16x16x32_bf16 v[32:35], v[184:187], v[80:83], v[32:35]
	s_add_i32 m0, s81, 49152
	v_mfma_f32_16x16x32_bf16 v[36:39], v[184:187], v[84:87], v[36:39]
	global_load_lds_dwordx4 v240, s[78:79]
	v_mfma_f32_16x16x32_bf16 v[40:43], v[184:187], v[88:91], v[40:43]
	s_add_i32 m0, s81, 53248
	v_mfma_f32_16x16x32_bf16 v[44:47], v[184:187], v[92:95], v[44:47]
	global_load_lds_dwordx4 v241, s[78:79]
	s_waitcnt lgkmcnt(8)
	v_mfma_f32_16x16x32_bf16 v[48:51], v[188:191], v[80:83], v[48:51]
	s_add_i32 m0, s81, 57344
	v_mfma_f32_16x16x32_bf16 v[52:55], v[188:191], v[84:87], v[52:55]
	global_load_lds_dwordx4 v242, s[78:79]
	v_mfma_f32_16x16x32_bf16 v[56:59], v[188:191], v[88:91], v[56:59]
	s_add_i32 m0, s81, 61440
	v_mfma_f32_16x16x32_bf16 v[60:63], v[188:191], v[92:95], v[60:63]
	global_load_lds_dwordx4 v243, s[78:79]
	s_waitcnt lgkmcnt(6)
	v_mfma_f32_16x16x32_bf16 v[0:3], v[208:211], v[224:227], v[0:3]
	s_add_u32 s76, s76, 0x80
	s_addc_u32 s77, s77, 0
	s_waitcnt lgkmcnt(5)
	v_mfma_f32_16x16x32_bf16 v[4:7], v[208:211], v[228:231], v[4:7]
	s_waitcnt lgkmcnt(4)
	v_mfma_f32_16x16x32_bf16 v[8:11], v[208:211], v[232:235], v[8:11]
	s_add_u32 s78, s78, 0x80
	s_addc_u32 s79, s79, 0
	s_waitcnt lgkmcnt(3)
	v_mfma_f32_16x16x32_bf16 v[12:15], v[208:211], v[236:239], v[12:15]
	s_waitcnt lgkmcnt(2)
	v_mfma_f32_16x16x32_bf16 v[16:19], v[212:215], v[224:227], v[16:19]
	v_mfma_f32_16x16x32_bf16 v[20:23], v[212:215], v[228:231], v[20:23]
	v_mfma_f32_16x16x32_bf16 v[24:27], v[212:215], v[232:235], v[24:27]
	v_mfma_f32_16x16x32_bf16 v[28:31], v[212:215], v[236:239], v[28:31]
	s_waitcnt lgkmcnt(1)
	v_mfma_f32_16x16x32_bf16 v[32:35], v[216:219], v[224:227], v[32:35]
	v_mfma_f32_16x16x32_bf16 v[36:39], v[216:219], v[228:231], v[36:39]
	v_mfma_f32_16x16x32_bf16 v[40:43], v[216:219], v[232:235], v[40:43]
	v_mfma_f32_16x16x32_bf16 v[44:47], v[216:219], v[236:239], v[44:47]
	s_waitcnt lgkmcnt(0)
	v_mfma_f32_16x16x32_bf16 v[48:51], v[220:223], v[224:227], v[48:51]
	v_mfma_f32_16x16x32_bf16 v[52:55], v[220:223], v[228:231], v[52:55]
	v_mfma_f32_16x16x32_bf16 v[56:59], v[220:223], v[232:235], v[56:59]
	v_mfma_f32_16x16x32_bf16 v[60:63], v[220:223], v[236:239], v[60:63]
	s_waitcnt vmcnt(0)
	s_barrier
	ds_read_b128 v[176:179], v244 offset:32768
	ds_read_b128 v[80:83], v246 offset:32768
	ds_read_b128 v[84:87], v246 offset:34816
	ds_read_b128 v[88:91], v246 offset:36864
	ds_read_b128 v[92:95], v246 offset:38912
	ds_read_b128 v[180:183], v244 offset:34816
	ds_read_b128 v[184:187], v244 offset:36864
	ds_read_b128 v[188:191], v244 offset:38912
	s_waitcnt lgkmcnt(6)
	v_mfma_f32_16x16x32_bf16 v[0:3], v[176:179], v[80:83], v[0:3]
	ds_read_b128 v[208:211], v245 offset:32768
	s_waitcnt lgkmcnt(6)
	v_mfma_f32_16x16x32_bf16 v[4:7], v[176:179], v[84:87], v[4:7]
	ds_read_b128 v[224:227], v247 offset:32768
	s_waitcnt lgkmcnt(6)
	v_mfma_f32_16x16x32_bf16 v[8:11], v[176:179], v[88:91], v[8:11]
	ds_read_b128 v[228:231], v247 offset:34816
	s_waitcnt lgkmcnt(6)
	v_mfma_f32_16x16x32_bf16 v[12:15], v[176:179], v[92:95], v[12:15]
	ds_read_b128 v[232:235], v247 offset:36864
	s_waitcnt lgkmcnt(6)
	v_mfma_f32_16x16x32_bf16 v[16:19], v[180:183], v[80:83], v[16:19]
	ds_read_b128 v[236:239], v247 offset:38912
	v_mfma_f32_16x16x32_bf16 v[20:23], v[180:183], v[84:87], v[20:23]
	ds_read_b128 v[212:215], v245 offset:34816
	v_mfma_f32_16x16x32_bf16 v[24:27], v[180:183], v[88:91], v[24:27]
	ds_read_b128 v[216:219], v245 offset:36864
	v_mfma_f32_16x16x32_bf16 v[28:31], v[180:183], v[92:95], v[28:31]
	ds_read_b128 v[220:223], v245 offset:38912
	s_waitcnt lgkmcnt(9)
	v_mfma_f32_16x16x32_bf16 v[32:35], v[184:187], v[80:83], v[32:35]
	v_mfma_f32_16x16x32_bf16 v[36:39], v[184:187], v[84:87], v[36:39]
	v_mfma_f32_16x16x32_bf16 v[40:43], v[184:187], v[88:91], v[40:43]
	v_mfma_f32_16x16x32_bf16 v[44:47], v[184:187], v[92:95], v[44:47]
	s_waitcnt lgkmcnt(8)
	v_mfma_f32_16x16x32_bf16 v[48:51], v[188:191], v[80:83], v[48:51]
	v_mfma_f32_16x16x32_bf16 v[52:55], v[188:191], v[84:87], v[52:55]
	v_mfma_f32_16x16x32_bf16 v[56:59], v[188:191], v[88:91], v[56:59]
	v_mfma_f32_16x16x32_bf16 v[60:63], v[188:191], v[92:95], v[60:63]
	s_waitcnt lgkmcnt(6)
	v_mfma_f32_16x16x32_bf16 v[0:3], v[208:211], v[224:227], v[0:3]
	s_waitcnt lgkmcnt(5)
	v_mfma_f32_16x16x32_bf16 v[4:7], v[208:211], v[228:231], v[4:7]
	s_waitcnt lgkmcnt(4)
	v_mfma_f32_16x16x32_bf16 v[8:11], v[208:211], v[232:235], v[8:11]
	s_waitcnt lgkmcnt(3)
	v_mfma_f32_16x16x32_bf16 v[12:15], v[208:211], v[236:239], v[12:15]
	s_waitcnt lgkmcnt(2)
	v_mfma_f32_16x16x32_bf16 v[16:19], v[212:215], v[224:227], v[16:19]
	v_mfma_f32_16x16x32_bf16 v[20:23], v[212:215], v[228:231], v[20:23]
	v_mfma_f32_16x16x32_bf16 v[24:27], v[212:215], v[232:235], v[24:27]
	v_mfma_f32_16x16x32_bf16 v[28:31], v[212:215], v[236:239], v[28:31]
	s_waitcnt lgkmcnt(1)
	v_mfma_f32_16x16x32_bf16 v[32:35], v[216:219], v[224:227], v[32:35]
	v_mfma_f32_16x16x32_bf16 v[36:39], v[216:219], v[228:231], v[36:39]
	v_mfma_f32_16x16x32_bf16 v[40:43], v[216:219], v[232:235], v[40:43]
	v_mfma_f32_16x16x32_bf16 v[44:47], v[216:219], v[236:239], v[44:47]
	s_waitcnt lgkmcnt(0)
	v_mfma_f32_16x16x32_bf16 v[48:51], v[220:223], v[224:227], v[48:51]
	v_mfma_f32_16x16x32_bf16 v[52:55], v[220:223], v[228:231], v[52:55]
	v_mfma_f32_16x16x32_bf16 v[56:59], v[220:223], v[232:235], v[56:59]
	v_mfma_f32_16x16x32_bf16 v[60:63], v[220:223], v[236:239], v[60:63]
.Lot_stage:
	s_barrier
	ds_write_b32 v248, v0 offset:0
	ds_write_b32 v248, v1 offset:528
	ds_write_b32 v248, v2 offset:1056
	ds_write_b32 v248, v3 offset:1584
	ds_write_b32 v248, v4 offset:64
	ds_write_b32 v248, v5 offset:592
	ds_write_b32 v248, v6 offset:1120
	ds_write_b32 v248, v7 offset:1648
	ds_write_b32 v248, v8 offset:128
	ds_write_b32 v248, v9 offset:656
	ds_write_b32 v248, v10 offset:1184
	ds_write_b32 v248, v11 offset:1712
	ds_write_b32 v248, v12 offset:192
	ds_write_b32 v248, v13 offset:720
	ds_write_b32 v248, v14 offset:1248
	ds_write_b32 v248, v15 offset:1776
	ds_write_b32 v248, v16 offset:8448
	ds_write_b32 v248, v17 offset:8976
	ds_write_b32 v248, v18 offset:9504
	ds_write_b32 v248, v19 offset:10032
	ds_write_b32 v248, v20 offset:8512
	ds_write_b32 v248, v21 offset:9040
	ds_write_b32 v248, v22 offset:9568
	ds_write_b32 v248, v23 offset:10096
	ds_write_b32 v248, v24 offset:8576
	ds_write_b32 v248, v25 offset:9104
	ds_write_b32 v248, v26 offset:9632
	ds_write_b32 v248, v27 offset:10160
	ds_write_b32 v248, v28 offset:8640
	ds_write_b32 v248, v29 offset:9168
	ds_write_b32 v248, v30 offset:9696
	ds_write_b32 v248, v31 offset:10224
	ds_write_b32 v248, v32 offset:16896
	ds_write_b32 v248, v33 offset:17424
	ds_write_b32 v248, v34 offset:17952
	ds_write_b32 v248, v35 offset:18480
	ds_write_b32 v248, v36 offset:16960
	ds_write_b32 v248, v37 offset:17488
	ds_write_b32 v248, v38 offset:18016
	ds_write_b32 v248, v39 offset:18544
	ds_write_b32 v248, v40 offset:17024
	ds_write_b32 v248, v41 offset:17552
	ds_write_b32 v248, v42 offset:18080
	ds_write_b32 v248, v43 offset:18608
	ds_write_b32 v248, v44 offset:17088
	ds_write_b32 v248, v45 offset:17616
	ds_write_b32 v248, v46 offset:18144
	ds_write_b32 v248, v47 offset:18672
	ds_write_b32 v248, v48 offset:25344
	ds_write_b32 v248, v49 offset:25872
	ds_write_b32 v248, v50 offset:26400
	ds_write_b32 v248, v51 offset:26928
	ds_write_b32 v248, v52 offset:25408
	ds_write_b32 v248, v53 offset:25936
	ds_write_b32 v248, v54 offset:26464
	ds_write_b32 v248, v55 offset:26992
	ds_write_b32 v248, v56 offset:25472
	ds_write_b32 v248, v57 offset:26000
	ds_write_b32 v248, v58 offset:26528
	ds_write_b32 v248, v59 offset:27056
	ds_write_b32 v248, v60 offset:25536
	ds_write_b32 v248, v61 offset:26064
	ds_write_b32 v248, v62 offset:26592
	ds_write_b32 v248, v63 offset:27120
	global_load_dwordx4 v[208:211], v114, s[90:91]
	global_load_dwordx4 v[212:215], v114, s[90:91] offset:16
	s_cmp_eq_u64 s[52:53], 0
	s_cbranch_scc0 .Lot_epi_l1
	v_add_u32_e32 v96, 0x70000, v102
	global_load_dwordx4 v[216:219], v96, s[86:87] nt
	global_load_dwordx4 v[220:223], v96, s[86:87] offset:16 nt
	s_waitcnt lgkmcnt(0)
	s_barrier
	ds_read_b128 v[0:3], v124 offset:0
	ds_read_b128 v[4:7], v124 offset:16
	ds_read_b128 v[8:11], v124 offset:8448
	ds_read_b128 v[12:15], v124 offset:8464
	ds_read_b128 v[16:19], v124 offset:16896
	ds_read_b128 v[20:23], v124 offset:16912
	ds_read_b128 v[24:27], v124 offset:25344
	ds_read_b128 v[28:31], v124 offset:25360
	ds_read_b128 v[32:35], v124 offset:33792
	ds_read_b128 v[36:39], v124 offset:33808
	ds_read_b128 v[40:43], v124 offset:42240
	ds_read_b128 v[44:47], v124 offset:42256
	ds_read_b128 v[48:51], v124 offset:50688
	ds_read_b128 v[52:55], v124 offset:50704
	ds_read_b128 v[56:59], v124 offset:59136
	ds_read_b128 v[60:63], v124 offset:59152
	s_waitcnt vmcnt(2)
	s_waitcnt lgkmcnt(14)
	v_fma_f32 v0, v208, v0, v64
	v_fma_f32 v1, v209, v1, v65
	v_fma_f32 v2, v210, v2, v66
	v_fma_f32 v3, v211, v3, v67
	v_fma_f32 v4, v212, v4, v68
	v_fma_f32 v5, v213, v5, v69
	v_fma_f32 v6, v214, v6, v70
	v_fma_f32 v7, v215, v7, v71
	v_cvt_pk_bf16_f32 v0, v0, v1
	v_cvt_pk_bf16_f32 v1, v2, v3
	v_cvt_pk_bf16_f32 v2, v4, v5
	v_cvt_pk_bf16_f32 v3, v6, v7
	v_add_u32_e32 v96, 0, v108
	global_store_dwordx4 v96, v[0:3], s[88:89]
	s_waitcnt vmcnt(3)
	s_waitcnt lgkmcnt(12)
	v_fma_f32 v8, v208, v8, v74
	v_fma_f32 v9, v209, v9, v75
	v_fma_f32 v10, v210, v10, v76
	v_fma_f32 v11, v211, v11, v77
	v_fma_f32 v12, v212, v12, v98
	v_fma_f32 v13, v213, v13, v99
	v_fma_f32 v14, v214, v14, v100
	v_fma_f32 v15, v215, v15, v101
	v_cvt_pk_bf16_f32 v8, v8, v9
	v_cvt_pk_bf16_f32 v9, v10, v11
	v_cvt_pk_bf16_f32 v10, v12, v13
	v_cvt_pk_bf16_f32 v11, v14, v15
	v_add_u32_e32 v96, 32768, v108
	global_store_dwordx4 v96, v[8:11], s[88:89]
	s_waitcnt vmcnt(4)
	s_waitcnt lgkmcnt(10)
	v_fma_f32 v16, v208, v16, v104
	v_fma_f32 v17, v209, v17, v105
	v_fma_f32 v18, v210, v18, v106
	v_fma_f32 v19, v211, v19, v107
	v_fma_f32 v20, v212, v20, v110
	v_fma_f32 v21, v213, v21, v111
	v_fma_f32 v22, v214, v22, v112
	v_fma_f32 v23, v215, v23, v113
	v_cvt_pk_bf16_f32 v16, v16, v17
	v_cvt_pk_bf16_f32 v17, v18, v19
	v_cvt_pk_bf16_f32 v18, v20, v21
	v_cvt_pk_bf16_f32 v19, v22, v23
	v_add_u32_e32 v96, 65536, v108
	global_store_dwordx4 v96, v[16:19], s[88:89]
	s_waitcnt vmcnt(5)
	s_waitcnt lgkmcnt(8)
	v_fma_f32 v24, v208, v24, v116
	v_fma_f32 v25, v209, v25, v117
	v_fma_f32 v26, v210, v26, v118
	v_fma_f32 v27, v211, v27, v119
	v_fma_f32 v28, v212, v28, v120
	v_fma_f32 v29, v213, v29, v121
	v_fma_f32 v30, v214, v30, v122
	v_fma_f32 v31, v215, v31, v123
	v_cvt_pk_bf16_f32 v24, v24, v25
	v_cvt_pk_bf16_f32 v25, v26, v27
	v_cvt_pk_bf16_f32 v26, v28, v29
	v_cvt_pk_bf16_f32 v27, v30, v31
	v_add_u32_e32 v96, 98304, v108
	global_store_dwordx4 v96, v[24:27], s[88:89]
	s_waitcnt vmcnt(6)
	s_waitcnt lgkmcnt(6)
	v_fma_f32 v32, v208, v32, v126
	v_fma_f32 v33, v209, v33, v127
	v_fma_f32 v34, v210, v34, v128
	v_fma_f32 v35, v211, v35, v129
	v_fma_f32 v36, v212, v36, v168
	v_fma_f32 v37, v213, v37, v169
	v_fma_f32 v38, v214, v38, v170
	v_fma_f32 v39, v215, v39, v171
	v_cvt_pk_bf16_f32 v32, v32, v33
	v_cvt_pk_bf16_f32 v33, v34, v35
	v_cvt_pk_bf16_f32 v34, v36, v37
	v_cvt_pk_bf16_f32 v35, v38, v39
	v_add_u32_e32 v96, 131072, v108
	global_store_dwordx4 v96, v[32:35], s[88:89]
	s_waitcnt vmcnt(7)
	s_waitcnt lgkmcnt(4)
	v_fma_f32 v40, v208, v40, v192
	v_fma_f32 v41, v209, v41, v193
	v_fma_f32 v42, v210, v42, v194
	v_fma_f32 v43, v211, v43, v195
	v_fma_f32 v44, v212, v44, v196
	v_fma_f32 v45, v213, v45, v197
	v_fma_f32 v46, v214, v46, v198
	v_fma_f32 v47, v215, v47, v199
	v_cvt_pk_bf16_f32 v40, v40, v41
	v_cvt_pk_bf16_f32 v41, v42, v43
	v_cvt_pk_bf16_f32 v42, v44, v45
	v_cvt_pk_bf16_f32 v43, v46, v47
	v_add_u32_e32 v96, 163840, v108
	global_store_dwordx4 v96, v[40:43], s[88:89]
	s_waitcnt vmcnt(8)
	s_waitcnt lgkmcnt(2)
	v_fma_f32 v48, v208, v48, v200
	v_fma_f32 v49, v209, v49, v201
	v_fma_f32 v50, v210, v50, v202
	v_fma_f32 v51, v211, v51, v203
	v_fma_f32 v52, v212, v52, v250
	v_fma_f32 v53, v213, v53, v251
	v_fma_f32 v54, v214, v54, v252
	v_fma_f32 v55, v215, v55, v253
	v_cvt_pk_bf16_f32 v48, v48, v49
	v_cvt_pk_bf16_f32 v49, v50, v51
	v_cvt_pk_bf16_f32 v50, v52, v53
	v_cvt_pk_bf16_f32 v51, v54, v55
	v_add_u32_e32 v96, 196608, v108
	global_store_dwordx4 v96, v[48:51], s[88:89]
	s_waitcnt vmcnt(7)
	s_waitcnt lgkmcnt(0)
	v_fma_f32 v56, v208, v56, v216
	v_fma_f32 v57, v209, v57, v217
	v_fma_f32 v58, v210, v58, v218
	v_fma_f32 v59, v211, v59, v219
	v_fma_f32 v60, v212, v60, v220
	v_fma_f32 v61, v213, v61, v221
	v_fma_f32 v62, v214, v62, v222
	v_fma_f32 v63, v215, v63, v223
	v_cvt_pk_bf16_f32 v56, v56, v57
	v_cvt_pk_bf16_f32 v57, v58, v59
	v_cvt_pk_bf16_f32 v58, v60, v61
	v_cvt_pk_bf16_f32 v59, v62, v63
	v_add_u32_e32 v96, 229376, v108
	global_store_dwordx4 v96, v[56:59], s[88:89]
	s_branch .LBB0_624
.Lot_epi_l1:
	s_waitcnt lgkmcnt(0)
	s_barrier
	ds_read_b128 v[0:3], v124 offset:0
	ds_read_b128 v[4:7], v124 offset:16
	ds_read_b128 v[8:11], v124 offset:8448
	ds_read_b128 v[12:15], v124 offset:8464
	ds_read_b128 v[16:19], v124 offset:16896
	ds_read_b128 v[20:23], v124 offset:16912
	ds_read_b128 v[24:27], v124 offset:25344
	ds_read_b128 v[28:31], v124 offset:25360
	ds_read_b128 v[32:35], v124 offset:33792
	ds_read_b128 v[36:39], v124 offset:33808
	ds_read_b128 v[40:43], v124 offset:42240
	ds_read_b128 v[44:47], v124 offset:42256
	ds_read_b128 v[48:51], v124 offset:50688
	ds_read_b128 v[52:55], v124 offset:50704
	ds_read_b128 v[56:59], v124 offset:59136
	ds_read_b128 v[60:63], v124 offset:59152
	s_waitcnt vmcnt(0)
	s_waitcnt lgkmcnt(14)
	v_lshlrev_b32_e32 v134, 16, v64
	v_fma_f32 v0, v208, v0, v134
	v_and_b32_e32 v136, 0xffff0000, v64
	v_fma_f32 v1, v209, v1, v136
	v_lshlrev_b32_e32 v134, 16, v65
	v_fma_f32 v2, v210, v2, v134
	v_and_b32_e32 v136, 0xffff0000, v65
	v_fma_f32 v3, v211, v3, v136
	v_lshlrev_b32_e32 v134, 16, v66
	v_fma_f32 v4, v212, v4, v134
	v_and_b32_e32 v136, 0xffff0000, v66
	v_fma_f32 v5, v213, v5, v136
	v_lshlrev_b32_e32 v134, 16, v67
	v_fma_f32 v6, v214, v6, v134
	v_and_b32_e32 v136, 0xffff0000, v67
	v_fma_f32 v7, v215, v7, v136
	v_add_u32_e32 v96, 0x0, v102
	global_store_dwordx4 v96, v[0:3], s[88:89] nt
	global_store_dwordx4 v96, v[4:7], s[88:89] offset:16 nt
	s_waitcnt lgkmcnt(12)
	v_lshlrev_b32_e32 v134, 16, v68
	v_fma_f32 v8, v208, v8, v134
	v_and_b32_e32 v136, 0xffff0000, v68
	v_fma_f32 v9, v209, v9, v136
	v_lshlrev_b32_e32 v134, 16, v69
	v_fma_f32 v10, v210, v10, v134
	v_and_b32_e32 v136, 0xffff0000, v69
	v_fma_f32 v11, v211, v11, v136
	v_lshlrev_b32_e32 v134, 16, v70
	v_fma_f32 v12, v212, v12, v134
	v_and_b32_e32 v136, 0xffff0000, v70
	v_fma_f32 v13, v213, v13, v136
	v_lshlrev_b32_e32 v134, 16, v71
	v_fma_f32 v14, v214, v14, v134
	v_and_b32_e32 v136, 0xffff0000, v71
	v_fma_f32 v15, v215, v15, v136
	v_add_u32_e32 v96, 0x10000, v102
	global_store_dwordx4 v96, v[8:11], s[88:89] nt
	global_store_dwordx4 v96, v[12:15], s[88:89] offset:16 nt
	s_waitcnt lgkmcnt(10)
	v_lshlrev_b32_e32 v134, 16, v192
	v_fma_f32 v16, v208, v16, v134
	v_and_b32_e32 v136, 0xffff0000, v192
	v_fma_f32 v17, v209, v17, v136
	v_lshlrev_b32_e32 v134, 16, v193
	v_fma_f32 v18, v210, v18, v134
	v_and_b32_e32 v136, 0xffff0000, v193
	v_fma_f32 v19, v211, v19, v136
	v_lshlrev_b32_e32 v134, 16, v194
	v_fma_f32 v20, v212, v20, v134
	v_and_b32_e32 v136, 0xffff0000, v194
	v_fma_f32 v21, v213, v21, v136
	v_lshlrev_b32_e32 v134, 16, v195
	v_fma_f32 v22, v214, v22, v134
	v_and_b32_e32 v136, 0xffff0000, v195
	v_fma_f32 v23, v215, v23, v136
	v_add_u32_e32 v96, 0x20000, v102
	global_store_dwordx4 v96, v[16:19], s[88:89] nt
	global_store_dwordx4 v96, v[20:23], s[88:89] offset:16 nt
	s_waitcnt lgkmcnt(8)
	v_lshlrev_b32_e32 v134, 16, v196
	v_fma_f32 v24, v208, v24, v134
	v_and_b32_e32 v136, 0xffff0000, v196
	v_fma_f32 v25, v209, v25, v136
	v_lshlrev_b32_e32 v134, 16, v197
	v_fma_f32 v26, v210, v26, v134
	v_and_b32_e32 v136, 0xffff0000, v197
	v_fma_f32 v27, v211, v27, v136
	v_lshlrev_b32_e32 v134, 16, v198
	v_fma_f32 v28, v212, v28, v134
	v_and_b32_e32 v136, 0xffff0000, v198
	v_fma_f32 v29, v213, v29, v136
	v_lshlrev_b32_e32 v134, 16, v199
	v_fma_f32 v30, v214, v30, v134
	v_and_b32_e32 v136, 0xffff0000, v199
	v_fma_f32 v31, v215, v31, v136
	v_add_u32_e32 v96, 0x30000, v102
	global_store_dwordx4 v96, v[24:27], s[88:89] nt
	global_store_dwordx4 v96, v[28:31], s[88:89] offset:16 nt
	s_waitcnt lgkmcnt(6)
	v_lshlrev_b32_e32 v134, 16, v200
	v_fma_f32 v32, v208, v32, v134
	v_and_b32_e32 v136, 0xffff0000, v200
	v_fma_f32 v33, v209, v33, v136
	v_lshlrev_b32_e32 v134, 16, v201
	v_fma_f32 v34, v210, v34, v134
	v_and_b32_e32 v136, 0xffff0000, v201
	v_fma_f32 v35, v211, v35, v136
	v_lshlrev_b32_e32 v134, 16, v202
	v_fma_f32 v36, v212, v36, v134
	v_and_b32_e32 v136, 0xffff0000, v202
	v_fma_f32 v37, v213, v37, v136
	v_lshlrev_b32_e32 v134, 16, v203
	v_fma_f32 v38, v214, v38, v134
	v_and_b32_e32 v136, 0xffff0000, v203
	v_fma_f32 v39, v215, v39, v136
	v_add_u32_e32 v96, 0x40000, v102
	global_store_dwordx4 v96, v[32:35], s[88:89] nt
	global_store_dwordx4 v96, v[36:39], s[88:89] offset:16 nt
	s_waitcnt lgkmcnt(4)
	v_lshlrev_b32_e32 v134, 16, v110
	v_fma_f32 v40, v208, v40, v134
	v_and_b32_e32 v136, 0xffff0000, v110
	v_fma_f32 v41, v209, v41, v136
	v_lshlrev_b32_e32 v134, 16, v111
	v_fma_f32 v42, v210, v42, v134
	v_and_b32_e32 v136, 0xffff0000, v111
	v_fma_f32 v43, v211, v43, v136
	v_lshlrev_b32_e32 v134, 16, v112
	v_fma_f32 v44, v212, v44, v134
	v_and_b32_e32 v136, 0xffff0000, v112
	v_fma_f32 v45, v213, v45, v136
	v_lshlrev_b32_e32 v134, 16, v113
	v_fma_f32 v46, v214, v46, v134
	v_and_b32_e32 v136, 0xffff0000, v113
	v_fma_f32 v47, v215, v47, v136
	v_add_u32_e32 v96, 0x50000, v102
	global_store_dwordx4 v96, v[40:43], s[88:89] nt
	global_store_dwordx4 v96, v[44:47], s[88:89] offset:16 nt
	s_waitcnt lgkmcnt(2)
	v_lshlrev_b32_e32 v134, 16, v116
	v_fma_f32 v48, v208, v48, v134
	v_and_b32_e32 v136, 0xffff0000, v116
	v_fma_f32 v49, v209, v49, v136
	v_lshlrev_b32_e32 v134, 16, v117
	v_fma_f32 v50, v210, v50, v134
	v_and_b32_e32 v136, 0xffff0000, v117
	v_fma_f32 v51, v211, v51, v136
	v_lshlrev_b32_e32 v134, 16, v118
	v_fma_f32 v52, v212, v52, v134
	v_and_b32_e32 v136, 0xffff0000, v118
	v_fma_f32 v53, v213, v53, v136
	v_lshlrev_b32_e32 v134, 16, v119
	v_fma_f32 v54, v214, v54, v134
	v_and_b32_e32 v136, 0xffff0000, v119
	v_fma_f32 v55, v215, v55, v136
	v_add_u32_e32 v96, 0x60000, v102
	global_store_dwordx4 v96, v[48:51], s[88:89] nt
	global_store_dwordx4 v96, v[52:55], s[88:89] offset:16 nt
	s_waitcnt lgkmcnt(0)
	v_lshlrev_b32_e32 v134, 16, v120
	v_fma_f32 v56, v208, v56, v134
	v_and_b32_e32 v136, 0xffff0000, v120
	v_fma_f32 v57, v209, v57, v136
	v_lshlrev_b32_e32 v134, 16, v121
	v_fma_f32 v58, v210, v58, v134
	v_and_b32_e32 v136, 0xffff0000, v121
	v_fma_f32 v59, v211, v59, v136
	v_lshlrev_b32_e32 v134, 16, v122
	v_fma_f32 v60, v212, v60, v134
	v_and_b32_e32 v136, 0xffff0000, v122
	v_fma_f32 v61, v213, v61, v136
	v_lshlrev_b32_e32 v134, 16, v123
	v_fma_f32 v62, v214, v62, v134
	v_and_b32_e32 v136, 0xffff0000, v123
	v_fma_f32 v63, v215, v63, v136
	v_add_u32_e32 v96, 0x70000, v102
	global_store_dwordx4 v96, v[56:59], s[88:89] nt
	global_store_dwordx4 v96, v[60:63], s[88:89] offset:16 nt
	s_branch .LBB0_624
